# kloops-12-barriers-phases-3-4-and-7-8-merged-non-up
# speedup vs baseline: 1.0020x; 1.0020x over previous
; #define PG8_STAGE(bufoff, gbase, hoff, imm) do { _Pragma("unroll") for (int _i = 0; _i < 2; ++_i) { \
;         asm volatile("s_mov_b32 m0, %0\n\ts_nop 0\n\tglobal_load_lds_dwordx4 %1, %2" \
;             :: "s"(lds0 + (unsigned)((bufoff) + _i * 8192)), "v"(voff0), "s"((const char*)(gbase) + (size_t)(hoff) + (size_t)(_i * 8192)) : "memory"); } } while (0)
; #define PG8_LDA(dst, b, h) do { _Pragma("unroll") for (int m = 0; m < 4; ++m) _Pragma("unroll") for (int k = 0; k < 2; ++k) dst[m][k] = *(const LAS bf16x8*)(lds + PG8_SA(b, h) + aoff + m * 2048 + k * 1024); } while (0)
; #define PG8_LDB(dst, b, h) do { _Pragma("unroll") for (int n = 0; n < 2; ++n) _Pragma("unroll") for (int k = 0; k < 2; ++k) dst[n][k] = *(const LAS bf16x8*)(lds + PG8_SB(b, h) + boff + n * 2048 + k * 1024); } while (0)
; #define PG8_MMA(ai, bj, At, Bt) do { __builtin_amdgcn_s_setprio(1); _Pragma("unroll") for (int m = 0; m < 4; ++m) _Pragma("unroll") for (int n = 0; n < 2; ++n) _Pragma("unroll") for (int k = 0; k < 2; ++k) \
;         acc[ai][bj][m][n] = __builtin_amdgcn_mfma_f32_16x16x32_bf16(Bt[n][k], At[m][k], acc[ai][bj][m][n], 0, 0, 0); __builtin_amdgcn_s_setprio(0); } while (0)
; #define PG8_WAIT_V(n) asm volatile("s_waitcnt vmcnt(" #n ")" ::: "memory")
; #define PG8_WAIT_L(n) asm volatile("s_waitcnt lgkmcnt(" #n ")" ::: "memory")
; #define PG8_BAR __builtin_amdgcn_s_barrier()
; #define PG8_SCHED __builtin_amdgcn_sched_barrier(0)
; template <class Epi>
; __device__ __forceinline__ void gemm_phase(LAS unsigned char* lds, const Gemm g, const StaticOrder& S, const Epi& E) {
;     ...
;             PG8_LDB(B0, 0, 0); PG8_SCHED; PG8_LDA(At, 0, 0); PG8_STAGE(PG8_SA(1, 1), aT + KS, hA, 0);
;             PG8_WAIT_L(8); PG8_BAR; PG8_WAIT_L(0); PG8_MMA(0, 0, At, B0); PG8_BAR; PG8_SCHED;
;             PG8_LDB(B1, 0, 1); PG8_STAGE(PG8_SB(0, 0), b2, 0, 0);
;             PG8_BAR; PG8_WAIT_L(0); PG8_MMA(0, 1, At, B1); PG8_BAR;
;             PG8_LDA(At, 0, 1); PG8_STAGE(PG8_SA(0, 0), a2, 0, 0);
;             PG8_BAR; PG8_WAIT_L(0); PG8_MMA(1, 0, At, B0); PG8_BAR; PG8_SCHED;
;             PG8_STAGE(PG8_SB(0, 1), b2, hB, 0);
;             PG8_WAIT_V(6); PG8_BAR; PG8_MMA(1, 1, At, B1); PG8_BAR;
.LBB0_293:
	s_add_u32 s52, s8, 0x8000
	s_addc_u32 s53, s9, 0
	ds_read_b128 v[128:131], v224
	ds_read_b128 v[132:135], v224 offset:1024
	ds_read_b128 v[136:139], v224 offset:2048
	ds_read_b128 v[140:143], v224 offset:3072
	s_add_u32 s54, s8, 0x84000
	s_addc_u32 s55, s9, 0
	s_add_u32 s96, s8, 0x86000
	s_addc_u32 s97, s9, 0
	s_cmp_eq_u32 s95, 4
	s_cselect_b32 s9, s0, s53
	s_cselect_b32 s8, s1, s52
	ds_read_b128 v[144:147], v225
	ds_read_b128 v[148:151], v225 offset:1024
	ds_read_b128 v[152:155], v225 offset:2048
	ds_read_b128 v[156:159], v225 offset:3072
	ds_read_b128 v[160:163], v225 offset:4096
	ds_read_b128 v[164:167], v225 offset:5120
	ds_read_b128 v[168:171], v225 offset:6144
	ds_read_b128 v[172:175], v225 offset:7168
	s_mov_b32 m0, s86
	s_nop 0
	global_load_lds_dwordx4 v221, s[54:55]
	s_mov_b32 m0, s87
	s_nop 0
	global_load_lds_dwordx4 v221, s[96:97]
	s_waitcnt lgkmcnt(8)
	s_waitcnt vmcnt(10)
	s_barrier
	s_waitcnt lgkmcnt(7)
	v_mfma_f32_16x16x32_bf16 v[124:127], v[128:131], v[144:147], v[124:127]
	v_mfma_f32_16x16x32_bf16 v[120:123], v[136:139], v[144:147], v[120:123]
	s_waitcnt lgkmcnt(5)
	v_mfma_f32_16x16x32_bf16 v[116:119], v[128:131], v[152:155], v[116:119]
	v_mfma_f32_16x16x32_bf16 v[112:115], v[136:139], v[152:155], v[112:115]
	s_waitcnt lgkmcnt(3)
	v_mfma_f32_16x16x32_bf16 v[96:99], v[128:131], v[160:163], v[96:99]
	v_mfma_f32_16x16x32_bf16 v[88:91], v[136:139], v[160:163], v[88:91]
	s_waitcnt lgkmcnt(1)
	v_mfma_f32_16x16x32_bf16 v[80:83], v[128:131], v[168:171], v[80:83]
	v_mfma_f32_16x16x32_bf16 v[72:75], v[136:139], v[168:171], v[72:75]
	v_mfma_f32_16x16x32_bf16 v[124:127], v[132:135], v[148:151], v[124:127]
	v_mfma_f32_16x16x32_bf16 v[120:123], v[140:143], v[148:151], v[120:123]
	v_mfma_f32_16x16x32_bf16 v[116:119], v[132:135], v[156:159], v[116:119]
	v_mfma_f32_16x16x32_bf16 v[112:115], v[140:143], v[156:159], v[112:115]
	v_mfma_f32_16x16x32_bf16 v[96:99], v[132:135], v[164:167], v[96:99]
	v_mfma_f32_16x16x32_bf16 v[88:91], v[140:143], v[164:167], v[88:91]
	s_waitcnt lgkmcnt(0)
	v_mfma_f32_16x16x32_bf16 v[80:83], v[132:135], v[172:175], v[80:83]
	v_mfma_f32_16x16x32_bf16 v[72:75], v[140:143], v[172:175], v[72:75]
	s_barrier
	ds_read_b128 v[176:179], v226
	ds_read_b128 v[180:183], v226 offset:1024
	ds_read_b128 v[184:187], v226 offset:2048
	ds_read_b128 v[188:191], v226 offset:3072
	s_cselect_b32 s54, s47, s93
	s_cselect_b32 s55, s45, s94
	s_mov_b32 m0, s60
	s_nop 0
	global_load_lds_dwordx4 v221, s[54:55]
	s_add_u32 s96, s54, 0x2000
	s_addc_u32 s97, s55, 0
	s_mov_b32 m0, s61
	s_nop 0
	global_load_lds_dwordx4 v221, s[96:97]
	s_waitcnt vmcnt(10)
	s_barrier
	s_waitcnt lgkmcnt(3)
	v_mfma_f32_16x16x32_bf16 v[108:111], v[176:179], v[144:147], v[108:111]
	s_waitcnt lgkmcnt(1)
	v_mfma_f32_16x16x32_bf16 v[104:107], v[184:187], v[144:147], v[104:107]
	v_mfma_f32_16x16x32_bf16 v[100:103], v[176:179], v[152:155], v[100:103]
	v_mfma_f32_16x16x32_bf16 v[92:95], v[184:187], v[152:155], v[92:95]
	v_mfma_f32_16x16x32_bf16 v[84:87], v[176:179], v[160:163], v[84:87]
	v_mfma_f32_16x16x32_bf16 v[76:79], v[184:187], v[160:163], v[76:79]
	v_mfma_f32_16x16x32_bf16 v[68:71], v[176:179], v[168:171], v[68:71]
	v_mfma_f32_16x16x32_bf16 v[64:67], v[184:187], v[168:171], v[64:67]
	v_mfma_f32_16x16x32_bf16 v[108:111], v[180:183], v[148:151], v[108:111]
	s_waitcnt lgkmcnt(0)
	v_mfma_f32_16x16x32_bf16 v[104:107], v[188:191], v[148:151], v[104:107]
	v_mfma_f32_16x16x32_bf16 v[100:103], v[180:183], v[156:159], v[100:103]
	v_mfma_f32_16x16x32_bf16 v[92:95], v[188:191], v[156:159], v[92:95]
	v_mfma_f32_16x16x32_bf16 v[84:87], v[180:183], v[164:167], v[84:87]
	v_mfma_f32_16x16x32_bf16 v[76:79], v[188:191], v[164:167], v[76:79]
	v_mfma_f32_16x16x32_bf16 v[68:71], v[180:183], v[172:175], v[68:71]
	v_mfma_f32_16x16x32_bf16 v[64:67], v[188:191], v[172:175], v[64:67]
	s_barrier
	ds_read_b128 v[144:147], v225 offset:16384
	ds_read_b128 v[148:151], v225 offset:17408
	ds_read_b128 v[152:155], v225 offset:18432
	ds_read_b128 v[156:159], v225 offset:19456
	ds_read_b128 v[160:163], v225 offset:20480
	ds_read_b128 v[164:167], v225 offset:21504
	ds_read_b128 v[168:171], v225 offset:22528
	ds_read_b128 v[172:175], v225 offset:23552
	s_mov_b32 m0, s59
	s_nop 0
	global_load_lds_dwordx4 v221, s[8:9]
	s_add_u32 s96, s8, 0x2000
	s_addc_u32 s97, s9, 0
	s_mov_b32 m0, s62
	s_nop 0
	global_load_lds_dwordx4 v221, s[96:97]
	s_add_u32 s96, s54, 0x20000
	s_addc_u32 s97, s55, 0
	s_mov_b32 m0, s63
	s_nop 0
	global_load_lds_dwordx4 v221, s[96:97]
	s_add_u32 s96, s54, 0x22000
	s_addc_u32 s97, s55, 0
	s_mov_b32 m0, s64
	s_nop 0
	global_load_lds_dwordx4 v221, s[96:97]
	s_waitcnt vmcnt(10)
	s_barrier
; #define PG8_STAGE(bufoff, gbase, hoff, imm) do { _Pragma("unroll") for (int _i = 0; _i < 2; ++_i) { \
;         asm volatile("s_mov_b32 m0, %0\n\ts_nop 0\n\tglobal_load_lds_dwordx4 %1, %2" \
;             :: "s"(lds0 + (unsigned)((bufoff) + _i * 8192)), "v"(voff0), "s"((const char*)(gbase) + (size_t)(hoff) + (size_t)(_i * 8192)) : "memory"); } } while (0)
; #define PG8_LDA(dst, b, h) do { _Pragma("unroll") for (int m = 0; m < 4; ++m) _Pragma("unroll") for (int k = 0; k < 2; ++k) dst[m][k] = *(const LAS bf16x8*)(lds + PG8_SA(b, h) + aoff + m * 2048 + k * 1024); } while (0)
; #define PG8_LDB(dst, b, h) do { _Pragma("unroll") for (int n = 0; n < 2; ++n) _Pragma("unroll") for (int k = 0; k < 2; ++k) dst[n][k] = *(const LAS bf16x8*)(lds + PG8_SB(b, h) + boff + n * 2048 + k * 1024); } while (0)
; #define PG8_MMA(ai, bj, At, Bt) do { __builtin_amdgcn_s_setprio(1); _Pragma("unroll") for (int m = 0; m < 4; ++m) _Pragma("unroll") for (int n = 0; n < 2; ++n) _Pragma("unroll") for (int k = 0; k < 2; ++k) \
;         acc[ai][bj][m][n] = __builtin_amdgcn_mfma_f32_16x16x32_bf16(Bt[n][k], At[m][k], acc[ai][bj][m][n], 0, 0, 0); __builtin_amdgcn_s_setprio(0); } while (0)
; #define PG8_WAIT_V(n) asm volatile("s_waitcnt vmcnt(" #n ")" ::: "memory")
; #define PG8_WAIT_L(n) asm volatile("s_waitcnt lgkmcnt(" #n ")" ::: "memory")
; #define PG8_BAR __builtin_amdgcn_s_barrier()
; #define PG8_SCHED __builtin_amdgcn_sched_barrier(0)
; template <class Epi>
; __device__ __forceinline__ void gemm_phase(LAS unsigned char* lds, const Gemm g, const StaticOrder& S, const Epi& E) {
;     ...
;             PG8_BAR; PG8_WAIT_L(0); PG8_MMA(1, 0, At, B0); PG8_BAR; PG8_SCHED;
;             PG8_STAGE(PG8_SB(0, 1), b2, hB, 0);
;             PG8_WAIT_V(6); PG8_BAR; PG8_MMA(1, 1, At, B1); PG8_BAR;
;             PG8_LDB(B0, 1, 0); PG8_SCHED; PG8_LDA(At, 1, 0); PG8_STAGE(PG8_SA(0, 1), a2, hA, 0);
;             PG8_WAIT_L(8); PG8_BAR; PG8_WAIT_L(0); PG8_MMA(0, 0, At, B0); PG8_BAR; PG8_SCHED;
;             PG8_LDB(B1, 1, 1); PG8_STAGE(PG8_SB(1, 0), b2 + KS, 0, 0);
;             PG8_BAR; PG8_WAIT_L(0); PG8_MMA(0, 1, At, B1); PG8_BAR;
	s_waitcnt lgkmcnt(7)
	v_mfma_f32_16x16x32_bf16 v[60:63], v[128:131], v[144:147], v[60:63]
	v_mfma_f32_16x16x32_bf16 v[56:59], v[136:139], v[144:147], v[56:59]
	s_waitcnt lgkmcnt(5)
	v_mfma_f32_16x16x32_bf16 v[48:51], v[128:131], v[152:155], v[48:51]
	v_mfma_f32_16x16x32_bf16 v[40:43], v[136:139], v[152:155], v[40:43]
	s_waitcnt lgkmcnt(3)
	v_mfma_f32_16x16x32_bf16 v[32:35], v[128:131], v[160:163], v[32:35]
	v_mfma_f32_16x16x32_bf16 v[24:27], v[136:139], v[160:163], v[24:27]
	s_waitcnt lgkmcnt(1)
	v_mfma_f32_16x16x32_bf16 v[16:19], v[128:131], v[168:171], v[16:19]
	v_mfma_f32_16x16x32_bf16 v[8:11], v[136:139], v[168:171], v[8:11]
	v_mfma_f32_16x16x32_bf16 v[60:63], v[132:135], v[148:151], v[60:63]
	v_mfma_f32_16x16x32_bf16 v[56:59], v[140:143], v[148:151], v[56:59]
	v_mfma_f32_16x16x32_bf16 v[48:51], v[132:135], v[156:159], v[48:51]
	v_mfma_f32_16x16x32_bf16 v[40:43], v[140:143], v[156:159], v[40:43]
	v_mfma_f32_16x16x32_bf16 v[32:35], v[132:135], v[164:167], v[32:35]
	v_mfma_f32_16x16x32_bf16 v[24:27], v[140:143], v[164:167], v[24:27]
	s_waitcnt lgkmcnt(0)
	v_mfma_f32_16x16x32_bf16 v[16:19], v[132:135], v[172:175], v[16:19]
	v_mfma_f32_16x16x32_bf16 v[8:11], v[140:143], v[172:175], v[8:11]
	v_mfma_f32_16x16x32_bf16 v[52:55], v[176:179], v[144:147], v[52:55]
	v_mfma_f32_16x16x32_bf16 v[44:47], v[184:187], v[144:147], v[44:47]
	v_mfma_f32_16x16x32_bf16 v[36:39], v[176:179], v[152:155], v[36:39]
	v_mfma_f32_16x16x32_bf16 v[28:31], v[184:187], v[152:155], v[28:31]
	v_mfma_f32_16x16x32_bf16 v[20:23], v[176:179], v[160:163], v[20:23]
	v_mfma_f32_16x16x32_bf16 v[12:15], v[184:187], v[160:163], v[12:15]
	v_mfma_f32_16x16x32_bf16 v[4:7], v[176:179], v[168:171], v[4:7]
	v_mfma_f32_16x16x32_bf16 v[0:3], v[184:187], v[168:171], v[0:3]
	v_mfma_f32_16x16x32_bf16 v[52:55], v[180:183], v[148:151], v[52:55]
	v_mfma_f32_16x16x32_bf16 v[44:47], v[188:191], v[148:151], v[44:47]
	v_mfma_f32_16x16x32_bf16 v[36:39], v[180:183], v[156:159], v[36:39]
	v_mfma_f32_16x16x32_bf16 v[28:31], v[188:191], v[156:159], v[28:31]
	v_mfma_f32_16x16x32_bf16 v[20:23], v[180:183], v[164:167], v[20:23]
	v_mfma_f32_16x16x32_bf16 v[12:15], v[188:191], v[164:167], v[12:15]
	v_mfma_f32_16x16x32_bf16 v[4:7], v[180:183], v[172:175], v[4:7]
	v_mfma_f32_16x16x32_bf16 v[0:3], v[188:191], v[172:175], v[0:3]
	s_barrier
	ds_read_b128 v[128:131], v227
	ds_read_b128 v[132:135], v227 offset:1024
	ds_read_b128 v[136:139], v227 offset:2048
	ds_read_b128 v[140:143], v227 offset:3072
	ds_read_b128 v[144:147], v225 offset:32768
	ds_read_b128 v[148:151], v225 offset:33792
	ds_read_b128 v[152:155], v225 offset:34816
	ds_read_b128 v[156:159], v225 offset:35840
	ds_read_b128 v[160:163], v225 offset:36864
	ds_read_b128 v[164:167], v225 offset:37888
	ds_read_b128 v[168:171], v225 offset:38912
	ds_read_b128 v[172:175], v225 offset:39936
	s_add_u32 s96, s8, 0x80000
	s_addc_u32 s97, s9, 0
	s_mov_b32 m0, s65
	s_nop 0
	global_load_lds_dwordx4 v221, s[96:97]
	s_add_u32 s96, s8, 0x82000
	s_addc_u32 s97, s9, 0
	s_mov_b32 m0, s66
	s_nop 0
	global_load_lds_dwordx4 v221, s[96:97]
	s_waitcnt lgkmcnt(8)
	s_waitcnt vmcnt(10)
	s_barrier
	s_waitcnt lgkmcnt(7)
	v_mfma_f32_16x16x32_bf16 v[124:127], v[128:131], v[144:147], v[124:127]
	v_mfma_f32_16x16x32_bf16 v[120:123], v[136:139], v[144:147], v[120:123]
	s_waitcnt lgkmcnt(5)
	v_mfma_f32_16x16x32_bf16 v[116:119], v[128:131], v[152:155], v[116:119]
	v_mfma_f32_16x16x32_bf16 v[112:115], v[136:139], v[152:155], v[112:115]
	s_waitcnt lgkmcnt(3)
	v_mfma_f32_16x16x32_bf16 v[96:99], v[128:131], v[160:163], v[96:99]
	v_mfma_f32_16x16x32_bf16 v[88:91], v[136:139], v[160:163], v[88:91]
	s_waitcnt lgkmcnt(1)
	v_mfma_f32_16x16x32_bf16 v[80:83], v[128:131], v[168:171], v[80:83]
	v_mfma_f32_16x16x32_bf16 v[72:75], v[136:139], v[168:171], v[72:75]
	v_mfma_f32_16x16x32_bf16 v[124:127], v[132:135], v[148:151], v[124:127]
	v_mfma_f32_16x16x32_bf16 v[120:123], v[140:143], v[148:151], v[120:123]
	v_mfma_f32_16x16x32_bf16 v[116:119], v[132:135], v[156:159], v[116:119]
	v_mfma_f32_16x16x32_bf16 v[112:115], v[140:143], v[156:159], v[112:115]
	v_mfma_f32_16x16x32_bf16 v[96:99], v[132:135], v[164:167], v[96:99]
	v_mfma_f32_16x16x32_bf16 v[88:91], v[140:143], v[164:167], v[88:91]
	s_waitcnt lgkmcnt(0)
	v_mfma_f32_16x16x32_bf16 v[80:83], v[132:135], v[172:175], v[80:83]
	v_mfma_f32_16x16x32_bf16 v[72:75], v[140:143], v[172:175], v[72:75]
	s_barrier
	ds_read_b128 v[176:179], v228
	ds_read_b128 v[180:183], v228 offset:1024
	ds_read_b128 v[184:187], v228 offset:2048
	ds_read_b128 v[188:191], v228 offset:3072
	s_add_u32 s96, s54, 0x4000
	s_addc_u32 s97, s55, 0
	s_mov_b32 m0, s69
	s_nop 0
	global_load_lds_dwordx4 v221, s[96:97]
	s_add_u32 s96, s54, 0x6000
	s_addc_u32 s97, s55, 0
	s_mov_b32 m0, s70
	s_nop 0
	global_load_lds_dwordx4 v221, s[96:97]
	s_waitcnt vmcnt(10)
	s_barrier
; #define PG8_STAGE(bufoff, gbase, hoff, imm) do { _Pragma("unroll") for (int _i = 0; _i < 2; ++_i) { \
;         asm volatile("s_mov_b32 m0, %0\n\ts_nop 0\n\tglobal_load_lds_dwordx4 %1, %2" \
;             :: "s"(lds0 + (unsigned)((bufoff) + _i * 8192)), "v"(voff0), "s"((const char*)(gbase) + (size_t)(hoff) + (size_t)(_i * 8192)) : "memory"); } } while (0)
; #define PG8_LDA(dst, b, h) do { _Pragma("unroll") for (int m = 0; m < 4; ++m) _Pragma("unroll") for (int k = 0; k < 2; ++k) dst[m][k] = *(const LAS bf16x8*)(lds + PG8_SA(b, h) + aoff + m * 2048 + k * 1024); } while (0)
; #define PG8_MMA(ai, bj, At, Bt) do { __builtin_amdgcn_s_setprio(1); _Pragma("unroll") for (int m = 0; m < 4; ++m) _Pragma("unroll") for (int n = 0; n < 2; ++n) _Pragma("unroll") for (int k = 0; k < 2; ++k) \
;         acc[ai][bj][m][n] = __builtin_amdgcn_mfma_f32_16x16x32_bf16(Bt[n][k], At[m][k], acc[ai][bj][m][n], 0, 0, 0); __builtin_amdgcn_s_setprio(0); } while (0)
; #define PG8_WAIT_V(n) asm volatile("s_waitcnt vmcnt(" #n ")" ::: "memory")
; #define PG8_WAIT_L(n) asm volatile("s_waitcnt lgkmcnt(" #n ")" ::: "memory")
; #define PG8_BAR __builtin_amdgcn_s_barrier()
; #define PG8_SCHED __builtin_amdgcn_sched_barrier(0)
; template <class Epi>
; __device__ __forceinline__ void gemm_phase(LAS unsigned char* lds, const Gemm g, const StaticOrder& S, const Epi& E) {
;     ...
;             PG8_BAR; PG8_WAIT_L(0); PG8_MMA(0, 1, At, B1); PG8_BAR;
;             PG8_LDA(At, 1, 1); PG8_STAGE(PG8_SA(1, 0), a2 + KS, 0, 0);
;             PG8_BAR; PG8_WAIT_L(0); PG8_MMA(1, 0, At, B0); PG8_BAR; PG8_SCHED;
;             PG8_STAGE(PG8_SB(1, 1), b2 + KS, hB, 0);
;             PG8_WAIT_V(6); PG8_BAR; PG8_MMA(1, 1, At, B1); PG8_BAR;
;         }
;     __device__ __forceinline__ void operator()(f32x4 (&acc)[2][2][4][2], const Unit& u, int wr, int wc, int fr, int fq, LAS unsigned char*) const {
;         const int b = u.pm >> 6;
;         const int col0 = u.pn * BM + wc * 32 + 8 * fq;
;         const size_t off0 = (size_t)(u.pm * BM + wr * 64 + fr) * D + col0;
;         f32x4 sc[2][2];
; #pragma unroll
;         for (int bj = 0; bj < 2; ++bj)
; #pragma unroll
;             for (int n = 0; n < 2; ++n) { f32x4 gt = *(const f32x4*)(gate + (size_t)b * MODW + col0 + bj * HALF + n * 4); sc[bj][n] = gt + 1.0f;
;                 if (cs) sc[bj][n] *= *(const f32x4*)(cs + col0 + bj * HALF + n * 4); }
	s_waitcnt lgkmcnt(3)
	v_mfma_f32_16x16x32_bf16 v[108:111], v[176:179], v[144:147], v[108:111]
	s_waitcnt lgkmcnt(1)
	v_mfma_f32_16x16x32_bf16 v[104:107], v[184:187], v[144:147], v[104:107]
	v_mfma_f32_16x16x32_bf16 v[100:103], v[176:179], v[152:155], v[100:103]
	v_mfma_f32_16x16x32_bf16 v[92:95], v[184:187], v[152:155], v[92:95]
	v_mfma_f32_16x16x32_bf16 v[84:87], v[176:179], v[160:163], v[84:87]
	v_mfma_f32_16x16x32_bf16 v[76:79], v[184:187], v[160:163], v[76:79]
	v_mfma_f32_16x16x32_bf16 v[68:71], v[176:179], v[168:171], v[68:71]
	v_mfma_f32_16x16x32_bf16 v[64:67], v[184:187], v[168:171], v[64:67]
	v_mfma_f32_16x16x32_bf16 v[108:111], v[180:183], v[148:151], v[108:111]
	s_waitcnt lgkmcnt(0)
	v_mfma_f32_16x16x32_bf16 v[104:107], v[188:191], v[148:151], v[104:107]
	v_mfma_f32_16x16x32_bf16 v[100:103], v[180:183], v[156:159], v[100:103]
	v_mfma_f32_16x16x32_bf16 v[92:95], v[188:191], v[156:159], v[92:95]
	v_mfma_f32_16x16x32_bf16 v[84:87], v[180:183], v[164:167], v[84:87]
	v_mfma_f32_16x16x32_bf16 v[76:79], v[188:191], v[164:167], v[76:79]
	v_mfma_f32_16x16x32_bf16 v[68:71], v[180:183], v[172:175], v[68:71]
	v_mfma_f32_16x16x32_bf16 v[64:67], v[188:191], v[172:175], v[64:67]
	s_barrier
	ds_read_b128 v[144:147], v225 offset:49152
	ds_read_b128 v[148:151], v225 offset:50176
	ds_read_b128 v[152:155], v225 offset:51200
	ds_read_b128 v[156:159], v225 offset:52224
	ds_read_b128 v[160:163], v225 offset:53248
	ds_read_b128 v[164:167], v225 offset:54272
	ds_read_b128 v[168:171], v225 offset:55296
	ds_read_b128 v[172:175], v225 offset:56320
	s_add_u32 s96, s8, 0x4000
	s_addc_u32 s97, s9, 0
	s_mov_b32 m0, s71
	s_nop 0
	global_load_lds_dwordx4 v221, s[96:97]
	s_add_u32 s8, s8, 0x6000
	s_addc_u32 s9, s9, 0
	s_mov_b32 m0, s72
	s_nop 0
	global_load_lds_dwordx4 v221, s[8:9]
	s_add_u32 s8, s54, 0x24000
	s_addc_u32 s9, s55, 0
	s_mov_b32 m0, s73
	s_nop 0
	global_load_lds_dwordx4 v221, s[8:9]
	s_add_u32 s8, s54, 0x26000
	s_addc_u32 s9, s55, 0
	s_mov_b32 m0, s85
	s_nop 0
	global_load_lds_dwordx4 v221, s[8:9]
	s_waitcnt vmcnt(10)
	s_barrier
	s_waitcnt lgkmcnt(7)
	v_mfma_f32_16x16x32_bf16 v[60:63], v[128:131], v[144:147], v[60:63]
	v_mfma_f32_16x16x32_bf16 v[56:59], v[136:139], v[144:147], v[56:59]
	s_waitcnt lgkmcnt(5)
	v_mfma_f32_16x16x32_bf16 v[48:51], v[128:131], v[152:155], v[48:51]
	v_mfma_f32_16x16x32_bf16 v[40:43], v[136:139], v[152:155], v[40:43]
	s_waitcnt lgkmcnt(3)
	v_mfma_f32_16x16x32_bf16 v[32:35], v[128:131], v[160:163], v[32:35]
	v_mfma_f32_16x16x32_bf16 v[24:27], v[136:139], v[160:163], v[24:27]
	s_waitcnt lgkmcnt(1)
	v_mfma_f32_16x16x32_bf16 v[16:19], v[128:131], v[168:171], v[16:19]
	v_mfma_f32_16x16x32_bf16 v[8:11], v[136:139], v[168:171], v[8:11]
	v_mfma_f32_16x16x32_bf16 v[60:63], v[132:135], v[148:151], v[60:63]
	v_mfma_f32_16x16x32_bf16 v[56:59], v[140:143], v[148:151], v[56:59]
	v_mfma_f32_16x16x32_bf16 v[48:51], v[132:135], v[156:159], v[48:51]
	v_mfma_f32_16x16x32_bf16 v[40:43], v[140:143], v[156:159], v[40:43]
	v_mfma_f32_16x16x32_bf16 v[32:35], v[132:135], v[164:167], v[32:35]
	v_mfma_f32_16x16x32_bf16 v[24:27], v[140:143], v[164:167], v[24:27]
	s_waitcnt lgkmcnt(0)
	v_mfma_f32_16x16x32_bf16 v[16:19], v[132:135], v[172:175], v[16:19]
	v_mfma_f32_16x16x32_bf16 v[8:11], v[140:143], v[172:175], v[8:11]
	v_mfma_f32_16x16x32_bf16 v[52:55], v[176:179], v[144:147], v[52:55]
	v_mfma_f32_16x16x32_bf16 v[44:47], v[184:187], v[144:147], v[44:47]
	v_mfma_f32_16x16x32_bf16 v[36:39], v[176:179], v[152:155], v[36:39]
	v_mfma_f32_16x16x32_bf16 v[28:31], v[184:187], v[152:155], v[28:31]
	v_mfma_f32_16x16x32_bf16 v[20:23], v[176:179], v[160:163], v[20:23]
	v_mfma_f32_16x16x32_bf16 v[12:15], v[184:187], v[160:163], v[12:15]
	v_mfma_f32_16x16x32_bf16 v[4:7], v[176:179], v[168:171], v[4:7]
	v_mfma_f32_16x16x32_bf16 v[0:3], v[184:187], v[168:171], v[0:3]
	v_mfma_f32_16x16x32_bf16 v[52:55], v[180:183], v[148:151], v[52:55]
	v_mfma_f32_16x16x32_bf16 v[44:47], v[188:191], v[148:151], v[44:47]
	v_mfma_f32_16x16x32_bf16 v[36:39], v[180:183], v[156:159], v[36:39]
	v_mfma_f32_16x16x32_bf16 v[28:31], v[188:191], v[156:159], v[28:31]
	v_mfma_f32_16x16x32_bf16 v[20:23], v[180:183], v[164:167], v[20:23]
	v_mfma_f32_16x16x32_bf16 v[12:15], v[188:191], v[164:167], v[12:15]
	v_mfma_f32_16x16x32_bf16 v[4:7], v[180:183], v[172:175], v[4:7]
	v_mfma_f32_16x16x32_bf16 v[0:3], v[188:191], v[172:175], v[0:3]
	s_add_i32 s95, s95, 2
	s_add_u32 s93, s93, 0x8000
	s_addc_u32 s94, s94, 0
	s_cmp_gt_u32 s95, 5
	s_mov_b64 s[8:9], s[52:53]
	s_barrier
	s_cbranch_scc0 .LBB0_293
	s_ashr_i32 s0, s89, 6
	v_lshl_or_b32 v128, s92, 8, v223
	s_mul_hi_i32 s1, s0, 0xc000
	s_mul_i32 s0, s0, 0xc000
	v_ashrrev_i32_e32 v129, 31, v128
	s_add_u32 s0, s67, s0
	s_addc_u32 s1, s68, s1
	v_lshlrev_b64 v[130:131], 2, v[128:129]
	v_lshl_add_u64 v[132:133], s[0:1], 0, v[130:131]
	v_cndmask_b32_e64 v138, 0, 1, s[42:43]
	v_cmp_ne_u32_e64 s[8:9], 1, v138
	v_lshl_add_u64 v[130:131], s[38:39], 0, v[130:131]
	global_load_dwordx4 v[196:199], v[132:133], off
	global_load_dwordx4 v[200:203], v[132:133], off offset:16
	global_load_dwordx4 v[204:207], v[132:133], off offset:512
	global_load_dwordx4 v[208:211], v[132:133], off offset:528
	v_readlane_b32 s96, v255, 3
	v_readlane_b32 s97, v255, 4
	s_andn2_b64 vcc, exec, s[42:43]
	s_cbranch_vccnz .Lp2_nocs
	global_load_dwordx4 v[134:137], v[130:131], off
	global_load_dwordx4 v[138:141], v[130:131], off offset:16
	global_load_dwordx4 v[142:145], v[130:131], off offset:512
	global_load_dwordx4 v[146:149], v[130:131], off offset:528

; #define PG8_STAGE(bufoff, gbase, hoff, imm) do { _Pragma("unroll") for (int _i = 0; _i < 2; ++_i) { \
;         asm volatile("s_mov_b32 m0, %0\n\ts_nop 0\n\tglobal_load_lds_dwordx4 %1, %2" \
;             :: "s"(lds0 + (unsigned)((bufoff) + _i * 8192)), "v"(voff0), "s"((const char*)(gbase) + (size_t)(hoff) + (size_t)(_i * 8192)) : "memory"); } } while (0)
; #define PG8_LDA(dst, b, h) do { _Pragma("unroll") for (int m = 0; m < 4; ++m) _Pragma("unroll") for (int k = 0; k < 2; ++k) dst[m][k] = *(const LAS bf16x8*)(lds + PG8_SA(b, h) + aoff + m * 2048 + k * 1024); } while (0)
; #define PG8_LDB(dst, b, h) do { _Pragma("unroll") for (int n = 0; n < 2; ++n) _Pragma("unroll") for (int k = 0; k < 2; ++k) dst[n][k] = *(const LAS bf16x8*)(lds + PG8_SB(b, h) + boff + n * 2048 + k * 1024); } while (0)
; #define PG8_MMA(ai, bj, At, Bt) do { __builtin_amdgcn_s_setprio(1); _Pragma("unroll") for (int m = 0; m < 4; ++m) _Pragma("unroll") for (int n = 0; n < 2; ++n) _Pragma("unroll") for (int k = 0; k < 2; ++k) \
;         acc[ai][bj][m][n] = __builtin_amdgcn_mfma_f32_16x16x32_bf16(Bt[n][k], At[m][k], acc[ai][bj][m][n], 0, 0, 0); __builtin_amdgcn_s_setprio(0); } while (0)
; #define PG8_WAIT_V(n) asm volatile("s_waitcnt vmcnt(" #n ")" ::: "memory")
; #define PG8_WAIT_L(n) asm volatile("s_waitcnt lgkmcnt(" #n ")" ::: "memory")
; #define PG8_BAR __builtin_amdgcn_s_barrier()
; #define PG8_SCHED __builtin_amdgcn_sched_barrier(0)
; template <class Epi>
; __device__ __forceinline__ void gemm_phase(LAS unsigned char* lds, const Gemm g, const StaticOrder& S, const Epi& E) {
;     ...
;             PG8_LDB(B0, 0, 0); PG8_SCHED; PG8_LDA(At, 0, 0); PG8_STAGE(PG8_SA(1, 1), aT + KS, hA, 0);
;             PG8_WAIT_L(8); PG8_BAR; PG8_WAIT_L(0); PG8_MMA(0, 0, At, B0); PG8_BAR; PG8_SCHED;
;             PG8_LDB(B1, 0, 1); PG8_STAGE(PG8_SB(0, 0), b2, 0, 0);
;             PG8_BAR; PG8_WAIT_L(0); PG8_MMA(0, 1, At, B1); PG8_BAR;
;             PG8_LDA(At, 0, 1); PG8_STAGE(PG8_SA(0, 0), a2, 0, 0);
;             PG8_BAR; PG8_WAIT_L(0); PG8_MMA(1, 0, At, B0); PG8_BAR; PG8_SCHED;
;             PG8_STAGE(PG8_SB(0, 1), b2, hB, 0);
;             PG8_WAIT_V(6); PG8_BAR; PG8_MMA(1, 1, At, B1); PG8_BAR;
.LBB0_434:
	s_add_u32 s56, s54, 0x8000
	v_add_u32_e32 v128, 0x10000, v133
	s_addc_u32 s57, s55, 0
	ds_read_b128 v[136:139], v128
	ds_read_b128 v[140:143], v128 offset:1024
	ds_read_b128 v[144:147], v128 offset:2048
	ds_read_b128 v[148:151], v128 offset:3072
	s_add_u32 s58, s54, 0x84000
	s_addc_u32 s59, s55, 0
	s_add_u32 s66, s54, 0x86000
	s_addc_u32 s67, s55, 0
	s_cmp_eq_u32 s65, 28
	s_cselect_b32 s55, s0, s57
	s_cselect_b32 s54, s1, s56
	ds_read_b128 v[152:155], v134
	ds_read_b128 v[156:159], v134 offset:1024
	ds_read_b128 v[160:163], v134 offset:2048
	ds_read_b128 v[164:167], v134 offset:3072
	ds_read_b128 v[168:171], v134 offset:4096
	ds_read_b128 v[172:175], v134 offset:5120
	ds_read_b128 v[176:179], v134 offset:6144
	ds_read_b128 v[180:183], v134 offset:7168
	s_mov_b32 m0, s50
	s_nop 0
	global_load_lds_dwordx4 v130, s[58:59]
	s_mov_b32 m0, s51
	s_nop 0
	global_load_lds_dwordx4 v130, s[66:67]
	s_waitcnt lgkmcnt(8)
	s_waitcnt vmcnt(10)
	s_barrier
	s_waitcnt lgkmcnt(7)
	v_mfma_f32_16x16x32_bf16 v[124:127], v[136:139], v[152:155], v[124:127]
	v_mfma_f32_16x16x32_bf16 v[120:123], v[144:147], v[152:155], v[120:123]
	s_waitcnt lgkmcnt(5)
	v_mfma_f32_16x16x32_bf16 v[116:119], v[136:139], v[160:163], v[116:119]
	v_mfma_f32_16x16x32_bf16 v[108:111], v[144:147], v[160:163], v[108:111]
	s_waitcnt lgkmcnt(3)
	v_mfma_f32_16x16x32_bf16 v[100:103], v[136:139], v[168:171], v[100:103]
	v_mfma_f32_16x16x32_bf16 v[92:95], v[144:147], v[168:171], v[92:95]
	s_waitcnt lgkmcnt(1)
	v_mfma_f32_16x16x32_bf16 v[84:87], v[136:139], v[176:179], v[84:87]
	v_mfma_f32_16x16x32_bf16 v[76:79], v[144:147], v[176:179], v[76:79]
	v_mfma_f32_16x16x32_bf16 v[124:127], v[140:143], v[156:159], v[124:127]
	v_mfma_f32_16x16x32_bf16 v[120:123], v[148:151], v[156:159], v[120:123]
	v_mfma_f32_16x16x32_bf16 v[116:119], v[140:143], v[164:167], v[116:119]
	v_mfma_f32_16x16x32_bf16 v[108:111], v[148:151], v[164:167], v[108:111]
	v_mfma_f32_16x16x32_bf16 v[100:103], v[140:143], v[172:175], v[100:103]
	v_mfma_f32_16x16x32_bf16 v[92:95], v[148:151], v[172:175], v[92:95]
	s_waitcnt lgkmcnt(0)
	v_mfma_f32_16x16x32_bf16 v[84:87], v[140:143], v[180:183], v[84:87]
	v_mfma_f32_16x16x32_bf16 v[76:79], v[148:151], v[180:183], v[76:79]
	s_barrier
	v_add_u32_e32 v128, 0x14000, v133
	ds_read_b128 v[184:187], v128
	ds_read_b128 v[200:203], v128 offset:1024
	ds_read_b128 v[204:207], v128 offset:2048
	ds_read_b128 v[208:211], v128 offset:3072
	s_cselect_b32 s58, s9, s63
	s_cselect_b32 s59, s7, s64
	s_mov_b32 m0, s26
	s_nop 0
	global_load_lds_dwordx4 v130, s[58:59]
	s_add_u32 s66, s58, 0x2000
	s_addc_u32 s67, s59, 0
	s_mov_b32 m0, s27
	s_nop 0
	global_load_lds_dwordx4 v130, s[66:67]
	s_waitcnt vmcnt(10)
	s_barrier
	s_waitcnt lgkmcnt(3)
	v_mfma_f32_16x16x32_bf16 v[112:115], v[184:187], v[152:155], v[112:115]
	s_waitcnt lgkmcnt(1)
	v_mfma_f32_16x16x32_bf16 v[104:107], v[204:207], v[152:155], v[104:107]
	v_mfma_f32_16x16x32_bf16 v[96:99], v[184:187], v[160:163], v[96:99]
	v_mfma_f32_16x16x32_bf16 v[88:91], v[204:207], v[160:163], v[88:91]
	v_mfma_f32_16x16x32_bf16 v[80:83], v[184:187], v[168:171], v[80:83]
	v_mfma_f32_16x16x32_bf16 v[72:75], v[204:207], v[168:171], v[72:75]
	v_mfma_f32_16x16x32_bf16 v[68:71], v[184:187], v[176:179], v[68:71]
	v_mfma_f32_16x16x32_bf16 v[64:67], v[204:207], v[176:179], v[64:67]
	v_mfma_f32_16x16x32_bf16 v[112:115], v[200:203], v[156:159], v[112:115]
	s_waitcnt lgkmcnt(0)
	v_mfma_f32_16x16x32_bf16 v[104:107], v[208:211], v[156:159], v[104:107]
	v_mfma_f32_16x16x32_bf16 v[96:99], v[200:203], v[164:167], v[96:99]
	v_mfma_f32_16x16x32_bf16 v[88:91], v[208:211], v[164:167], v[88:91]
	v_mfma_f32_16x16x32_bf16 v[80:83], v[200:203], v[172:175], v[80:83]
	v_mfma_f32_16x16x32_bf16 v[72:75], v[208:211], v[172:175], v[72:75]
	v_mfma_f32_16x16x32_bf16 v[68:71], v[200:203], v[180:183], v[68:71]
	v_mfma_f32_16x16x32_bf16 v[64:67], v[208:211], v[180:183], v[64:67]
	s_barrier
	ds_read_b128 v[152:155], v134 offset:16384
	ds_read_b128 v[156:159], v134 offset:17408
	ds_read_b128 v[160:163], v134 offset:18432
	ds_read_b128 v[164:167], v134 offset:19456
	ds_read_b128 v[168:171], v134 offset:20480
	ds_read_b128 v[172:175], v134 offset:21504
	ds_read_b128 v[176:179], v134 offset:22528
	ds_read_b128 v[180:183], v134 offset:23552
	s_mov_b32 m0, s25
	s_nop 0
	global_load_lds_dwordx4 v130, s[54:55]
	s_add_u32 s66, s54, 0x2000
	s_addc_u32 s67, s55, 0
	s_mov_b32 m0, s28
	s_nop 0
	global_load_lds_dwordx4 v130, s[66:67]
	s_add_u32 s66, s58, 0x80000
	s_addc_u32 s67, s59, 0
	s_mov_b32 m0, s29
	s_nop 0
	global_load_lds_dwordx4 v130, s[66:67]
	s_add_u32 s66, s58, 0x82000
	s_addc_u32 s67, s59, 0
	s_mov_b32 m0, s30
	s_nop 0
	global_load_lds_dwordx4 v130, s[66:67]
	s_waitcnt vmcnt(10)
	s_barrier
; #define PG8_STAGE(bufoff, gbase, hoff, imm) do { _Pragma("unroll") for (int _i = 0; _i < 2; ++_i) { \
;         asm volatile("s_mov_b32 m0, %0\n\ts_nop 0\n\tglobal_load_lds_dwordx4 %1, %2" \
;             :: "s"(lds0 + (unsigned)((bufoff) + _i * 8192)), "v"(voff0), "s"((const char*)(gbase) + (size_t)(hoff) + (size_t)(_i * 8192)) : "memory"); } } while (0)
; #define PG8_LDA(dst, b, h) do { _Pragma("unroll") for (int m = 0; m < 4; ++m) _Pragma("unroll") for (int k = 0; k < 2; ++k) dst[m][k] = *(const LAS bf16x8*)(lds + PG8_SA(b, h) + aoff + m * 2048 + k * 1024); } while (0)
; #define PG8_LDB(dst, b, h) do { _Pragma("unroll") for (int n = 0; n < 2; ++n) _Pragma("unroll") for (int k = 0; k < 2; ++k) dst[n][k] = *(const LAS bf16x8*)(lds + PG8_SB(b, h) + boff + n * 2048 + k * 1024); } while (0)
; #define PG8_MMA(ai, bj, At, Bt) do { __builtin_amdgcn_s_setprio(1); _Pragma("unroll") for (int m = 0; m < 4; ++m) _Pragma("unroll") for (int n = 0; n < 2; ++n) _Pragma("unroll") for (int k = 0; k < 2; ++k) \
;         acc[ai][bj][m][n] = __builtin_amdgcn_mfma_f32_16x16x32_bf16(Bt[n][k], At[m][k], acc[ai][bj][m][n], 0, 0, 0); __builtin_amdgcn_s_setprio(0); } while (0)
; #define PG8_WAIT_V(n) asm volatile("s_waitcnt vmcnt(" #n ")" ::: "memory")
; #define PG8_WAIT_L(n) asm volatile("s_waitcnt lgkmcnt(" #n ")" ::: "memory")
; #define PG8_BAR __builtin_amdgcn_s_barrier()
; #define PG8_SCHED __builtin_amdgcn_sched_barrier(0)
; template <class Epi>
; __device__ __forceinline__ void gemm_phase(LAS unsigned char* lds, const Gemm g, const StaticOrder& S, const Epi& E) {
;     ...
;             PG8_BAR; PG8_WAIT_L(0); PG8_MMA(1, 0, At, B0); PG8_BAR; PG8_SCHED;
;             PG8_STAGE(PG8_SB(0, 1), b2, hB, 0);
;             PG8_WAIT_V(6); PG8_BAR; PG8_MMA(1, 1, At, B1); PG8_BAR;
;             PG8_LDB(B0, 1, 0); PG8_SCHED; PG8_LDA(At, 1, 0); PG8_STAGE(PG8_SA(0, 1), a2, hA, 0);
;             PG8_WAIT_L(8); PG8_BAR; PG8_WAIT_L(0); PG8_MMA(0, 0, At, B0); PG8_BAR; PG8_SCHED;
;             PG8_LDB(B1, 1, 1); PG8_STAGE(PG8_SB(1, 0), b2 + KS, 0, 0);
;             PG8_BAR; PG8_WAIT_L(0); PG8_MMA(0, 1, At, B1); PG8_BAR;
	s_waitcnt lgkmcnt(7)
	v_mfma_f32_16x16x32_bf16 v[60:63], v[136:139], v[152:155], v[60:63]
	v_mfma_f32_16x16x32_bf16 v[56:59], v[144:147], v[152:155], v[56:59]
	s_waitcnt lgkmcnt(5)
	v_mfma_f32_16x16x32_bf16 v[52:55], v[136:139], v[160:163], v[52:55]
	v_mfma_f32_16x16x32_bf16 v[44:47], v[144:147], v[160:163], v[44:47]
	s_waitcnt lgkmcnt(3)
	v_mfma_f32_16x16x32_bf16 v[36:39], v[136:139], v[168:171], v[36:39]
	v_mfma_f32_16x16x32_bf16 v[28:31], v[144:147], v[168:171], v[28:31]
	s_waitcnt lgkmcnt(1)
	v_mfma_f32_16x16x32_bf16 v[20:23], v[136:139], v[176:179], v[20:23]
	v_mfma_f32_16x16x32_bf16 v[12:15], v[144:147], v[176:179], v[12:15]
	v_mfma_f32_16x16x32_bf16 v[60:63], v[140:143], v[156:159], v[60:63]
	v_mfma_f32_16x16x32_bf16 v[56:59], v[148:151], v[156:159], v[56:59]
	v_mfma_f32_16x16x32_bf16 v[52:55], v[140:143], v[164:167], v[52:55]
	v_mfma_f32_16x16x32_bf16 v[44:47], v[148:151], v[164:167], v[44:47]
	v_mfma_f32_16x16x32_bf16 v[36:39], v[140:143], v[172:175], v[36:39]
	v_mfma_f32_16x16x32_bf16 v[28:31], v[148:151], v[172:175], v[28:31]
	s_waitcnt lgkmcnt(0)
	v_mfma_f32_16x16x32_bf16 v[20:23], v[140:143], v[180:183], v[20:23]
	v_mfma_f32_16x16x32_bf16 v[12:15], v[148:151], v[180:183], v[12:15]
	v_mfma_f32_16x16x32_bf16 v[48:51], v[184:187], v[152:155], v[48:51]
	v_mfma_f32_16x16x32_bf16 v[40:43], v[204:207], v[152:155], v[40:43]
	v_mfma_f32_16x16x32_bf16 v[32:35], v[184:187], v[160:163], v[32:35]
	v_mfma_f32_16x16x32_bf16 v[24:27], v[204:207], v[160:163], v[24:27]
	v_mfma_f32_16x16x32_bf16 v[16:19], v[184:187], v[168:171], v[16:19]
	v_mfma_f32_16x16x32_bf16 v[8:11], v[204:207], v[168:171], v[8:11]
	v_mfma_f32_16x16x32_bf16 v[4:7], v[184:187], v[176:179], v[4:7]
	v_mfma_f32_16x16x32_bf16 v[0:3], v[204:207], v[176:179], v[0:3]
	v_mfma_f32_16x16x32_bf16 v[48:51], v[200:203], v[156:159], v[48:51]
	v_mfma_f32_16x16x32_bf16 v[40:43], v[208:211], v[156:159], v[40:43]
	v_mfma_f32_16x16x32_bf16 v[32:35], v[200:203], v[164:167], v[32:35]
	v_mfma_f32_16x16x32_bf16 v[24:27], v[208:211], v[164:167], v[24:27]
	v_mfma_f32_16x16x32_bf16 v[16:19], v[200:203], v[172:175], v[16:19]
	v_mfma_f32_16x16x32_bf16 v[8:11], v[208:211], v[172:175], v[8:11]
	v_mfma_f32_16x16x32_bf16 v[4:7], v[200:203], v[180:183], v[4:7]
	v_mfma_f32_16x16x32_bf16 v[0:3], v[208:211], v[180:183], v[0:3]
	v_add_u32_e32 v128, 0x18000, v133
	s_barrier
	ds_read_b128 v[136:139], v128
	ds_read_b128 v[140:143], v128 offset:1024
	ds_read_b128 v[144:147], v128 offset:2048
	ds_read_b128 v[148:151], v128 offset:3072
	ds_read_b128 v[152:155], v134 offset:32768
	ds_read_b128 v[156:159], v134 offset:33792
	ds_read_b128 v[160:163], v134 offset:34816
	ds_read_b128 v[164:167], v134 offset:35840
	ds_read_b128 v[168:171], v134 offset:36864
	ds_read_b128 v[172:175], v134 offset:37888
	ds_read_b128 v[176:179], v134 offset:38912
	ds_read_b128 v[180:183], v134 offset:39936
	s_add_u32 s66, s54, 0x80000
	s_addc_u32 s67, s55, 0
	s_mov_b32 m0, s34
	s_nop 0
	global_load_lds_dwordx4 v130, s[66:67]
	s_add_u32 s66, s54, 0x82000
	s_addc_u32 s67, s55, 0
	s_mov_b32 m0, s37
	s_nop 0
	global_load_lds_dwordx4 v130, s[66:67]
	s_waitcnt lgkmcnt(8)
	s_waitcnt vmcnt(10)
	s_barrier
	s_waitcnt lgkmcnt(7)
	v_mfma_f32_16x16x32_bf16 v[124:127], v[136:139], v[152:155], v[124:127]
	v_mfma_f32_16x16x32_bf16 v[120:123], v[144:147], v[152:155], v[120:123]
	s_waitcnt lgkmcnt(5)
	v_mfma_f32_16x16x32_bf16 v[116:119], v[136:139], v[160:163], v[116:119]
	v_mfma_f32_16x16x32_bf16 v[108:111], v[144:147], v[160:163], v[108:111]
	s_waitcnt lgkmcnt(3)
	v_mfma_f32_16x16x32_bf16 v[100:103], v[136:139], v[168:171], v[100:103]
	v_mfma_f32_16x16x32_bf16 v[92:95], v[144:147], v[168:171], v[92:95]
	s_waitcnt lgkmcnt(1)
	v_mfma_f32_16x16x32_bf16 v[84:87], v[136:139], v[176:179], v[84:87]
	v_mfma_f32_16x16x32_bf16 v[76:79], v[144:147], v[176:179], v[76:79]
	v_mfma_f32_16x16x32_bf16 v[124:127], v[140:143], v[156:159], v[124:127]
	v_mfma_f32_16x16x32_bf16 v[120:123], v[148:151], v[156:159], v[120:123]
	v_mfma_f32_16x16x32_bf16 v[116:119], v[140:143], v[164:167], v[116:119]
	v_mfma_f32_16x16x32_bf16 v[108:111], v[148:151], v[164:167], v[108:111]
	v_mfma_f32_16x16x32_bf16 v[100:103], v[140:143], v[172:175], v[100:103]
	v_mfma_f32_16x16x32_bf16 v[92:95], v[148:151], v[172:175], v[92:95]
	s_waitcnt lgkmcnt(0)
	v_mfma_f32_16x16x32_bf16 v[84:87], v[140:143], v[180:183], v[84:87]
	v_mfma_f32_16x16x32_bf16 v[76:79], v[148:151], v[180:183], v[76:79]
	s_barrier
	v_add_u32_e32 v128, 0x1c000, v133
	ds_read_b128 v[184:187], v128
	ds_read_b128 v[200:203], v128 offset:1024
	ds_read_b128 v[204:207], v128 offset:2048
	ds_read_b128 v[208:211], v128 offset:3072
	s_add_u32 s66, s58, 0x4000
	s_addc_u32 s67, s59, 0
	s_mov_b32 m0, s38
	s_nop 0
	global_load_lds_dwordx4 v130, s[66:67]
	s_add_u32 s66, s58, 0x6000
	s_addc_u32 s67, s59, 0
	s_mov_b32 m0, s39
	s_nop 0
	global_load_lds_dwordx4 v130, s[66:67]
	s_waitcnt vmcnt(10)
	s_barrier
	s_waitcnt lgkmcnt(3)
	v_mfma_f32_16x16x32_bf16 v[112:115], v[184:187], v[152:155], v[112:115]
	s_waitcnt lgkmcnt(1)
	v_mfma_f32_16x16x32_bf16 v[104:107], v[204:207], v[152:155], v[104:107]
	v_mfma_f32_16x16x32_bf16 v[96:99], v[184:187], v[160:163], v[96:99]
	v_mfma_f32_16x16x32_bf16 v[88:91], v[204:207], v[160:163], v[88:91]
	v_mfma_f32_16x16x32_bf16 v[80:83], v[184:187], v[168:171], v[80:83]
	v_mfma_f32_16x16x32_bf16 v[72:75], v[204:207], v[168:171], v[72:75]
	v_mfma_f32_16x16x32_bf16 v[68:71], v[184:187], v[176:179], v[68:71]
	v_mfma_f32_16x16x32_bf16 v[64:67], v[204:207], v[176:179], v[64:67]
	v_mfma_f32_16x16x32_bf16 v[112:115], v[200:203], v[156:159], v[112:115]
	s_waitcnt lgkmcnt(0)
	v_mfma_f32_16x16x32_bf16 v[104:107], v[208:211], v[156:159], v[104:107]
	v_mfma_f32_16x16x32_bf16 v[96:99], v[200:203], v[164:167], v[96:99]
	v_mfma_f32_16x16x32_bf16 v[88:91], v[208:211], v[164:167], v[88:91]
	v_mfma_f32_16x16x32_bf16 v[80:83], v[200:203], v[172:175], v[80:83]
	v_mfma_f32_16x16x32_bf16 v[72:75], v[208:211], v[172:175], v[72:75]
	v_mfma_f32_16x16x32_bf16 v[68:71], v[200:203], v[180:183], v[68:71]
	v_mfma_f32_16x16x32_bf16 v[64:67], v[208:211], v[180:183], v[64:67]
	s_barrier
; #define PG8_STAGE(bufoff, gbase, hoff, imm) do { _Pragma("unroll") for (int _i = 0; _i < 2; ++_i) { \
;         asm volatile("s_mov_b32 m0, %0\n\ts_nop 0\n\tglobal_load_lds_dwordx4 %1, %2" \
;             :: "s"(lds0 + (unsigned)((bufoff) + _i * 8192)), "v"(voff0), "s"((const char*)(gbase) + (size_t)(hoff) + (size_t)(_i * 8192)) : "memory"); } } while (0)
; #define PG8_LDA(dst, b, h) do { _Pragma("unroll") for (int m = 0; m < 4; ++m) _Pragma("unroll") for (int k = 0; k < 2; ++k) dst[m][k] = *(const LAS bf16x8*)(lds + PG8_SA(b, h) + aoff + m * 2048 + k * 1024); } while (0)
; #define PG8_MMA(ai, bj, At, Bt) do { __builtin_amdgcn_s_setprio(1); _Pragma("unroll") for (int m = 0; m < 4; ++m) _Pragma("unroll") for (int n = 0; n < 2; ++n) _Pragma("unroll") for (int k = 0; k < 2; ++k) \
;         acc[ai][bj][m][n] = __builtin_amdgcn_mfma_f32_16x16x32_bf16(Bt[n][k], At[m][k], acc[ai][bj][m][n], 0, 0, 0); __builtin_amdgcn_s_setprio(0); } while (0)
; #define PG8_WAIT_V(n) asm volatile("s_waitcnt vmcnt(" #n ")" ::: "memory")
; #define PG8_WAIT_L(n) asm volatile("s_waitcnt lgkmcnt(" #n ")" ::: "memory")
; #define PG8_BAR __builtin_amdgcn_s_barrier()
; #define PG8_SCHED __builtin_amdgcn_sched_barrier(0)
; template <class Epi>
; __device__ __forceinline__ void gemm_phase(LAS unsigned char* lds, const Gemm g, const StaticOrder& S, const Epi& E) {
;     ...
;             PG8_BAR; PG8_WAIT_L(0); PG8_MMA(0, 1, At, B1); PG8_BAR;
;             PG8_LDA(At, 1, 1); PG8_STAGE(PG8_SA(1, 0), a2 + KS, 0, 0);
;             PG8_BAR; PG8_WAIT_L(0); PG8_MMA(1, 0, At, B0); PG8_BAR; PG8_SCHED;
;             PG8_STAGE(PG8_SB(1, 1), b2 + KS, hB, 0);
;             PG8_WAIT_V(6); PG8_BAR; PG8_MMA(1, 1, At, B1); PG8_BAR;
	ds_read_b128 v[152:155], v134 offset:49152
	ds_read_b128 v[156:159], v134 offset:50176
	ds_read_b128 v[160:163], v134 offset:51200
	ds_read_b128 v[164:167], v134 offset:52224
	ds_read_b128 v[168:171], v134 offset:53248
	ds_read_b128 v[172:175], v134 offset:54272
	ds_read_b128 v[176:179], v134 offset:55296
	ds_read_b128 v[180:183], v134 offset:56320
	s_add_u32 s66, s54, 0x4000
	s_addc_u32 s67, s55, 0
	s_mov_b32 m0, s40
	s_nop 0
	global_load_lds_dwordx4 v130, s[66:67]
	s_add_u32 s54, s54, 0x6000
	s_addc_u32 s55, s55, 0
	s_mov_b32 m0, s41
	s_nop 0
	global_load_lds_dwordx4 v130, s[54:55]
	s_add_u32 s54, s58, 0x84000
	s_addc_u32 s55, s59, 0
	s_mov_b32 m0, s42
	s_nop 0
	global_load_lds_dwordx4 v130, s[54:55]
	s_add_u32 s54, s58, 0x86000
	s_addc_u32 s55, s59, 0
	s_mov_b32 m0, s43
	s_nop 0
	global_load_lds_dwordx4 v130, s[54:55]
	s_waitcnt vmcnt(10)
	s_barrier
	s_waitcnt lgkmcnt(7)
	v_mfma_f32_16x16x32_bf16 v[60:63], v[136:139], v[152:155], v[60:63]
	v_mfma_f32_16x16x32_bf16 v[56:59], v[144:147], v[152:155], v[56:59]
	s_waitcnt lgkmcnt(5)
	v_mfma_f32_16x16x32_bf16 v[52:55], v[136:139], v[160:163], v[52:55]
	v_mfma_f32_16x16x32_bf16 v[44:47], v[144:147], v[160:163], v[44:47]
	s_waitcnt lgkmcnt(3)
	v_mfma_f32_16x16x32_bf16 v[36:39], v[136:139], v[168:171], v[36:39]
	v_mfma_f32_16x16x32_bf16 v[28:31], v[144:147], v[168:171], v[28:31]
	s_waitcnt lgkmcnt(1)
	v_mfma_f32_16x16x32_bf16 v[20:23], v[136:139], v[176:179], v[20:23]
	v_mfma_f32_16x16x32_bf16 v[12:15], v[144:147], v[176:179], v[12:15]
	v_mfma_f32_16x16x32_bf16 v[60:63], v[140:143], v[156:159], v[60:63]
	v_mfma_f32_16x16x32_bf16 v[56:59], v[148:151], v[156:159], v[56:59]
	v_mfma_f32_16x16x32_bf16 v[52:55], v[140:143], v[164:167], v[52:55]
	v_mfma_f32_16x16x32_bf16 v[44:47], v[148:151], v[164:167], v[44:47]
	v_mfma_f32_16x16x32_bf16 v[36:39], v[140:143], v[172:175], v[36:39]
	v_mfma_f32_16x16x32_bf16 v[28:31], v[148:151], v[172:175], v[28:31]
	s_waitcnt lgkmcnt(0)
	v_mfma_f32_16x16x32_bf16 v[20:23], v[140:143], v[180:183], v[20:23]
	v_mfma_f32_16x16x32_bf16 v[12:15], v[148:151], v[180:183], v[12:15]
	v_mfma_f32_16x16x32_bf16 v[48:51], v[184:187], v[152:155], v[48:51]
	v_mfma_f32_16x16x32_bf16 v[40:43], v[204:207], v[152:155], v[40:43]
	v_mfma_f32_16x16x32_bf16 v[32:35], v[184:187], v[160:163], v[32:35]
	v_mfma_f32_16x16x32_bf16 v[24:27], v[204:207], v[160:163], v[24:27]
	v_mfma_f32_16x16x32_bf16 v[16:19], v[184:187], v[168:171], v[16:19]
	v_mfma_f32_16x16x32_bf16 v[8:11], v[204:207], v[168:171], v[8:11]
	v_mfma_f32_16x16x32_bf16 v[4:7], v[184:187], v[176:179], v[4:7]
	v_mfma_f32_16x16x32_bf16 v[0:3], v[204:207], v[176:179], v[0:3]
	v_mfma_f32_16x16x32_bf16 v[48:51], v[200:203], v[156:159], v[48:51]
	v_mfma_f32_16x16x32_bf16 v[40:43], v[208:211], v[156:159], v[40:43]
	v_mfma_f32_16x16x32_bf16 v[32:35], v[200:203], v[164:167], v[32:35]
	v_mfma_f32_16x16x32_bf16 v[24:27], v[208:211], v[164:167], v[24:27]
	v_mfma_f32_16x16x32_bf16 v[16:19], v[200:203], v[172:175], v[16:19]
	v_mfma_f32_16x16x32_bf16 v[8:11], v[208:211], v[172:175], v[8:11]
	v_mfma_f32_16x16x32_bf16 v[4:7], v[200:203], v[180:183], v[4:7]
	v_mfma_f32_16x16x32_bf16 v[0:3], v[208:211], v[180:183], v[0:3]
	s_add_i32 s65, s65, 2
	s_add_u32 s63, s63, 0x8000
	s_addc_u32 s64, s64, 0
	s_cmp_gt_u32 s65, 29
	s_mov_b64 s[54:55], s[56:57]
	s_barrier
	s_cbranch_scc0 .LBB0_434
; __device__ __forceinline__ unsigned cvt_pk_bf16(float lo, float hi) { unsigned r; asm volatile("v_cvt_pk_bf16_f32 %0, %1, %2" : "=v"(r) : "v"(lo), "v"(hi)); return r; }
; #define PG8_WAIT_V(n) asm volatile("s_waitcnt vmcnt(" #n ")" ::: "memory")
; #define PG8_BAR __builtin_amdgcn_s_barrier()
; template <class Epi>
; __device__ __forceinline__ void gemm_phase(LAS unsigned char* lds, const Gemm g, const StaticOrder& S, const Epi& E) {
;     ...
;         if (!has_next) break;
; #pragma unroll
;         for (int a = 0; a < 2; ++a)
; #pragma unroll
;             for (int b = 0; b < 2; ++b)
; #pragma unroll
;                 for (int m = 0; m < 4; ++m)
; #pragma unroll
;                     for (int n = 0; n < 2; ++n) acc[a][b][m][n] = (f32x4){0.f, 0.f, 0.f, 0.f};
;         cur = nxt; cA = nA; cB = nB; ++ui;
;     }
;     PG8_WAIT_V(0);
;     if (wr == 0) PG8_BAR;
;     PG8_BAR;
;     __device__ __forceinline__ void operator()(f32x4 (&acc)[2][2][4][2], const Unit& u, int wr, int wc, int fr, int fq, LAS unsigned char*) const {
;         const int row0 = u.pm * BM + wr * 64 + fr, col0 = u.pn * BM + wc * 32 + 8 * fq;
; #pragma unroll
;         for (int ai = 0; ai < 2; ++ai)
; #pragma unroll
;             for (int m = 0; m < 4; ++m) { bf16_t* rowp = O + (size_t)(row0 + ai * HALF + m * 16) * ldc + col0;
; #pragma unroll
;                 for (int bj = 0; bj < 2; ++bj) { const f32x4 v0 = acc[ai][bj][m][0], v1 = acc[ai][bj][m][1];
;                     u32x4 w; w.x = cvt_pk_bf16(v0[0], v0[1]); w.y = cvt_pk_bf16(v0[2], v0[3]); w.z = cvt_pk_bf16(v1[0], v1[1]); w.w = cvt_pk_bf16(v1[2], v1[3]);
;                     *(u32x4*)(rowp + bj * HALF) = w; } }
	v_lshl_add_u32 v136, s62, 8, v131
	v_lshl_or_b32 v128, s61, 8, v132
	v_ashrrev_i32_e32 v137, 31, v136
	v_ashrrev_i32_e32 v129, 31, v128
	v_lshlrev_b64 v[138:139], 12, v[136:137]
	v_lshl_add_u64 v[138:139], s[2:3], 0, v[138:139]
	v_lshlrev_b64 v[140:141], 1, v[128:129]
	v_lshl_add_u64 v[128:129], v[138:139], 0, v[140:141]
	v_cvt_pk_bf16_f32 v124, v124, v125
	v_cvt_pk_bf16_f32 v125, v126, v127
	v_cvt_pk_bf16_f32 v126, v120, v121
	v_cvt_pk_bf16_f32 v127, v122, v123
	global_store_dwordx4 v[128:129], v[124:127], off
	v_cvt_pk_bf16_f32 v112, v112, v113
	v_cvt_pk_bf16_f32 v113, v114, v115
	v_cvt_pk_bf16_f32 v114, v104, v105
	v_or_b32_e32 v104, 16, v136
	v_ashrrev_i32_e32 v105, 31, v104
	v_lshlrev_b64 v[104:105], 12, v[104:105]
	v_lshl_add_u64 v[104:105], s[2:3], 0, v[104:105]
	v_cvt_pk_bf16_f32 v115, v106, v107
	global_store_dwordx4 v[128:129], v[112:115], off offset:256
	s_mov_b64 s[0:1], 0x80000
	s_mov_b32 s61, s6
	v_lshl_add_u64 v[112:113], v[104:105], 0, v[140:141]
	v_cvt_pk_bf16_f32 v104, v116, v117
	v_cvt_pk_bf16_f32 v105, v118, v119
	v_cvt_pk_bf16_f32 v106, v108, v109
	v_cvt_pk_bf16_f32 v107, v110, v111
	global_store_dwordx4 v[112:113], v[104:107], off
	v_cvt_pk_bf16_f32 v96, v96, v97
	v_cvt_pk_bf16_f32 v97, v98, v99
	v_cvt_pk_bf16_f32 v98, v88, v89
	v_or_b32_e32 v88, 32, v136
	v_ashrrev_i32_e32 v89, 31, v88
	v_lshlrev_b64 v[88:89], 12, v[88:89]
	v_lshl_add_u64 v[88:89], s[2:3], 0, v[88:89]
	v_cvt_pk_bf16_f32 v99, v90, v91
	global_store_dwordx4 v[112:113], v[96:99], off offset:256
	s_mov_b32 s62, s8
	s_mov_b64 s[56:57], s[52:53]
	v_lshl_add_u64 v[96:97], v[88:89], 0, v[140:141]
	v_cvt_pk_bf16_f32 v88, v100, v101
	v_cvt_pk_bf16_f32 v89, v102, v103
	v_cvt_pk_bf16_f32 v90, v92, v93
	v_cvt_pk_bf16_f32 v91, v94, v95
	global_store_dwordx4 v[96:97], v[88:91], off
	v_cvt_pk_bf16_f32 v80, v80, v81
	v_cvt_pk_bf16_f32 v81, v82, v83
	v_cvt_pk_bf16_f32 v82, v72, v73
	v_or_b32_e32 v72, 48, v136
	v_ashrrev_i32_e32 v73, 31, v72
	v_lshlrev_b64 v[72:73], 12, v[72:73]
	v_lshl_add_u64 v[72:73], s[2:3], 0, v[72:73]
	v_cvt_pk_bf16_f32 v83, v74, v75
	global_store_dwordx4 v[96:97], v[80:83], off offset:256
	s_mov_b64 s[54:55], s[10:11]
	s_nop 0
	v_lshl_add_u64 v[80:81], v[72:73], 0, v[140:141]
	v_cvt_pk_bf16_f32 v72, v84, v85
	v_cvt_pk_bf16_f32 v73, v86, v87
	v_cvt_pk_bf16_f32 v74, v76, v77
	v_cvt_pk_bf16_f32 v75, v78, v79
	global_store_dwordx4 v[80:81], v[72:75], off
	v_cvt_pk_bf16_f32 v68, v68, v69
	v_cvt_pk_bf16_f32 v69, v70, v71
	v_cvt_pk_bf16_f32 v70, v64, v65
	v_cvt_pk_bf16_f32 v71, v66, v67
	global_store_dwordx4 v[80:81], v[68:71], off offset:256
	v_cvt_pk_bf16_f32 v60, v60, v61
	v_cvt_pk_bf16_f32 v61, v62, v63
	v_cvt_pk_bf16_f32 v62, v56, v57
	v_add_co_u32_e32 v56, vcc, s93, v128
	v_lshl_add_u64 v[64:65], v[128:129], 0, s[0:1]
	s_nop 0
	v_addc_co_u32_e32 v57, vcc, 0, v129, vcc
	v_cvt_pk_bf16_f32 v63, v58, v59
	global_store_dwordx4 v[56:57], v[60:63], off
	v_cvt_pk_bf16_f32 v48, v48, v49
	v_cvt_pk_bf16_f32 v49, v50, v51
	v_cvt_pk_bf16_f32 v50, v40, v41
	v_cvt_pk_bf16_f32 v51, v42, v43
	global_store_dwordx4 v[64:65], v[48:51], off offset:256
	s_mov_b64 s[0:1], 0x90000
	v_cvt_pk_bf16_f32 v40, v52, v53
	v_cvt_pk_bf16_f32 v41, v54, v55
	v_cvt_pk_bf16_f32 v42, v44, v45
	v_add_co_u32_e32 v44, vcc, s33, v128
	v_lshl_add_u64 v[48:49], v[128:129], 0, s[0:1]
	s_nop 0
	v_addc_co_u32_e32 v45, vcc, 0, v129, vcc
	v_cvt_pk_bf16_f32 v43, v46, v47
	global_store_dwordx4 v[44:45], v[40:43], off
	v_cvt_pk_bf16_f32 v32, v32, v33
	v_cvt_pk_bf16_f32 v33, v34, v35
	v_cvt_pk_bf16_f32 v34, v24, v25
	v_cvt_pk_bf16_f32 v35, v26, v27
	global_store_dwordx4 v[48:49], v[32:35], off offset:256
	s_mov_b64 s[0:1], 0xa0000
	v_cvt_pk_bf16_f32 v24, v36, v37
	v_cvt_pk_bf16_f32 v25, v38, v39
	v_cvt_pk_bf16_f32 v26, v28, v29
	v_add_co_u32_e32 v28, vcc, s18, v128
	v_lshl_add_u64 v[32:33], v[128:129], 0, s[0:1]
	s_nop 0
	v_addc_co_u32_e32 v29, vcc, 0, v129, vcc
	v_cvt_pk_bf16_f32 v27, v30, v31
	global_store_dwordx4 v[28:29], v[24:27], off
	v_cvt_pk_bf16_f32 v16, v16, v17
	v_cvt_pk_bf16_f32 v17, v18, v19
	v_cvt_pk_bf16_f32 v18, v8, v9
	v_cvt_pk_bf16_f32 v19, v10, v11
	global_store_dwordx4 v[32:33], v[16:19], off offset:256
	v_cvt_pk_bf16_f32 v8, v20, v21
	v_cvt_pk_bf16_f32 v9, v22, v23
	v_cvt_pk_bf16_f32 v10, v12, v13
	v_add_co_u32_e32 v12, vcc, s19, v128
	s_mov_b64 s[0:1], 0xb0000
	s_nop 0
	v_addc_co_u32_e32 v13, vcc, 0, v129, vcc
	v_lshl_add_u64 v[16:17], v[128:129], 0, s[0:1]
	s_and_b64 vcc, exec, s[4:5]
	v_cvt_pk_bf16_f32 v11, v14, v15
	global_store_dwordx4 v[12:13], v[8:11], off
	v_cvt_pk_bf16_f32 v4, v4, v5
	v_cvt_pk_bf16_f32 v5, v6, v7
	v_cvt_pk_bf16_f32 v6, v0, v1
	v_cvt_pk_bf16_f32 v7, v2, v3
	global_store_dwordx4 v[16:17], v[4:7], off offset:256
	s_cbranch_vccz .LBB0_427
	s_waitcnt vmcnt(0)
	s_cmpk_gt_u32 s16, 0xff
	v_readlane_b32 s38, v255, 44
	s_cbranch_scc1 .LBB0_438
	s_barrier

; #define PG8_STAGE(bufoff, gbase, hoff, imm) do { _Pragma("unroll") for (int _i = 0; _i < 2; ++_i) { \
;         asm volatile("s_mov_b32 m0, %0\n\ts_nop 0\n\tglobal_load_lds_dwordx4 %1, %2" \
;             :: "s"(lds0 + (unsigned)((bufoff) + _i * 8192)), "v"(voff0), "s"((const char*)(gbase) + (size_t)(hoff) + (size_t)(_i * 8192)) : "memory"); } } while (0)
; #define PG8_LDA(dst, b, h) do { _Pragma("unroll") for (int m = 0; m < 4; ++m) _Pragma("unroll") for (int k = 0; k < 2; ++k) dst[m][k] = *(const LAS bf16x8*)(lds + PG8_SA(b, h) + aoff + m * 2048 + k * 1024); } while (0)
; #define PG8_LDB(dst, b, h) do { _Pragma("unroll") for (int n = 0; n < 2; ++n) _Pragma("unroll") for (int k = 0; k < 2; ++k) dst[n][k] = *(const LAS bf16x8*)(lds + PG8_SB(b, h) + boff + n * 2048 + k * 1024); } while (0)
; #define PG8_MMA(ai, bj, At, Bt) do { __builtin_amdgcn_s_setprio(1); _Pragma("unroll") for (int m = 0; m < 4; ++m) _Pragma("unroll") for (int n = 0; n < 2; ++n) _Pragma("unroll") for (int k = 0; k < 2; ++k) \
;         acc[ai][bj][m][n] = __builtin_amdgcn_mfma_f32_16x16x32_bf16(Bt[n][k], At[m][k], acc[ai][bj][m][n], 0, 0, 0); __builtin_amdgcn_s_setprio(0); } while (0)
; #define PG8_WAIT_V(n) asm volatile("s_waitcnt vmcnt(" #n ")" ::: "memory")
; #define PG8_WAIT_L(n) asm volatile("s_waitcnt lgkmcnt(" #n ")" ::: "memory")
; #define PG8_BAR __builtin_amdgcn_s_barrier()
; #define PG8_SCHED __builtin_amdgcn_sched_barrier(0)
; template <class Epi>
; __device__ __forceinline__ void gemm_phase(LAS unsigned char* lds, const Gemm g, const StaticOrder& S, const Epi& E) {
;     ...
;             PG8_LDB(B0, 0, 0); PG8_SCHED; PG8_LDA(At, 0, 0); PG8_STAGE(PG8_SA(1, 1), aT + KS, hA, 0);
;             PG8_WAIT_L(8); PG8_BAR; PG8_WAIT_L(0); PG8_MMA(0, 0, At, B0); PG8_BAR; PG8_SCHED;
;             PG8_LDB(B1, 0, 1); PG8_STAGE(PG8_SB(0, 0), b2, 0, 0);
;             PG8_BAR; PG8_WAIT_L(0); PG8_MMA(0, 1, At, B1); PG8_BAR;
;             PG8_LDA(At, 0, 1); PG8_STAGE(PG8_SA(0, 0), a2, 0, 0);
;             PG8_BAR; PG8_WAIT_L(0); PG8_MMA(1, 0, At, B0); PG8_BAR; PG8_SCHED;
;             PG8_STAGE(PG8_SB(0, 1), b2, hB, 0);
;             PG8_WAIT_V(6); PG8_BAR; PG8_MMA(1, 1, At, B1); PG8_BAR;
.LBB0_506:
	v_add_u32_e32 v140, 0x10000, v202
	ds_read_b128 v[128:131], v140
	ds_read_b128 v[132:135], v140 offset:1024
	ds_read_b128 v[136:139], v140 offset:2048
	ds_read_b128 v[140:143], v140 offset:3072
	s_add_u32 s80, s78, 0x8000
	s_addc_u32 s81, s79, 0
	s_and_b64 s[82:83], s[84:85], exec
	s_cselect_b32 s83, s51, s81
	s_cselect_b32 s82, s71, s80
	ds_read_b128 v[144:147], v203
	ds_read_b128 v[148:151], v203 offset:1024
	ds_read_b128 v[152:155], v203 offset:2048
	ds_read_b128 v[156:159], v203 offset:3072
	ds_read_b128 v[160:163], v203 offset:4096
	ds_read_b128 v[164:167], v203 offset:5120
	ds_read_b128 v[204:207], v203 offset:6144
	ds_read_b128 v[208:211], v203 offset:7168
	s_add_u32 s48, s78, 0x84000
	s_addc_u32 s49, s79, 0
	s_mov_b32 m0, s87
	s_nop 0
	global_load_lds_dwordx4 v168, s[48:49]
	s_add_u32 s48, s78, 0x86000
	s_addc_u32 s49, s79, 0
	s_mov_b32 m0, s96
	s_nop 0
	global_load_lds_dwordx4 v168, s[48:49]
	s_waitcnt lgkmcnt(8)
	s_waitcnt vmcnt(10)
	s_barrier
	s_waitcnt lgkmcnt(7)
	v_mfma_f32_16x16x32_bf16 v[96:99], v[128:131], v[144:147], v[96:99]
	v_mfma_f32_16x16x32_bf16 v[44:47], v[136:139], v[144:147], v[44:47]
	s_waitcnt lgkmcnt(5)
	v_mfma_f32_16x16x32_bf16 v[92:95], v[128:131], v[152:155], v[92:95]
	v_mfma_f32_16x16x32_bf16 v[40:43], v[136:139], v[152:155], v[40:43]
	s_waitcnt lgkmcnt(3)
	v_mfma_f32_16x16x32_bf16 v[84:87], v[128:131], v[160:163], v[84:87]
	v_mfma_f32_16x16x32_bf16 v[36:39], v[136:139], v[160:163], v[36:39]
	s_waitcnt lgkmcnt(1)
	v_mfma_f32_16x16x32_bf16 v[124:127], v[128:131], v[204:207], v[124:127]
	v_mfma_f32_16x16x32_bf16 v[120:123], v[136:139], v[204:207], v[120:123]
	v_mfma_f32_16x16x32_bf16 v[96:99], v[132:135], v[148:151], v[96:99]
	v_mfma_f32_16x16x32_bf16 v[44:47], v[140:143], v[148:151], v[44:47]
	v_mfma_f32_16x16x32_bf16 v[92:95], v[132:135], v[156:159], v[92:95]
	v_mfma_f32_16x16x32_bf16 v[40:43], v[140:143], v[156:159], v[40:43]
	v_mfma_f32_16x16x32_bf16 v[84:87], v[132:135], v[164:167], v[84:87]
	v_mfma_f32_16x16x32_bf16 v[36:39], v[140:143], v[164:167], v[36:39]
	s_waitcnt lgkmcnt(0)
	v_mfma_f32_16x16x32_bf16 v[124:127], v[132:135], v[208:211], v[124:127]
	v_mfma_f32_16x16x32_bf16 v[120:123], v[140:143], v[208:211], v[120:123]
	s_barrier
	v_add_u32_e32 v188, 0x14000, v202
	ds_read_b128 v[212:215], v188
	ds_read_b128 v[236:239], v188 offset:1024
	ds_read_b128 v[240:243], v188 offset:2048
	ds_read_b128 v[244:247], v188 offset:3072
	s_and_b64 s[48:49], s[84:85], exec
	s_cselect_b32 s78, s62, s9
	s_cselect_b32 s79, s69, s63
	s_mov_b32 m0, s25
	s_nop 0
	global_load_lds_dwordx4 v168, s[78:79]
	s_add_u32 s48, s78, 0x2000
	s_addc_u32 s49, s79, 0
	s_mov_b32 m0, s26
	s_nop 0
	global_load_lds_dwordx4 v168, s[48:49]
	s_waitcnt vmcnt(10)
	s_barrier
	s_waitcnt lgkmcnt(3)
	v_mfma_f32_16x16x32_bf16 v[80:83], v[212:215], v[144:147], v[80:83]
	s_waitcnt lgkmcnt(1)
	v_mfma_f32_16x16x32_bf16 v[32:35], v[240:243], v[144:147], v[32:35]
	v_mfma_f32_16x16x32_bf16 v[76:79], v[212:215], v[152:155], v[76:79]
	v_mfma_f32_16x16x32_bf16 v[28:31], v[240:243], v[152:155], v[28:31]
	v_mfma_f32_16x16x32_bf16 v[72:75], v[212:215], v[160:163], v[72:75]
	v_mfma_f32_16x16x32_bf16 v[24:27], v[240:243], v[160:163], v[24:27]
	v_mfma_f32_16x16x32_bf16 v[116:119], v[212:215], v[204:207], v[116:119]
	v_mfma_f32_16x16x32_bf16 v[112:115], v[240:243], v[204:207], v[112:115]
	v_mfma_f32_16x16x32_bf16 v[80:83], v[236:239], v[148:151], v[80:83]
	s_waitcnt lgkmcnt(0)
	v_mfma_f32_16x16x32_bf16 v[32:35], v[244:247], v[148:151], v[32:35]
	v_mfma_f32_16x16x32_bf16 v[76:79], v[236:239], v[156:159], v[76:79]
	v_mfma_f32_16x16x32_bf16 v[28:31], v[244:247], v[156:159], v[28:31]
	v_mfma_f32_16x16x32_bf16 v[72:75], v[236:239], v[164:167], v[72:75]
	v_mfma_f32_16x16x32_bf16 v[24:27], v[244:247], v[164:167], v[24:27]
	v_mfma_f32_16x16x32_bf16 v[116:119], v[236:239], v[208:211], v[116:119]
	v_mfma_f32_16x16x32_bf16 v[112:115], v[244:247], v[208:211], v[112:115]
	s_barrier
	ds_read_b128 v[144:147], v203 offset:16384
	ds_read_b128 v[148:151], v203 offset:17408
	ds_read_b128 v[152:155], v203 offset:18432
	ds_read_b128 v[156:159], v203 offset:19456
	ds_read_b128 v[160:163], v203 offset:20480
	ds_read_b128 v[164:167], v203 offset:21504
	ds_read_b128 v[204:207], v203 offset:22528
	ds_read_b128 v[208:211], v203 offset:23552
	s_mov_b32 m0, s24
	s_nop 0
	global_load_lds_dwordx4 v168, s[82:83]
	s_add_u32 s48, s82, 0x2000
	s_addc_u32 s49, s83, 0
	s_mov_b32 m0, s27
	s_nop 0
	global_load_lds_dwordx4 v168, s[48:49]
	s_add_u32 s48, s78, 0x80000
	s_addc_u32 s49, s79, 0
	s_mov_b32 m0, s28
	s_nop 0
	global_load_lds_dwordx4 v168, s[48:49]
	s_add_u32 s48, s78, 0x82000
	s_addc_u32 s49, s79, 0
	s_mov_b32 m0, s29
	s_nop 0
	global_load_lds_dwordx4 v168, s[48:49]
	s_waitcnt vmcnt(10)
	s_barrier
; #define PG8_STAGE(bufoff, gbase, hoff, imm) do { _Pragma("unroll") for (int _i = 0; _i < 2; ++_i) { \
;         asm volatile("s_mov_b32 m0, %0\n\ts_nop 0\n\tglobal_load_lds_dwordx4 %1, %2" \
;             :: "s"(lds0 + (unsigned)((bufoff) + _i * 8192)), "v"(voff0), "s"((const char*)(gbase) + (size_t)(hoff) + (size_t)(_i * 8192)) : "memory"); } } while (0)
; #define PG8_LDA(dst, b, h) do { _Pragma("unroll") for (int m = 0; m < 4; ++m) _Pragma("unroll") for (int k = 0; k < 2; ++k) dst[m][k] = *(const LAS bf16x8*)(lds + PG8_SA(b, h) + aoff + m * 2048 + k * 1024); } while (0)
; #define PG8_LDB(dst, b, h) do { _Pragma("unroll") for (int n = 0; n < 2; ++n) _Pragma("unroll") for (int k = 0; k < 2; ++k) dst[n][k] = *(const LAS bf16x8*)(lds + PG8_SB(b, h) + boff + n * 2048 + k * 1024); } while (0)
; #define PG8_MMA(ai, bj, At, Bt) do { __builtin_amdgcn_s_setprio(1); _Pragma("unroll") for (int m = 0; m < 4; ++m) _Pragma("unroll") for (int n = 0; n < 2; ++n) _Pragma("unroll") for (int k = 0; k < 2; ++k) \
;         acc[ai][bj][m][n] = __builtin_amdgcn_mfma_f32_16x16x32_bf16(Bt[n][k], At[m][k], acc[ai][bj][m][n], 0, 0, 0); __builtin_amdgcn_s_setprio(0); } while (0)
; #define PG8_WAIT_V(n) asm volatile("s_waitcnt vmcnt(" #n ")" ::: "memory")
; #define PG8_WAIT_L(n) asm volatile("s_waitcnt lgkmcnt(" #n ")" ::: "memory")
; #define PG8_BAR __builtin_amdgcn_s_barrier()
; #define PG8_SCHED __builtin_amdgcn_sched_barrier(0)
; template <class Epi>
; __device__ __forceinline__ void gemm_phase(LAS unsigned char* lds, const Gemm g, const StaticOrder& S, const Epi& E) {
;     ...
;             PG8_BAR; PG8_WAIT_L(0); PG8_MMA(1, 0, At, B0); PG8_BAR; PG8_SCHED;
;             PG8_STAGE(PG8_SB(0, 1), b2, hB, 0);
;             PG8_WAIT_V(6); PG8_BAR; PG8_MMA(1, 1, At, B1); PG8_BAR;
;             PG8_LDB(B0, 1, 0); PG8_SCHED; PG8_LDA(At, 1, 0); PG8_STAGE(PG8_SA(0, 1), a2, hA, 0);
;             PG8_WAIT_L(8); PG8_BAR; PG8_WAIT_L(0); PG8_MMA(0, 0, At, B0); PG8_BAR; PG8_SCHED;
;             PG8_LDB(B1, 1, 1); PG8_STAGE(PG8_SB(1, 0), b2 + KS, 0, 0);
;             PG8_BAR; PG8_WAIT_L(0); PG8_MMA(0, 1, At, B1); PG8_BAR;
	s_waitcnt lgkmcnt(7)
	v_mfma_f32_16x16x32_bf16 v[68:71], v[128:131], v[144:147], v[68:71]
	v_mfma_f32_16x16x32_bf16 v[20:23], v[136:139], v[144:147], v[20:23]
	s_waitcnt lgkmcnt(5)
	v_mfma_f32_16x16x32_bf16 v[64:67], v[128:131], v[152:155], v[64:67]
	v_mfma_f32_16x16x32_bf16 v[16:19], v[136:139], v[152:155], v[16:19]
	s_waitcnt lgkmcnt(3)
	v_mfma_f32_16x16x32_bf16 v[60:63], v[128:131], v[160:163], v[60:63]
	v_mfma_f32_16x16x32_bf16 v[12:15], v[136:139], v[160:163], v[12:15]
	s_waitcnt lgkmcnt(1)
	v_mfma_f32_16x16x32_bf16 v[108:111], v[128:131], v[204:207], v[108:111]
	v_mfma_f32_16x16x32_bf16 v[104:107], v[136:139], v[204:207], v[104:107]
	v_mfma_f32_16x16x32_bf16 v[68:71], v[132:135], v[148:151], v[68:71]
	v_mfma_f32_16x16x32_bf16 v[20:23], v[140:143], v[148:151], v[20:23]
	v_mfma_f32_16x16x32_bf16 v[64:67], v[132:135], v[156:159], v[64:67]
	v_mfma_f32_16x16x32_bf16 v[16:19], v[140:143], v[156:159], v[16:19]
	v_mfma_f32_16x16x32_bf16 v[60:63], v[132:135], v[164:167], v[60:63]
	v_mfma_f32_16x16x32_bf16 v[12:15], v[140:143], v[164:167], v[12:15]
	s_waitcnt lgkmcnt(0)
	v_mfma_f32_16x16x32_bf16 v[108:111], v[132:135], v[208:211], v[108:111]
	v_mfma_f32_16x16x32_bf16 v[104:107], v[140:143], v[208:211], v[104:107]
	v_mfma_f32_16x16x32_bf16 v[56:59], v[212:215], v[144:147], v[56:59]
	v_mfma_f32_16x16x32_bf16 v[8:11], v[240:243], v[144:147], v[8:11]
	v_mfma_f32_16x16x32_bf16 v[52:55], v[212:215], v[152:155], v[52:55]
	v_mfma_f32_16x16x32_bf16 v[4:7], v[240:243], v[152:155], v[4:7]
	v_mfma_f32_16x16x32_bf16 v[48:51], v[212:215], v[160:163], v[48:51]
	v_mfma_f32_16x16x32_bf16 v[0:3], v[240:243], v[160:163], v[0:3]
	v_mfma_f32_16x16x32_bf16 v[100:103], v[212:215], v[204:207], v[100:103]
	v_mfma_f32_16x16x32_bf16 v[88:91], v[240:243], v[204:207], v[88:91]
	v_mfma_f32_16x16x32_bf16 v[56:59], v[236:239], v[148:151], v[56:59]
	v_mfma_f32_16x16x32_bf16 v[8:11], v[244:247], v[148:151], v[8:11]
	v_mfma_f32_16x16x32_bf16 v[52:55], v[236:239], v[156:159], v[52:55]
	v_mfma_f32_16x16x32_bf16 v[4:7], v[244:247], v[156:159], v[4:7]
	v_mfma_f32_16x16x32_bf16 v[48:51], v[236:239], v[164:167], v[48:51]
	v_mfma_f32_16x16x32_bf16 v[0:3], v[244:247], v[164:167], v[0:3]
	v_mfma_f32_16x16x32_bf16 v[100:103], v[236:239], v[208:211], v[100:103]
	v_mfma_f32_16x16x32_bf16 v[88:91], v[244:247], v[208:211], v[88:91]
	v_add_u32_e32 v140, 0x18000, v202
	s_barrier
	ds_read_b128 v[128:131], v140
	ds_read_b128 v[132:135], v140 offset:1024
	ds_read_b128 v[136:139], v140 offset:2048
	ds_read_b128 v[140:143], v140 offset:3072
	ds_read_b128 v[144:147], v203 offset:32768
	ds_read_b128 v[148:151], v203 offset:33792
	ds_read_b128 v[152:155], v203 offset:34816
	ds_read_b128 v[156:159], v203 offset:35840
	ds_read_b128 v[160:163], v203 offset:36864
	ds_read_b128 v[164:167], v203 offset:37888
	ds_read_b128 v[204:207], v203 offset:38912
	ds_read_b128 v[208:211], v203 offset:39936
	s_add_u32 s48, s82, 0x80000
	s_addc_u32 s49, s83, 0
	s_mov_b32 m0, s30
	s_nop 0
	global_load_lds_dwordx4 v168, s[48:49]
	s_add_u32 s48, s82, 0x82000
	s_addc_u32 s49, s83, 0
	s_mov_b32 m0, s34
	s_nop 0
	global_load_lds_dwordx4 v168, s[48:49]
	s_waitcnt lgkmcnt(8)
	s_waitcnt vmcnt(10)
	s_barrier
	s_waitcnt lgkmcnt(7)
	v_mfma_f32_16x16x32_bf16 v[96:99], v[128:131], v[144:147], v[96:99]
	v_mfma_f32_16x16x32_bf16 v[44:47], v[136:139], v[144:147], v[44:47]
	s_waitcnt lgkmcnt(5)
	v_mfma_f32_16x16x32_bf16 v[92:95], v[128:131], v[152:155], v[92:95]
	v_mfma_f32_16x16x32_bf16 v[40:43], v[136:139], v[152:155], v[40:43]
	s_waitcnt lgkmcnt(3)
	v_mfma_f32_16x16x32_bf16 v[84:87], v[128:131], v[160:163], v[84:87]
	v_mfma_f32_16x16x32_bf16 v[36:39], v[136:139], v[160:163], v[36:39]
	s_waitcnt lgkmcnt(1)
	v_mfma_f32_16x16x32_bf16 v[124:127], v[128:131], v[204:207], v[124:127]
	v_mfma_f32_16x16x32_bf16 v[120:123], v[136:139], v[204:207], v[120:123]
	v_mfma_f32_16x16x32_bf16 v[96:99], v[132:135], v[148:151], v[96:99]
	v_mfma_f32_16x16x32_bf16 v[44:47], v[140:143], v[148:151], v[44:47]
	v_mfma_f32_16x16x32_bf16 v[92:95], v[132:135], v[156:159], v[92:95]
	v_mfma_f32_16x16x32_bf16 v[40:43], v[140:143], v[156:159], v[40:43]
	v_mfma_f32_16x16x32_bf16 v[84:87], v[132:135], v[164:167], v[84:87]
	v_mfma_f32_16x16x32_bf16 v[36:39], v[140:143], v[164:167], v[36:39]
	s_waitcnt lgkmcnt(0)
	v_mfma_f32_16x16x32_bf16 v[124:127], v[132:135], v[208:211], v[124:127]
	v_mfma_f32_16x16x32_bf16 v[120:123], v[140:143], v[208:211], v[120:123]
	s_barrier
	v_add_u32_e32 v188, 0x1c000, v202
	ds_read_b128 v[212:215], v188
	ds_read_b128 v[236:239], v188 offset:1024
	ds_read_b128 v[240:243], v188 offset:2048
	ds_read_b128 v[244:247], v188 offset:3072
	s_add_u32 s48, s78, 0x4000
	s_addc_u32 s49, s79, 0
	s_mov_b32 m0, s38
	s_nop 0
	global_load_lds_dwordx4 v168, s[48:49]
	s_add_u32 s48, s78, 0x6000
	s_addc_u32 s49, s79, 0
	s_mov_b32 m0, s39
	s_nop 0
	global_load_lds_dwordx4 v168, s[48:49]
	s_waitcnt vmcnt(10)
	s_barrier
; #define PG8_STAGE(bufoff, gbase, hoff, imm) do { _Pragma("unroll") for (int _i = 0; _i < 2; ++_i) { \
;         asm volatile("s_mov_b32 m0, %0\n\ts_nop 0\n\tglobal_load_lds_dwordx4 %1, %2" \
;             :: "s"(lds0 + (unsigned)((bufoff) + _i * 8192)), "v"(voff0), "s"((const char*)(gbase) + (size_t)(hoff) + (size_t)(_i * 8192)) : "memory"); } } while (0)
; #define PG8_LDA(dst, b, h) do { _Pragma("unroll") for (int m = 0; m < 4; ++m) _Pragma("unroll") for (int k = 0; k < 2; ++k) dst[m][k] = *(const LAS bf16x8*)(lds + PG8_SA(b, h) + aoff + m * 2048 + k * 1024); } while (0)
; #define PG8_LDB(dst, b, h) do { _Pragma("unroll") for (int n = 0; n < 2; ++n) _Pragma("unroll") for (int k = 0; k < 2; ++k) dst[n][k] = *(const LAS bf16x8*)(lds + PG8_SB(b, h) + boff + n * 2048 + k * 1024); } while (0)
; #define PG8_MMA(ai, bj, At, Bt) do { __builtin_amdgcn_s_setprio(1); _Pragma("unroll") for (int m = 0; m < 4; ++m) _Pragma("unroll") for (int n = 0; n < 2; ++n) _Pragma("unroll") for (int k = 0; k < 2; ++k) \
;         acc[ai][bj][m][n] = __builtin_amdgcn_mfma_f32_16x16x32_bf16(Bt[n][k], At[m][k], acc[ai][bj][m][n], 0, 0, 0); __builtin_amdgcn_s_setprio(0); } while (0)
; #define PG8_WAIT_V(n) asm volatile("s_waitcnt vmcnt(" #n ")" ::: "memory")
; #define PG8_WAIT_L(n) asm volatile("s_waitcnt lgkmcnt(" #n ")" ::: "memory")
; #define PG8_BAR __builtin_amdgcn_s_barrier()
; #define PG8_SCHED __builtin_amdgcn_sched_barrier(0)
; template <class Epi>
; __device__ __forceinline__ void gemm_phase(LAS unsigned char* lds, const Gemm g, const StaticOrder& S, const Epi& E) {
;     ...
;             PG8_LDB(B0, 1, 0); PG8_SCHED; PG8_LDA(At, 1, 0); PG8_STAGE(PG8_SA(0, 1), a2, hA, 0);
;             PG8_WAIT_L(8); PG8_BAR; PG8_WAIT_L(0); PG8_MMA(0, 0, At, B0); PG8_BAR; PG8_SCHED;
;             PG8_LDB(B1, 1, 1); PG8_STAGE(PG8_SB(1, 0), b2 + KS, 0, 0);
;             PG8_BAR; PG8_WAIT_L(0); PG8_MMA(0, 1, At, B1); PG8_BAR;
;             PG8_LDA(At, 1, 1); PG8_STAGE(PG8_SA(1, 0), a2 + KS, 0, 0);
;             PG8_BAR; PG8_WAIT_L(0); PG8_MMA(1, 0, At, B0); PG8_BAR; PG8_SCHED;
;             PG8_STAGE(PG8_SB(1, 1), b2 + KS, hB, 0);
;             PG8_WAIT_V(6); PG8_BAR; PG8_MMA(1, 1, At, B1); PG8_BAR;
	s_waitcnt lgkmcnt(3)
	v_mfma_f32_16x16x32_bf16 v[80:83], v[212:215], v[144:147], v[80:83]
	s_waitcnt lgkmcnt(1)
	v_mfma_f32_16x16x32_bf16 v[32:35], v[240:243], v[144:147], v[32:35]
	v_mfma_f32_16x16x32_bf16 v[76:79], v[212:215], v[152:155], v[76:79]
	v_mfma_f32_16x16x32_bf16 v[28:31], v[240:243], v[152:155], v[28:31]
	v_mfma_f32_16x16x32_bf16 v[72:75], v[212:215], v[160:163], v[72:75]
	v_mfma_f32_16x16x32_bf16 v[24:27], v[240:243], v[160:163], v[24:27]
	v_mfma_f32_16x16x32_bf16 v[116:119], v[212:215], v[204:207], v[116:119]
	v_mfma_f32_16x16x32_bf16 v[112:115], v[240:243], v[204:207], v[112:115]
	v_mfma_f32_16x16x32_bf16 v[80:83], v[236:239], v[148:151], v[80:83]
	s_waitcnt lgkmcnt(0)
	v_mfma_f32_16x16x32_bf16 v[32:35], v[244:247], v[148:151], v[32:35]
	v_mfma_f32_16x16x32_bf16 v[76:79], v[236:239], v[156:159], v[76:79]
	v_mfma_f32_16x16x32_bf16 v[28:31], v[244:247], v[156:159], v[28:31]
	v_mfma_f32_16x16x32_bf16 v[72:75], v[236:239], v[164:167], v[72:75]
	v_mfma_f32_16x16x32_bf16 v[24:27], v[244:247], v[164:167], v[24:27]
	v_mfma_f32_16x16x32_bf16 v[116:119], v[236:239], v[208:211], v[116:119]
	v_mfma_f32_16x16x32_bf16 v[112:115], v[244:247], v[208:211], v[112:115]
	s_barrier
	ds_read_b128 v[144:147], v203 offset:49152
	ds_read_b128 v[148:151], v203 offset:50176
	ds_read_b128 v[152:155], v203 offset:51200
	ds_read_b128 v[156:159], v203 offset:52224
	ds_read_b128 v[160:163], v203 offset:53248
	ds_read_b128 v[164:167], v203 offset:54272
	ds_read_b128 v[204:207], v203 offset:55296
	ds_read_b128 v[208:211], v203 offset:56320
	s_add_u32 s48, s82, 0x4000
	s_addc_u32 s49, s83, 0
	s_mov_b32 m0, s40
	s_nop 0
	global_load_lds_dwordx4 v168, s[48:49]
	s_add_u32 s48, s82, 0x6000
	s_addc_u32 s49, s83, 0
	s_mov_b32 m0, s41
	s_nop 0
	global_load_lds_dwordx4 v168, s[48:49]
	s_add_u32 s48, s78, 0x84000
	s_addc_u32 s49, s79, 0
	s_mov_b32 m0, s42
	s_nop 0
	global_load_lds_dwordx4 v168, s[48:49]
	s_add_u32 s48, s78, 0x86000
	s_addc_u32 s49, s79, 0
	s_mov_b32 m0, s43
	s_nop 0
	global_load_lds_dwordx4 v168, s[48:49]
	s_waitcnt vmcnt(10)
	s_barrier
	s_waitcnt lgkmcnt(7)
	v_mfma_f32_16x16x32_bf16 v[68:71], v[128:131], v[144:147], v[68:71]
	v_mfma_f32_16x16x32_bf16 v[20:23], v[136:139], v[144:147], v[20:23]
	s_waitcnt lgkmcnt(5)
	v_mfma_f32_16x16x32_bf16 v[64:67], v[128:131], v[152:155], v[64:67]
	v_mfma_f32_16x16x32_bf16 v[16:19], v[136:139], v[152:155], v[16:19]
	s_waitcnt lgkmcnt(3)
	v_mfma_f32_16x16x32_bf16 v[60:63], v[128:131], v[160:163], v[60:63]
	v_mfma_f32_16x16x32_bf16 v[12:15], v[136:139], v[160:163], v[12:15]
	s_waitcnt lgkmcnt(1)
	v_mfma_f32_16x16x32_bf16 v[108:111], v[128:131], v[204:207], v[108:111]
	v_mfma_f32_16x16x32_bf16 v[104:107], v[136:139], v[204:207], v[104:107]
	v_mfma_f32_16x16x32_bf16 v[68:71], v[132:135], v[148:151], v[68:71]
	v_mfma_f32_16x16x32_bf16 v[20:23], v[140:143], v[148:151], v[20:23]
	v_mfma_f32_16x16x32_bf16 v[64:67], v[132:135], v[156:159], v[64:67]
	v_mfma_f32_16x16x32_bf16 v[16:19], v[140:143], v[156:159], v[16:19]
	v_mfma_f32_16x16x32_bf16 v[60:63], v[132:135], v[164:167], v[60:63]
	v_mfma_f32_16x16x32_bf16 v[12:15], v[140:143], v[164:167], v[12:15]
	s_waitcnt lgkmcnt(0)
	v_mfma_f32_16x16x32_bf16 v[108:111], v[132:135], v[208:211], v[108:111]
	v_mfma_f32_16x16x32_bf16 v[104:107], v[140:143], v[208:211], v[104:107]
	v_mfma_f32_16x16x32_bf16 v[56:59], v[212:215], v[144:147], v[56:59]
	v_mfma_f32_16x16x32_bf16 v[8:11], v[240:243], v[144:147], v[8:11]
	v_mfma_f32_16x16x32_bf16 v[52:55], v[212:215], v[152:155], v[52:55]
	v_mfma_f32_16x16x32_bf16 v[4:7], v[240:243], v[152:155], v[4:7]
	v_mfma_f32_16x16x32_bf16 v[48:51], v[212:215], v[160:163], v[48:51]
	v_mfma_f32_16x16x32_bf16 v[0:3], v[240:243], v[160:163], v[0:3]
	v_mfma_f32_16x16x32_bf16 v[100:103], v[212:215], v[204:207], v[100:103]
	v_mfma_f32_16x16x32_bf16 v[88:91], v[240:243], v[204:207], v[88:91]
	v_mfma_f32_16x16x32_bf16 v[56:59], v[236:239], v[148:151], v[56:59]
	v_mfma_f32_16x16x32_bf16 v[8:11], v[244:247], v[148:151], v[8:11]
	v_mfma_f32_16x16x32_bf16 v[52:55], v[236:239], v[156:159], v[52:55]
	v_mfma_f32_16x16x32_bf16 v[4:7], v[244:247], v[156:159], v[4:7]
	v_mfma_f32_16x16x32_bf16 v[48:51], v[236:239], v[164:167], v[48:51]
	v_mfma_f32_16x16x32_bf16 v[0:3], v[244:247], v[164:167], v[0:3]
	v_mfma_f32_16x16x32_bf16 v[100:103], v[236:239], v[208:211], v[100:103]
	v_mfma_f32_16x16x32_bf16 v[88:91], v[244:247], v[208:211], v[88:91]
	s_add_i32 s0, s0, 2
	s_add_u32 s9, s9, 0x8000
	s_addc_u32 s63, s63, 0
	s_cmp_gt_u32 s0, 29
	s_mov_b64 s[78:79], s[80:81]
	s_barrier
	s_cbranch_scc1 .LBB0_509

; #define PG8_STAGE(bufoff, gbase, hoff, imm) do { _Pragma("unroll") for (int _i = 0; _i < 2; ++_i) { \
;         asm volatile("s_mov_b32 m0, %0\n\ts_nop 0\n\tglobal_load_lds_dwordx4 %1, %2" \
;             :: "s"(lds0 + (unsigned)((bufoff) + _i * 8192)), "v"(voff0), "s"((const char*)(gbase) + (size_t)(hoff) + (size_t)(_i * 8192)) : "memory"); } } while (0)
; #define PG8_LDA(dst, b, h) do { _Pragma("unroll") for (int m = 0; m < 4; ++m) _Pragma("unroll") for (int k = 0; k < 2; ++k) dst[m][k] = *(const LAS bf16x8*)(lds + PG8_SA(b, h) + aoff + m * 2048 + k * 1024); } while (0)
; #define PG8_LDB(dst, b, h) do { _Pragma("unroll") for (int n = 0; n < 2; ++n) _Pragma("unroll") for (int k = 0; k < 2; ++k) dst[n][k] = *(const LAS bf16x8*)(lds + PG8_SB(b, h) + boff + n * 2048 + k * 1024); } while (0)
; #define PG8_MMA(ai, bj, At, Bt) do { __builtin_amdgcn_s_setprio(1); _Pragma("unroll") for (int m = 0; m < 4; ++m) _Pragma("unroll") for (int n = 0; n < 2; ++n) _Pragma("unroll") for (int k = 0; k < 2; ++k) \
;         acc[ai][bj][m][n] = __builtin_amdgcn_mfma_f32_16x16x32_bf16(Bt[n][k], At[m][k], acc[ai][bj][m][n], 0, 0, 0); __builtin_amdgcn_s_setprio(0); } while (0)
; #define PG8_WAIT_V(n) asm volatile("s_waitcnt vmcnt(" #n ")" ::: "memory")
; #define PG8_BAR __builtin_amdgcn_s_barrier()
; template <class Epi>
; __device__ __forceinline__ void gemm_phase(LAS unsigned char* lds, const Gemm g, const StaticOrder& S, const Epi& E) {
;     ...
;         for (int t = 0; t < nt; t += 2) {
;             const bool last = (t == nt - 2);
;             if (last) E.pre(cur, wid, lane, (unsigned)(size_t)(lds + STAGE_BYTES));
;             const char* aT = cA + (size_t)t * KS;
;             const char* a2 = last ? nA : aT + 2 * KS; const char* b2 = last ? nB : cB + (size_t)(t + 2) * KS;
;             PG8_LDB(B0, 0, 0); PG8_SCHED; PG8_LDA(At, 0, 0); PG8_STAGE(PG8_SA(1, 1), aT + KS, hA, 0);
;             PG8_WAIT_L(8); PG8_BAR; PG8_WAIT_L(0); PG8_MMA(0, 0, At, B0); PG8_BAR; PG8_SCHED;
;             PG8_LDB(B1, 0, 1); PG8_STAGE(PG8_SB(0, 0), b2, 0, 0);
;             PG8_BAR; PG8_WAIT_L(0); PG8_MMA(0, 1, At, B1); PG8_BAR;
;             PG8_LDA(At, 0, 1); PG8_STAGE(PG8_SA(0, 0), a2, 0, 0);
;             PG8_BAR; PG8_WAIT_L(0); PG8_MMA(1, 0, At, B0); PG8_BAR; PG8_SCHED;
;             PG8_STAGE(PG8_SB(0, 1), b2, hB, 0);
;             PG8_WAIT_V(6); PG8_BAR; PG8_MMA(1, 1, At, B1); PG8_BAR;
.LBB0_610:
	s_add_u32 s62, s60, 0x8000
	v_add_u32_e32 v132, 0x10000, v236
	s_addc_u32 s63, s61, 0
	ds_read_b128 v[120:123], v132
	ds_read_b128 v[124:127], v132 offset:1024
	ds_read_b128 v[128:131], v132 offset:2048
	ds_read_b128 v[132:135], v132 offset:3072
	s_add_u32 s48, s60, 0x84000
	s_addc_u32 s49, s61, 0
	s_add_u32 s64, s60, 0x86000
	s_addc_u32 s65, s61, 0
	s_cmp_eq_u32 s71, 28
	s_cselect_b32 s61, s0, s63
	s_cselect_b32 s60, s1, s62
	ds_read_b128 v[136:139], v237
	ds_read_b128 v[140:143], v237 offset:1024
	ds_read_b128 v[152:155], v237 offset:2048
	ds_read_b128 v[156:159], v237 offset:3072
	ds_read_b128 v[160:163], v237 offset:4096
	ds_read_b128 v[164:167], v237 offset:5120
	ds_read_b128 v[168:171], v237 offset:6144
	ds_read_b128 v[172:175], v237 offset:7168
	s_mov_b32 m0, s67
	s_nop 0
	global_load_lds_dwordx4 v188, s[48:49]
	s_mov_b32 m0, s68
	s_nop 0
	global_load_lds_dwordx4 v188, s[64:65]
	s_waitcnt lgkmcnt(8)
	s_waitcnt vmcnt(10)
	s_barrier
	s_waitcnt lgkmcnt(7)
	v_mfma_f32_16x16x32_bf16 v[148:151], v[120:123], v[136:139], v[148:151]
	v_mfma_f32_16x16x32_bf16 v[144:147], v[128:131], v[136:139], v[144:147]
	s_waitcnt lgkmcnt(5)
	v_mfma_f32_16x16x32_bf16 v[108:111], v[120:123], v[152:155], v[108:111]
	v_mfma_f32_16x16x32_bf16 v[104:107], v[128:131], v[152:155], v[104:107]
	s_waitcnt lgkmcnt(3)
	v_mfma_f32_16x16x32_bf16 v[92:95], v[120:123], v[160:163], v[92:95]
	v_mfma_f32_16x16x32_bf16 v[88:91], v[128:131], v[160:163], v[88:91]
	s_waitcnt lgkmcnt(1)
	v_mfma_f32_16x16x32_bf16 v[76:79], v[120:123], v[168:171], v[76:79]
	v_mfma_f32_16x16x32_bf16 v[72:75], v[128:131], v[168:171], v[72:75]
	v_mfma_f32_16x16x32_bf16 v[148:151], v[124:127], v[140:143], v[148:151]
	v_mfma_f32_16x16x32_bf16 v[144:147], v[132:135], v[140:143], v[144:147]
	v_mfma_f32_16x16x32_bf16 v[108:111], v[124:127], v[156:159], v[108:111]
	v_mfma_f32_16x16x32_bf16 v[104:107], v[132:135], v[156:159], v[104:107]
	v_mfma_f32_16x16x32_bf16 v[92:95], v[124:127], v[164:167], v[92:95]
	v_mfma_f32_16x16x32_bf16 v[88:91], v[132:135], v[164:167], v[88:91]
	s_waitcnt lgkmcnt(0)
	v_mfma_f32_16x16x32_bf16 v[76:79], v[124:127], v[172:175], v[76:79]
	v_mfma_f32_16x16x32_bf16 v[72:75], v[132:135], v[172:175], v[72:75]
	s_barrier
	v_add_u32_e32 v200, 0x14000, v236
	ds_read_b128 v[176:179], v200
	ds_read_b128 v[180:183], v200 offset:1024
	ds_read_b128 v[184:187], v200 offset:2048
	ds_read_b128 v[200:203], v200 offset:3072
	s_cselect_b32 s64, s55, s69
	s_cselect_b32 s65, s53, s70
	s_mov_b32 m0, s24
	s_nop 0
	global_load_lds_dwordx4 v188, s[64:65]
	s_add_u32 s48, s64, 0x2000
	s_addc_u32 s49, s65, 0
	s_mov_b32 m0, s25
	s_nop 0
	global_load_lds_dwordx4 v188, s[48:49]
	s_waitcnt vmcnt(10)
	s_barrier
	s_waitcnt lgkmcnt(3)
	v_mfma_f32_16x16x32_bf16 v[116:119], v[176:179], v[136:139], v[116:119]
	s_waitcnt lgkmcnt(1)
	v_mfma_f32_16x16x32_bf16 v[112:115], v[184:187], v[136:139], v[112:115]
	v_mfma_f32_16x16x32_bf16 v[100:103], v[176:179], v[152:155], v[100:103]
	v_mfma_f32_16x16x32_bf16 v[96:99], v[184:187], v[152:155], v[96:99]
	v_mfma_f32_16x16x32_bf16 v[84:87], v[176:179], v[160:163], v[84:87]
	v_mfma_f32_16x16x32_bf16 v[80:83], v[184:187], v[160:163], v[80:83]
	v_mfma_f32_16x16x32_bf16 v[68:71], v[176:179], v[168:171], v[68:71]
	v_mfma_f32_16x16x32_bf16 v[64:67], v[184:187], v[168:171], v[64:67]
	v_mfma_f32_16x16x32_bf16 v[116:119], v[180:183], v[140:143], v[116:119]
	s_waitcnt lgkmcnt(0)
	v_mfma_f32_16x16x32_bf16 v[112:115], v[200:203], v[140:143], v[112:115]
	v_mfma_f32_16x16x32_bf16 v[100:103], v[180:183], v[156:159], v[100:103]
	v_mfma_f32_16x16x32_bf16 v[96:99], v[200:203], v[156:159], v[96:99]
	v_mfma_f32_16x16x32_bf16 v[84:87], v[180:183], v[164:167], v[84:87]
	v_mfma_f32_16x16x32_bf16 v[80:83], v[200:203], v[164:167], v[80:83]
	v_mfma_f32_16x16x32_bf16 v[68:71], v[180:183], v[172:175], v[68:71]
	v_mfma_f32_16x16x32_bf16 v[64:67], v[200:203], v[172:175], v[64:67]
	s_barrier
	ds_read_b128 v[136:139], v237 offset:16384
	ds_read_b128 v[140:143], v237 offset:17408
	ds_read_b128 v[152:155], v237 offset:18432
	ds_read_b128 v[156:159], v237 offset:19456
	ds_read_b128 v[160:163], v237 offset:20480
	ds_read_b128 v[164:167], v237 offset:21504
	ds_read_b128 v[168:171], v237 offset:22528
	ds_read_b128 v[172:175], v237 offset:23552
	s_mov_b32 m0, s22
	s_nop 0
	global_load_lds_dwordx4 v188, s[60:61]
	s_add_u32 s48, s60, 0x2000
	s_addc_u32 s49, s61, 0
	s_mov_b32 m0, s26
	s_nop 0
	global_load_lds_dwordx4 v188, s[48:49]
	s_add_u32 s48, s64, 0x80000
	s_addc_u32 s49, s65, 0
	s_mov_b32 m0, s27
	s_nop 0
	global_load_lds_dwordx4 v188, s[48:49]
	s_add_u32 s48, s64, 0x82000
	s_addc_u32 s49, s65, 0
	s_mov_b32 m0, s28
	s_nop 0
	global_load_lds_dwordx4 v188, s[48:49]
	s_waitcnt vmcnt(10)
	s_barrier
; #define PG8_STAGE(bufoff, gbase, hoff, imm) do { _Pragma("unroll") for (int _i = 0; _i < 2; ++_i) { \
;         asm volatile("s_mov_b32 m0, %0\n\ts_nop 0\n\tglobal_load_lds_dwordx4 %1, %2" \
;             :: "s"(lds0 + (unsigned)((bufoff) + _i * 8192)), "v"(voff0), "s"((const char*)(gbase) + (size_t)(hoff) + (size_t)(_i * 8192)) : "memory"); } } while (0)
; #define PG8_LDA(dst, b, h) do { _Pragma("unroll") for (int m = 0; m < 4; ++m) _Pragma("unroll") for (int k = 0; k < 2; ++k) dst[m][k] = *(const LAS bf16x8*)(lds + PG8_SA(b, h) + aoff + m * 2048 + k * 1024); } while (0)
; #define PG8_LDB(dst, b, h) do { _Pragma("unroll") for (int n = 0; n < 2; ++n) _Pragma("unroll") for (int k = 0; k < 2; ++k) dst[n][k] = *(const LAS bf16x8*)(lds + PG8_SB(b, h) + boff + n * 2048 + k * 1024); } while (0)
; #define PG8_MMA(ai, bj, At, Bt) do { __builtin_amdgcn_s_setprio(1); _Pragma("unroll") for (int m = 0; m < 4; ++m) _Pragma("unroll") for (int n = 0; n < 2; ++n) _Pragma("unroll") for (int k = 0; k < 2; ++k) \
;         acc[ai][bj][m][n] = __builtin_amdgcn_mfma_f32_16x16x32_bf16(Bt[n][k], At[m][k], acc[ai][bj][m][n], 0, 0, 0); __builtin_amdgcn_s_setprio(0); } while (0)
; #define PG8_WAIT_V(n) asm volatile("s_waitcnt vmcnt(" #n ")" ::: "memory")
; #define PG8_WAIT_L(n) asm volatile("s_waitcnt lgkmcnt(" #n ")" ::: "memory")
; #define PG8_BAR __builtin_amdgcn_s_barrier()
; #define PG8_SCHED __builtin_amdgcn_sched_barrier(0)
; template <class Epi>
; __device__ __forceinline__ void gemm_phase(LAS unsigned char* lds, const Gemm g, const StaticOrder& S, const Epi& E) {
;     ...
;             PG8_WAIT_V(6); PG8_BAR; PG8_MMA(1, 1, At, B1); PG8_BAR;
;             PG8_LDB(B0, 1, 0); PG8_SCHED; PG8_LDA(At, 1, 0); PG8_STAGE(PG8_SA(0, 1), a2, hA, 0);
;             PG8_WAIT_L(8); PG8_BAR; PG8_WAIT_L(0); PG8_MMA(0, 0, At, B0); PG8_BAR; PG8_SCHED;
;             PG8_LDB(B1, 1, 1); PG8_STAGE(PG8_SB(1, 0), b2 + KS, 0, 0);
;             PG8_BAR; PG8_WAIT_L(0); PG8_MMA(0, 1, At, B1); PG8_BAR;
;             PG8_LDA(At, 1, 1); PG8_STAGE(PG8_SA(1, 0), a2 + KS, 0, 0);
;             PG8_BAR; PG8_WAIT_L(0); PG8_MMA(1, 0, At, B0); PG8_BAR; PG8_SCHED;
	s_waitcnt lgkmcnt(7)
	v_mfma_f32_16x16x32_bf16 v[60:63], v[120:123], v[136:139], v[60:63]
	v_mfma_f32_16x16x32_bf16 v[56:59], v[128:131], v[136:139], v[56:59]
	s_waitcnt lgkmcnt(5)
	v_mfma_f32_16x16x32_bf16 v[44:47], v[120:123], v[152:155], v[44:47]
	v_mfma_f32_16x16x32_bf16 v[40:43], v[128:131], v[152:155], v[40:43]
	s_waitcnt lgkmcnt(3)
	v_mfma_f32_16x16x32_bf16 v[28:31], v[120:123], v[160:163], v[28:31]
	v_mfma_f32_16x16x32_bf16 v[24:27], v[128:131], v[160:163], v[24:27]
	s_waitcnt lgkmcnt(1)
	v_mfma_f32_16x16x32_bf16 v[12:15], v[120:123], v[168:171], v[12:15]
	v_mfma_f32_16x16x32_bf16 v[8:11], v[128:131], v[168:171], v[8:11]
	v_mfma_f32_16x16x32_bf16 v[60:63], v[124:127], v[140:143], v[60:63]
	v_mfma_f32_16x16x32_bf16 v[56:59], v[132:135], v[140:143], v[56:59]
	v_mfma_f32_16x16x32_bf16 v[44:47], v[124:127], v[156:159], v[44:47]
	v_mfma_f32_16x16x32_bf16 v[40:43], v[132:135], v[156:159], v[40:43]
	v_mfma_f32_16x16x32_bf16 v[28:31], v[124:127], v[164:167], v[28:31]
	v_mfma_f32_16x16x32_bf16 v[24:27], v[132:135], v[164:167], v[24:27]
	s_waitcnt lgkmcnt(0)
	v_mfma_f32_16x16x32_bf16 v[12:15], v[124:127], v[172:175], v[12:15]
	v_mfma_f32_16x16x32_bf16 v[8:11], v[132:135], v[172:175], v[8:11]
	v_mfma_f32_16x16x32_bf16 v[52:55], v[176:179], v[136:139], v[52:55]
	v_mfma_f32_16x16x32_bf16 v[48:51], v[184:187], v[136:139], v[48:51]
	v_mfma_f32_16x16x32_bf16 v[36:39], v[176:179], v[152:155], v[36:39]
	v_mfma_f32_16x16x32_bf16 v[32:35], v[184:187], v[152:155], v[32:35]
	v_mfma_f32_16x16x32_bf16 v[20:23], v[176:179], v[160:163], v[20:23]
	v_mfma_f32_16x16x32_bf16 v[16:19], v[184:187], v[160:163], v[16:19]
	v_mfma_f32_16x16x32_bf16 v[4:7], v[176:179], v[168:171], v[4:7]
	v_mfma_f32_16x16x32_bf16 v[0:3], v[184:187], v[168:171], v[0:3]
	v_mfma_f32_16x16x32_bf16 v[52:55], v[180:183], v[140:143], v[52:55]
	v_mfma_f32_16x16x32_bf16 v[48:51], v[200:203], v[140:143], v[48:51]
	v_mfma_f32_16x16x32_bf16 v[36:39], v[180:183], v[156:159], v[36:39]
	v_mfma_f32_16x16x32_bf16 v[32:35], v[200:203], v[156:159], v[32:35]
	v_mfma_f32_16x16x32_bf16 v[20:23], v[180:183], v[164:167], v[20:23]
	v_mfma_f32_16x16x32_bf16 v[16:19], v[200:203], v[164:167], v[16:19]
	v_mfma_f32_16x16x32_bf16 v[4:7], v[180:183], v[172:175], v[4:7]
	v_mfma_f32_16x16x32_bf16 v[0:3], v[200:203], v[172:175], v[0:3]
	v_add_u32_e32 v132, 0x18000, v236
	s_barrier
	ds_read_b128 v[120:123], v132
	ds_read_b128 v[124:127], v132 offset:1024
	ds_read_b128 v[128:131], v132 offset:2048
	ds_read_b128 v[132:135], v132 offset:3072
	ds_read_b128 v[136:139], v237 offset:32768
	ds_read_b128 v[140:143], v237 offset:33792
	ds_read_b128 v[152:155], v237 offset:34816
	ds_read_b128 v[156:159], v237 offset:35840
	ds_read_b128 v[160:163], v237 offset:36864
	ds_read_b128 v[164:167], v237 offset:37888
	ds_read_b128 v[168:171], v237 offset:38912
	ds_read_b128 v[172:175], v237 offset:39936
	s_add_u32 s48, s60, 0x80000
	s_addc_u32 s49, s61, 0
	s_mov_b32 m0, s29
	s_nop 0
	global_load_lds_dwordx4 v188, s[48:49]
	s_add_u32 s48, s60, 0x82000
	s_addc_u32 s49, s61, 0
	s_mov_b32 m0, s30
	s_nop 0
	global_load_lds_dwordx4 v188, s[48:49]
	s_waitcnt lgkmcnt(8)
	s_waitcnt vmcnt(10)
	s_barrier
	s_waitcnt lgkmcnt(7)
	v_mfma_f32_16x16x32_bf16 v[148:151], v[120:123], v[136:139], v[148:151]
	v_mfma_f32_16x16x32_bf16 v[144:147], v[128:131], v[136:139], v[144:147]
	s_waitcnt lgkmcnt(5)
	v_mfma_f32_16x16x32_bf16 v[108:111], v[120:123], v[152:155], v[108:111]
	v_mfma_f32_16x16x32_bf16 v[104:107], v[128:131], v[152:155], v[104:107]
	s_waitcnt lgkmcnt(3)
	v_mfma_f32_16x16x32_bf16 v[92:95], v[120:123], v[160:163], v[92:95]
	v_mfma_f32_16x16x32_bf16 v[88:91], v[128:131], v[160:163], v[88:91]
	s_waitcnt lgkmcnt(1)
	v_mfma_f32_16x16x32_bf16 v[76:79], v[120:123], v[168:171], v[76:79]
	v_mfma_f32_16x16x32_bf16 v[72:75], v[128:131], v[168:171], v[72:75]
	v_mfma_f32_16x16x32_bf16 v[148:151], v[124:127], v[140:143], v[148:151]
	v_mfma_f32_16x16x32_bf16 v[144:147], v[132:135], v[140:143], v[144:147]
	v_mfma_f32_16x16x32_bf16 v[108:111], v[124:127], v[156:159], v[108:111]
	v_mfma_f32_16x16x32_bf16 v[104:107], v[132:135], v[156:159], v[104:107]
	v_mfma_f32_16x16x32_bf16 v[92:95], v[124:127], v[164:167], v[92:95]
	v_mfma_f32_16x16x32_bf16 v[88:91], v[132:135], v[164:167], v[88:91]
	s_waitcnt lgkmcnt(0)
	v_mfma_f32_16x16x32_bf16 v[76:79], v[124:127], v[172:175], v[76:79]
	v_mfma_f32_16x16x32_bf16 v[72:75], v[132:135], v[172:175], v[72:75]
	s_barrier
	v_add_u32_e32 v200, 0x1c000, v236
	ds_read_b128 v[176:179], v200
	ds_read_b128 v[180:183], v200 offset:1024
	ds_read_b128 v[184:187], v200 offset:2048
	ds_read_b128 v[200:203], v200 offset:3072
	s_add_u32 s48, s64, 0x4000
	s_addc_u32 s49, s65, 0
	s_mov_b32 m0, s39
	s_nop 0
	global_load_lds_dwordx4 v188, s[48:49]
	s_add_u32 s48, s64, 0x6000
	s_addc_u32 s49, s65, 0
	s_mov_b32 m0, s40
	s_nop 0
	global_load_lds_dwordx4 v188, s[48:49]
	s_waitcnt vmcnt(10)
	s_barrier
	s_waitcnt lgkmcnt(3)
	v_mfma_f32_16x16x32_bf16 v[116:119], v[176:179], v[136:139], v[116:119]
	s_waitcnt lgkmcnt(1)
	v_mfma_f32_16x16x32_bf16 v[112:115], v[184:187], v[136:139], v[112:115]
	v_mfma_f32_16x16x32_bf16 v[100:103], v[176:179], v[152:155], v[100:103]
	v_mfma_f32_16x16x32_bf16 v[96:99], v[184:187], v[152:155], v[96:99]
	v_mfma_f32_16x16x32_bf16 v[84:87], v[176:179], v[160:163], v[84:87]
	v_mfma_f32_16x16x32_bf16 v[80:83], v[184:187], v[160:163], v[80:83]
	v_mfma_f32_16x16x32_bf16 v[68:71], v[176:179], v[168:171], v[68:71]
	v_mfma_f32_16x16x32_bf16 v[64:67], v[184:187], v[168:171], v[64:67]
	v_mfma_f32_16x16x32_bf16 v[116:119], v[180:183], v[140:143], v[116:119]
	s_waitcnt lgkmcnt(0)
	v_mfma_f32_16x16x32_bf16 v[112:115], v[200:203], v[140:143], v[112:115]
	v_mfma_f32_16x16x32_bf16 v[100:103], v[180:183], v[156:159], v[100:103]
	v_mfma_f32_16x16x32_bf16 v[96:99], v[200:203], v[156:159], v[96:99]
	v_mfma_f32_16x16x32_bf16 v[84:87], v[180:183], v[164:167], v[84:87]
	v_mfma_f32_16x16x32_bf16 v[80:83], v[200:203], v[164:167], v[80:83]
	v_mfma_f32_16x16x32_bf16 v[68:71], v[180:183], v[172:175], v[68:71]
	v_mfma_f32_16x16x32_bf16 v[64:67], v[200:203], v[172:175], v[64:67]
	s_barrier
; #define PG8_STAGE(bufoff, gbase, hoff, imm) do { _Pragma("unroll") for (int _i = 0; _i < 2; ++_i) { \
;         asm volatile("s_mov_b32 m0, %0\n\ts_nop 0\n\tglobal_load_lds_dwordx4 %1, %2" \
;             :: "s"(lds0 + (unsigned)((bufoff) + _i * 8192)), "v"(voff0), "s"((const char*)(gbase) + (size_t)(hoff) + (size_t)(_i * 8192)) : "memory"); } } while (0)
; #define PG8_LDA(dst, b, h) do { _Pragma("unroll") for (int m = 0; m < 4; ++m) _Pragma("unroll") for (int k = 0; k < 2; ++k) dst[m][k] = *(const LAS bf16x8*)(lds + PG8_SA(b, h) + aoff + m * 2048 + k * 1024); } while (0)
; #define PG8_LDB(dst, b, h) do { _Pragma("unroll") for (int n = 0; n < 2; ++n) _Pragma("unroll") for (int k = 0; k < 2; ++k) dst[n][k] = *(const LAS bf16x8*)(lds + PG8_SB(b, h) + boff + n * 2048 + k * 1024); } while (0)
; #define PG8_WAIT_V(n) asm volatile("s_waitcnt vmcnt(" #n ")" ::: "memory")
; #define PG8_WAIT_L(n) asm volatile("s_waitcnt lgkmcnt(" #n ")" ::: "memory")
; #define PG8_BAR __builtin_amdgcn_s_barrier()
; #define PG8_SCHED __builtin_amdgcn_sched_barrier(0)
; template <class Epi>
; __device__ __forceinline__ void gemm_phase(LAS unsigned char* lds, const Gemm g, const StaticOrder& S, const Epi& E) {
;     ...
;             PG8_LDB(B1, 1, 1); PG8_STAGE(PG8_SB(1, 0), b2 + KS, 0, 0);
;             PG8_BAR; PG8_WAIT_L(0); PG8_MMA(0, 1, At, B1); PG8_BAR;
;             PG8_LDA(At, 1, 1); PG8_STAGE(PG8_SA(1, 0), a2 + KS, 0, 0);
;             PG8_BAR; PG8_WAIT_L(0); PG8_MMA(1, 0, At, B0); PG8_BAR; PG8_SCHED;
;             PG8_STAGE(PG8_SB(1, 1), b2 + KS, hB, 0);
;             PG8_WAIT_V(6); PG8_BAR; PG8_MMA(1, 1, At, B1); PG8_BAR;
;         }
;         E(acc, cur, wr, wc, fr, fq, lds + STAGE_BYTES);
;     __device__ __forceinline__ void operator()(f32x4 (&acc)[2][2][4][2], const Unit& u, int wr, int wc, int fr, int fq, LAS unsigned char*) const {
;         const int b = u.pm >> 6;
;         const int col0 = u.pn * BM + wc * 32 + 8 * fq;
;         const size_t off0 = (size_t)(u.pm * BM + wr * 64 + fr) * D + col0;
;         f32x4 sc[2][2];
; #pragma unroll
;         for (int bj = 0; bj < 2; ++bj)
; #pragma unroll
;             for (int n = 0; n < 2; ++n) { f32x4 gt = *(const f32x4*)(gate + (size_t)b * MODW + col0 + bj * HALF + n * 4); sc[bj][n] = gt + 1.0f;
;                 if (cs) sc[bj][n] *= *(const f32x4*)(cs + col0 + bj * HALF + n * 4); }
	ds_read_b128 v[136:139], v237 offset:49152
	ds_read_b128 v[140:143], v237 offset:50176
	ds_read_b128 v[152:155], v237 offset:51200
	ds_read_b128 v[156:159], v237 offset:52224
	ds_read_b128 v[160:163], v237 offset:53248
	ds_read_b128 v[164:167], v237 offset:54272
	ds_read_b128 v[168:171], v237 offset:55296
	ds_read_b128 v[172:175], v237 offset:56320
	s_add_u32 s48, s60, 0x4000
	s_addc_u32 s49, s61, 0
	s_mov_b32 m0, s41
	s_nop 0
	global_load_lds_dwordx4 v188, s[48:49]
	s_add_u32 s48, s60, 0x6000
	s_addc_u32 s49, s61, 0
	s_mov_b32 m0, s42
	s_nop 0
	global_load_lds_dwordx4 v188, s[48:49]
	s_add_u32 s48, s64, 0x84000
	s_addc_u32 s49, s65, 0
	s_mov_b32 m0, s43
	s_nop 0
	global_load_lds_dwordx4 v188, s[48:49]
	s_add_u32 s48, s64, 0x86000
	s_addc_u32 s49, s65, 0
	s_mov_b32 m0, s66
	s_nop 0
	global_load_lds_dwordx4 v188, s[48:49]
	s_waitcnt vmcnt(10)
	s_barrier
	s_waitcnt lgkmcnt(7)
	v_mfma_f32_16x16x32_bf16 v[60:63], v[120:123], v[136:139], v[60:63]
	v_mfma_f32_16x16x32_bf16 v[56:59], v[128:131], v[136:139], v[56:59]
	s_waitcnt lgkmcnt(5)
	v_mfma_f32_16x16x32_bf16 v[44:47], v[120:123], v[152:155], v[44:47]
	v_mfma_f32_16x16x32_bf16 v[40:43], v[128:131], v[152:155], v[40:43]
	s_waitcnt lgkmcnt(3)
	v_mfma_f32_16x16x32_bf16 v[28:31], v[120:123], v[160:163], v[28:31]
	v_mfma_f32_16x16x32_bf16 v[24:27], v[128:131], v[160:163], v[24:27]
	s_waitcnt lgkmcnt(1)
	v_mfma_f32_16x16x32_bf16 v[12:15], v[120:123], v[168:171], v[12:15]
	v_mfma_f32_16x16x32_bf16 v[8:11], v[128:131], v[168:171], v[8:11]
	v_mfma_f32_16x16x32_bf16 v[60:63], v[124:127], v[140:143], v[60:63]
	v_mfma_f32_16x16x32_bf16 v[56:59], v[132:135], v[140:143], v[56:59]
	v_mfma_f32_16x16x32_bf16 v[44:47], v[124:127], v[156:159], v[44:47]
	v_mfma_f32_16x16x32_bf16 v[40:43], v[132:135], v[156:159], v[40:43]
	v_mfma_f32_16x16x32_bf16 v[28:31], v[124:127], v[164:167], v[28:31]
	v_mfma_f32_16x16x32_bf16 v[24:27], v[132:135], v[164:167], v[24:27]
	s_waitcnt lgkmcnt(0)
	v_mfma_f32_16x16x32_bf16 v[12:15], v[124:127], v[172:175], v[12:15]
	v_mfma_f32_16x16x32_bf16 v[8:11], v[132:135], v[172:175], v[8:11]
	v_mfma_f32_16x16x32_bf16 v[52:55], v[176:179], v[136:139], v[52:55]
	v_mfma_f32_16x16x32_bf16 v[48:51], v[184:187], v[136:139], v[48:51]
	v_mfma_f32_16x16x32_bf16 v[36:39], v[176:179], v[152:155], v[36:39]
	v_mfma_f32_16x16x32_bf16 v[32:35], v[184:187], v[152:155], v[32:35]
	v_mfma_f32_16x16x32_bf16 v[20:23], v[176:179], v[160:163], v[20:23]
	v_mfma_f32_16x16x32_bf16 v[16:19], v[184:187], v[160:163], v[16:19]
	v_mfma_f32_16x16x32_bf16 v[4:7], v[176:179], v[168:171], v[4:7]
	v_mfma_f32_16x16x32_bf16 v[0:3], v[184:187], v[168:171], v[0:3]
	v_mfma_f32_16x16x32_bf16 v[52:55], v[180:183], v[140:143], v[52:55]
	v_mfma_f32_16x16x32_bf16 v[48:51], v[200:203], v[140:143], v[48:51]
	v_mfma_f32_16x16x32_bf16 v[36:39], v[180:183], v[156:159], v[36:39]
	v_mfma_f32_16x16x32_bf16 v[32:35], v[200:203], v[156:159], v[32:35]
	v_mfma_f32_16x16x32_bf16 v[20:23], v[180:183], v[164:167], v[20:23]
	v_mfma_f32_16x16x32_bf16 v[16:19], v[200:203], v[164:167], v[16:19]
	v_mfma_f32_16x16x32_bf16 v[4:7], v[180:183], v[172:175], v[4:7]
	v_mfma_f32_16x16x32_bf16 v[0:3], v[200:203], v[172:175], v[0:3]
	s_add_i32 s71, s71, 2
	s_add_u32 s69, s69, 0x8000
	s_addc_u32 s70, s70, 0
	s_cmp_gt_u32 s71, 29
	s_mov_b64 s[60:61], s[62:63]
	s_barrier
	s_cbranch_scc0 .LBB0_610
	s_ashr_i32 s0, s50, 6
	s_mul_hi_i32 s1, s0, 0xc000
	s_mul_i32 s0, s0, 0xc000
	v_lshl_or_b32 v128, s51, 8, v234
	s_add_u32 s0, s37, s0
	v_ashrrev_i32_e32 v129, 31, v128
	s_addc_u32 s1, s38, s1
	v_lshl_add_u64 v[130:131], v[128:129], 2, s[0:1]
	global_load_dwordx4 v[120:123], v[130:131], off offset:16
	global_load_dwordx4 v[124:127], v[130:131], off
	s_mov_b32 s51, s52
	s_mov_b64 s[62:63], s[58:59]
	s_mov_b64 s[60:61], s[56:57]
	s_waitcnt vmcnt(1)
	v_pk_add_f32 v[210:211], v[122:123], 1.0 op_sel_hi:[1,0]
	s_waitcnt vmcnt(0)
	v_pk_add_f32 v[214:215], v[126:127], 1.0 op_sel_hi:[1,0]
	v_pk_add_f32 v[212:213], v[124:125], 1.0 op_sel_hi:[1,0]
	v_pk_add_f32 v[208:209], v[120:121], 1.0 op_sel_hi:[1,0]
	global_load_dwordx4 v[120:123], v[130:131], off offset:528
	global_load_dwordx4 v[124:127], v[130:131], off offset:512
	s_waitcnt vmcnt(1)
	v_pk_add_f32 v[200:201], v[120:121], 1.0 op_sel_hi:[1,0]
	v_lshl_add_u32 v120, s50, 8, v233
	v_ashrrev_i32_e32 v121, 31, v120
	v_lshlrev_b64 v[120:121], 11, v[120:121]
	v_lshl_add_u64 v[120:121], v[120:121], 0, v[128:129]
	v_lshlrev_b64 v[216:217], 1, v[120:121]
	v_lshl_add_u64 v[120:121], s[8:9], 0, v[216:217]
	global_load_dwordx4 v[238:241], v[120:121], off
	global_load_dwordx4 v[184:187], v[120:121], off offset:256
	v_pk_add_f32 v[202:203], v[122:123], 1.0 op_sel_hi:[1,0]
	v_add_co_u32_e32 v122, vcc, s45, v120
	s_waitcnt vmcnt(2)
	v_pk_add_f32 v[206:207], v[126:127], 1.0 op_sel_hi:[1,0]
	v_addc_co_u32_e32 v123, vcc, 0, v121, vcc
	global_load_dwordx4 v[180:183], v[122:123], off
	global_load_dwordx4 v[176:179], v[122:123], off offset:256
	v_add_co_u32_e32 v122, vcc, s36, v120
	v_pk_add_f32 v[204:205], v[124:125], 1.0 op_sel_hi:[1,0]
	s_nop 0
	v_addc_co_u32_e32 v123, vcc, 0, v121, vcc
	global_load_dwordx4 v[172:175], v[122:123], off
	global_load_dwordx4 v[168:171], v[122:123], off offset:256
	v_add_co_u32_e32 v122, vcc, s23, v120
	s_mov_b32 s50, s54
	s_nop 0
	v_addc_co_u32_e32 v123, vcc, 0, v121, vcc
	global_load_dwordx4 v[164:167], v[122:123], off
	global_load_dwordx4 v[160:163], v[122:123], off offset:256
	v_add_co_u32_e32 v122, vcc, s93, v120
	s_waitcnt vmcnt(7)
; __device__ __forceinline__ unsigned cvt_pk_bf16(float lo, float hi) { unsigned r; asm volatile("v_cvt_pk_bf16_f32 %0, %1, %2" : "=v"(r) : "v"(lo), "v"(hi)); return r; }
;     __device__ __forceinline__ void operator()(f32x4 (&acc)[2][2][4][2], const Unit& u, int wr, int wc, int fr, int fq, LAS unsigned char*) const {
;     ...
;             u32x4 xb[2][4][2];
; #pragma unroll
;             for (int ai = 0; ai < 2; ++ai)
; #pragma unroll
;                 for (int m = 0; m < 4; ++m)
; #pragma unroll
;                     for (int bj = 0; bj < 2; ++bj) xb[ai][m][bj] = *(const u32x4*)((const bf16_t*)in + off0 + (size_t)(ai * HALF + m * 16) * D + bj * HALF);
; #pragma unroll
;             for (int ai = 0; ai < 2; ++ai)
; #pragma unroll
;                 for (int m = 0; m < 4; ++m)
; #pragma unroll
;                     for (int bj = 0; bj < 2; ++bj) { const u32x4 x = xb[ai][m][bj];
;                         f32x4 r0 = (f32x4){__uint_as_float(x.x << 16), __uint_as_float(x.x & 0xffff0000u), __uint_as_float(x.y << 16), __uint_as_float(x.y & 0xffff0000u)};
;                         f32x4 r1 = (f32x4){__uint_as_float(x.z << 16), __uint_as_float(x.z & 0xffff0000u), __uint_as_float(x.w << 16), __uint_as_float(x.w & 0xffff0000u)};
;                         r0 += sc[bj][0] * acc[ai][bj][m][0]; r1 += sc[bj][1] * acc[ai][bj][m][1];
;                         u32x4 w; w.x = cvt_pk_bf16(r0[0], r0[1]); w.y = cvt_pk_bf16(r0[2], r0[3]); w.z = cvt_pk_bf16(r1[0], r1[1]); w.w = cvt_pk_bf16(r1[2], r1[3]);
;                         *(u32x4*)(out + off0 + (size_t)(ai * HALF + m * 16) * D + bj * HALF) = w; }
	v_lshlrev_b32_e32 v230, 16, v238
	v_addc_co_u32_e32 v123, vcc, 0, v121, vcc
	global_load_dwordx4 v[156:159], v[122:123], off
	global_load_dwordx4 v[152:155], v[122:123], off offset:256
	v_add_co_u32_e32 v122, vcc, s33, v120
	v_and_b32_e32 v231, 0xffff0000, v238
	s_nop 0
	v_addc_co_u32_e32 v123, vcc, 0, v121, vcc
	global_load_dwordx4 v[140:143], v[122:123], off
	global_load_dwordx4 v[136:139], v[122:123], off offset:256
	v_add_co_u32_e32 v122, vcc, s18, v120
	v_lshlrev_b32_e32 v242, 16, v240
	s_nop 0
	v_addc_co_u32_e32 v123, vcc, 0, v121, vcc
	global_load_dwordx4 v[132:135], v[122:123], off
	global_load_dwordx4 v[128:131], v[122:123], off offset:256
	v_add_co_u32_e32 v120, vcc, s19, v120
	v_and_b32_e32 v243, 0xffff0000, v240
	s_nop 0
	v_addc_co_u32_e32 v121, vcc, 0, v121, vcc
	global_load_dwordx4 v[124:127], v[120:121], off
	s_nop 0
	global_load_dwordx4 v[120:123], v[120:121], off offset:256
	v_lshlrev_b32_e32 v238, 16, v239
	v_and_b32_e32 v239, 0xffff0000, v239
	v_lshlrev_b32_e32 v240, 16, v241
	v_and_b32_e32 v241, 0xffff0000, v241
	v_pk_fma_f32 v[148:149], v[148:149], v[212:213], v[230:231]
	v_pk_fma_f32 v[144:145], v[144:145], v[208:209], v[242:243]
	v_pk_fma_f32 v[150:151], v[150:151], v[214:215], v[238:239]
	v_pk_fma_f32 v[230:231], v[146:147], v[210:211], v[240:241]
	v_cvt_pk_bf16_f32 v146, v148, v149
	v_cvt_pk_bf16_f32 v147, v150, v151
	v_cvt_pk_bf16_f32 v148, v144, v145
	v_lshl_add_u64 v[144:145], s[10:11], 0, v[216:217]
	v_cvt_pk_bf16_f32 v149, v230, v231
	global_store_dwordx4 v[144:145], v[146:149], off
	s_waitcnt vmcnt(15)
	v_lshlrev_b32_e32 v150, 16, v186
	v_and_b32_e32 v151, 0xffff0000, v186
	v_lshlrev_b32_e32 v146, 16, v184
	v_and_b32_e32 v147, 0xffff0000, v184
	v_lshlrev_b32_e32 v148, 16, v185
	v_and_b32_e32 v149, 0xffff0000, v185
	v_lshlrev_b32_e32 v184, 16, v187
	v_and_b32_e32 v185, 0xffff0000, v187
	v_pk_fma_f32 v[118:119], v[118:119], v[206:207], v[148:149]
	v_pk_fma_f32 v[116:117], v[116:117], v[204:205], v[146:147]
	v_pk_fma_f32 v[146:147], v[114:115], v[202:203], v[184:185]
	v_pk_fma_f32 v[114:115], v[112:113], v[200:201], v[150:151]
	v_cvt_pk_bf16_f32 v112, v116, v117
	v_cvt_pk_bf16_f32 v113, v118, v119
	s_waitcnt vmcnt(14)
	v_lshlrev_b32_e32 v116, 16, v182
	v_cvt_pk_bf16_f32 v114, v114, v115
	v_cvt_pk_bf16_f32 v115, v146, v147
	global_store_dwordx4 v[144:145], v[112:115], off offset:256
	v_and_b32_e32 v117, 0xffff0000, v182
	v_lshlrev_b32_e32 v118, 16, v183
	v_lshlrev_b32_e32 v112, 16, v180
	v_and_b32_e32 v113, 0xffff0000, v180
	v_and_b32_e32 v119, 0xffff0000, v183
	v_pk_fma_f32 v[108:109], v[108:109], v[212:213], v[112:113]
	v_lshlrev_b32_e32 v114, 16, v181
	v_and_b32_e32 v115, 0xffff0000, v181
	v_pk_fma_f32 v[112:113], v[106:107], v[210:211], v[118:119]
	v_pk_fma_f32 v[106:107], v[104:105], v[208:209], v[116:117]
	v_cvt_pk_bf16_f32 v104, v108, v109
	v_add_co_u32_e32 v108, vcc, s45, v144
	v_pk_fma_f32 v[110:111], v[110:111], v[214:215], v[114:115]
	s_nop 0
	v_addc_co_u32_e32 v109, vcc, 0, v145, vcc
	v_cvt_pk_bf16_f32 v105, v110, v111
	v_cvt_pk_bf16_f32 v106, v106, v107
	v_cvt_pk_bf16_f32 v107, v112, v113
	global_store_dwordx4 v[108:109], v[104:107], off
	s_waitcnt vmcnt(15)
	v_lshlrev_b32_e32 v110, 16, v178
	v_and_b32_e32 v111, 0xffff0000, v178
	v_lshlrev_b32_e32 v104, 16, v176
	v_and_b32_e32 v105, 0xffff0000, v176
	v_lshlrev_b32_e32 v106, 16, v177
	v_and_b32_e32 v107, 0xffff0000, v177
	v_lshlrev_b32_e32 v112, 16, v179
	v_and_b32_e32 v113, 0xffff0000, v179
	v_pk_fma_f32 v[102:103], v[102:103], v[206:207], v[106:107]
	v_pk_fma_f32 v[100:101], v[100:101], v[204:205], v[104:105]
	v_pk_fma_f32 v[104:105], v[98:99], v[202:203], v[112:113]
	v_pk_fma_f32 v[98:99], v[96:97], v[200:201], v[110:111]
	v_cvt_pk_bf16_f32 v96, v100, v101
	v_cvt_pk_bf16_f32 v97, v102, v103
	s_waitcnt vmcnt(14)
	v_lshlrev_b32_e32 v100, 16, v174
	v_cvt_pk_bf16_f32 v98, v98, v99
	v_cvt_pk_bf16_f32 v99, v104, v105
	global_store_dwordx4 v[108:109], v[96:99], off offset:256
	v_and_b32_e32 v101, 0xffff0000, v174
	v_lshlrev_b32_e32 v102, 16, v175
	v_lshlrev_b32_e32 v96, 16, v172
	v_and_b32_e32 v97, 0xffff0000, v172
	v_and_b32_e32 v103, 0xffff0000, v175
	v_pk_fma_f32 v[92:93], v[92:93], v[212:213], v[96:97]
	v_lshlrev_b32_e32 v98, 16, v173
	v_and_b32_e32 v99, 0xffff0000, v173
	v_pk_fma_f32 v[96:97], v[90:91], v[210:211], v[102:103]
	v_pk_fma_f32 v[90:91], v[88:89], v[208:209], v[100:101]
	v_cvt_pk_bf16_f32 v88, v92, v93
	v_add_co_u32_e32 v92, vcc, s36, v144
	v_pk_fma_f32 v[94:95], v[94:95], v[214:215], v[98:99]
	s_nop 0
	v_addc_co_u32_e32 v93, vcc, 0, v145, vcc
	v_cvt_pk_bf16_f32 v89, v94, v95
	v_cvt_pk_bf16_f32 v90, v90, v91
	v_cvt_pk_bf16_f32 v91, v96, v97
	global_store_dwordx4 v[92:93], v[88:91], off
	s_waitcnt vmcnt(15)
	v_lshlrev_b32_e32 v94, 16, v170
	v_and_b32_e32 v95, 0xffff0000, v170
	v_lshlrev_b32_e32 v88, 16, v168
	v_and_b32_e32 v89, 0xffff0000, v168
	v_lshlrev_b32_e32 v90, 16, v169
	v_and_b32_e32 v91, 0xffff0000, v169
	v_lshlrev_b32_e32 v96, 16, v171
	v_and_b32_e32 v97, 0xffff0000, v171
	v_pk_fma_f32 v[86:87], v[86:87], v[206:207], v[90:91]
	v_pk_fma_f32 v[84:85], v[84:85], v[204:205], v[88:89]
	v_pk_fma_f32 v[88:89], v[82:83], v[202:203], v[96:97]
	v_pk_fma_f32 v[82:83], v[80:81], v[200:201], v[94:95]
	v_cvt_pk_bf16_f32 v80, v84, v85
	v_cvt_pk_bf16_f32 v81, v86, v87
	s_waitcnt vmcnt(14)
; __device__ __forceinline__ unsigned cvt_pk_bf16(float lo, float hi) { unsigned r; asm volatile("v_cvt_pk_bf16_f32 %0, %1, %2" : "=v"(r) : "v"(lo), "v"(hi)); return r; }
;     __device__ __forceinline__ void operator()(f32x4 (&acc)[2][2][4][2], const Unit& u, int wr, int wc, int fr, int fq, LAS unsigned char*) const {
;     ...
;                     for (int bj = 0; bj < 2; ++bj) { const u32x4 x = xb[ai][m][bj];
;                         f32x4 r0 = (f32x4){__uint_as_float(x.x << 16), __uint_as_float(x.x & 0xffff0000u), __uint_as_float(x.y << 16), __uint_as_float(x.y & 0xffff0000u)};
;                         f32x4 r1 = (f32x4){__uint_as_float(x.z << 16), __uint_as_float(x.z & 0xffff0000u), __uint_as_float(x.w << 16), __uint_as_float(x.w & 0xffff0000u)};
;                         r0 += sc[bj][0] * acc[ai][bj][m][0]; r1 += sc[bj][1] * acc[ai][bj][m][1];
;                         u32x4 w; w.x = cvt_pk_bf16(r0[0], r0[1]); w.y = cvt_pk_bf16(r0[2], r0[3]); w.z = cvt_pk_bf16(r1[0], r1[1]); w.w = cvt_pk_bf16(r1[2], r1[3]);
;                         *(u32x4*)(out + off0 + (size_t)(ai * HALF + m * 16) * D + bj * HALF) = w; }
	v_lshlrev_b32_e32 v84, 16, v166
	v_cvt_pk_bf16_f32 v82, v82, v83
	v_cvt_pk_bf16_f32 v83, v88, v89
	global_store_dwordx4 v[92:93], v[80:83], off offset:256
	v_and_b32_e32 v85, 0xffff0000, v166
	v_lshlrev_b32_e32 v86, 16, v167
	v_lshlrev_b32_e32 v80, 16, v164
	v_and_b32_e32 v81, 0xffff0000, v164
	v_and_b32_e32 v87, 0xffff0000, v167
	v_pk_fma_f32 v[76:77], v[76:77], v[212:213], v[80:81]
	v_lshlrev_b32_e32 v82, 16, v165
	v_and_b32_e32 v83, 0xffff0000, v165
	v_pk_fma_f32 v[80:81], v[74:75], v[210:211], v[86:87]
	v_pk_fma_f32 v[74:75], v[72:73], v[208:209], v[84:85]
	v_cvt_pk_bf16_f32 v72, v76, v77
	v_add_co_u32_e32 v76, vcc, s23, v144
	v_pk_fma_f32 v[78:79], v[78:79], v[214:215], v[82:83]
	s_nop 0
	v_addc_co_u32_e32 v77, vcc, 0, v145, vcc
	v_cvt_pk_bf16_f32 v73, v78, v79
	v_cvt_pk_bf16_f32 v74, v74, v75
	v_cvt_pk_bf16_f32 v75, v80, v81
	global_store_dwordx4 v[76:77], v[72:75], off
	s_waitcnt vmcnt(15)
	v_lshlrev_b32_e32 v78, 16, v162
	v_and_b32_e32 v79, 0xffff0000, v162
	v_lshlrev_b32_e32 v72, 16, v160
	v_and_b32_e32 v73, 0xffff0000, v160
	v_lshlrev_b32_e32 v74, 16, v161
	v_and_b32_e32 v75, 0xffff0000, v161
	v_lshlrev_b32_e32 v80, 16, v163
	v_and_b32_e32 v81, 0xffff0000, v163
	v_pk_fma_f32 v[70:71], v[70:71], v[206:207], v[74:75]
	v_pk_fma_f32 v[68:69], v[68:69], v[204:205], v[72:73]
	v_pk_fma_f32 v[72:73], v[66:67], v[202:203], v[80:81]
	v_pk_fma_f32 v[66:67], v[64:65], v[200:201], v[78:79]
	v_cvt_pk_bf16_f32 v64, v68, v69
	v_cvt_pk_bf16_f32 v65, v70, v71
	s_waitcnt vmcnt(14)
	v_lshlrev_b32_e32 v68, 16, v158
	v_cvt_pk_bf16_f32 v66, v66, v67
	v_cvt_pk_bf16_f32 v67, v72, v73
	global_store_dwordx4 v[76:77], v[64:67], off offset:256
	v_and_b32_e32 v69, 0xffff0000, v158
	v_lshlrev_b32_e32 v70, 16, v159
	v_lshlrev_b32_e32 v64, 16, v156
	v_and_b32_e32 v65, 0xffff0000, v156
	v_and_b32_e32 v71, 0xffff0000, v159
	v_pk_fma_f32 v[60:61], v[60:61], v[212:213], v[64:65]
	v_lshlrev_b32_e32 v66, 16, v157
	v_and_b32_e32 v67, 0xffff0000, v157
	v_pk_fma_f32 v[64:65], v[58:59], v[210:211], v[70:71]
	v_pk_fma_f32 v[58:59], v[56:57], v[208:209], v[68:69]
	v_cvt_pk_bf16_f32 v56, v60, v61
	v_add_co_u32_e32 v60, vcc, s93, v144
	v_pk_fma_f32 v[62:63], v[62:63], v[214:215], v[66:67]
	s_nop 0
	v_addc_co_u32_e32 v61, vcc, 0, v145, vcc
	v_cvt_pk_bf16_f32 v57, v62, v63
	v_cvt_pk_bf16_f32 v58, v58, v59
	v_cvt_pk_bf16_f32 v59, v64, v65
	global_store_dwordx4 v[60:61], v[56:59], off
	s_waitcnt vmcnt(15)
	v_lshlrev_b32_e32 v62, 16, v154
	v_and_b32_e32 v63, 0xffff0000, v154
	v_lshlrev_b32_e32 v56, 16, v152
	v_and_b32_e32 v57, 0xffff0000, v152
	v_lshlrev_b32_e32 v58, 16, v153
	v_and_b32_e32 v59, 0xffff0000, v153
	v_lshlrev_b32_e32 v64, 16, v155
	v_and_b32_e32 v65, 0xffff0000, v155
	v_pk_fma_f32 v[54:55], v[54:55], v[206:207], v[58:59]
	v_pk_fma_f32 v[52:53], v[52:53], v[204:205], v[56:57]
	v_pk_fma_f32 v[56:57], v[50:51], v[202:203], v[64:65]
	v_pk_fma_f32 v[50:51], v[48:49], v[200:201], v[62:63]
	v_cvt_pk_bf16_f32 v48, v52, v53
	v_cvt_pk_bf16_f32 v49, v54, v55
	s_waitcnt vmcnt(14)
	v_lshlrev_b32_e32 v52, 16, v142
	v_cvt_pk_bf16_f32 v50, v50, v51
	v_cvt_pk_bf16_f32 v51, v56, v57
	global_store_dwordx4 v[60:61], v[48:51], off offset:256
	v_and_b32_e32 v53, 0xffff0000, v142
	v_lshlrev_b32_e32 v54, 16, v143
	v_lshlrev_b32_e32 v48, 16, v140
	v_and_b32_e32 v49, 0xffff0000, v140
	v_and_b32_e32 v55, 0xffff0000, v143
	v_pk_fma_f32 v[44:45], v[44:45], v[212:213], v[48:49]
	v_lshlrev_b32_e32 v50, 16, v141
	v_and_b32_e32 v51, 0xffff0000, v141
	v_pk_fma_f32 v[48:49], v[42:43], v[210:211], v[54:55]
	v_pk_fma_f32 v[42:43], v[40:41], v[208:209], v[52:53]
	v_cvt_pk_bf16_f32 v40, v44, v45
	v_add_co_u32_e32 v44, vcc, s33, v144
	v_pk_fma_f32 v[46:47], v[46:47], v[214:215], v[50:51]
	s_nop 0
	v_addc_co_u32_e32 v45, vcc, 0, v145, vcc
	v_cvt_pk_bf16_f32 v41, v46, v47
	v_cvt_pk_bf16_f32 v42, v42, v43
	v_cvt_pk_bf16_f32 v43, v48, v49
	global_store_dwordx4 v[44:45], v[40:43], off
	s_waitcnt vmcnt(15)
; __device__ __forceinline__ unsigned cvt_pk_bf16(float lo, float hi) { unsigned r; asm volatile("v_cvt_pk_bf16_f32 %0, %1, %2" : "=v"(r) : "v"(lo), "v"(hi)); return r; }
; #define PG8_WAIT_V(n) asm volatile("s_waitcnt vmcnt(" #n ")" ::: "memory")
; #define PG8_BAR __builtin_amdgcn_s_barrier()
; template <class Epi>
; __device__ __forceinline__ void gemm_phase(LAS unsigned char* lds, const Gemm g, const StaticOrder& S, const Epi& E) {
;     ...
;         if (!has_next) break;
; #pragma unroll
;         for (int a = 0; a < 2; ++a)
; #pragma unroll
;             for (int b = 0; b < 2; ++b)
; #pragma unroll
;                 for (int m = 0; m < 4; ++m)
; #pragma unroll
;                     for (int n = 0; n < 2; ++n) acc[a][b][m][n] = (f32x4){0.f, 0.f, 0.f, 0.f};
;         cur = nxt; cA = nA; cB = nB; ++ui;
;     }
;     PG8_WAIT_V(0);
;     if (wr == 0) PG8_BAR;
;     PG8_BAR;
;     __device__ __forceinline__ void operator()(f32x4 (&acc)[2][2][4][2], const Unit& u, int wr, int wc, int fr, int fq, LAS unsigned char*) const {
;     ...
;             for (int ai = 0; ai < 2; ++ai)
; #pragma unroll
;                 for (int m = 0; m < 4; ++m)
; #pragma unroll
;                     for (int bj = 0; bj < 2; ++bj) { const u32x4 x = xb[ai][m][bj];
;                         f32x4 r0 = (f32x4){__uint_as_float(x.x << 16), __uint_as_float(x.x & 0xffff0000u), __uint_as_float(x.y << 16), __uint_as_float(x.y & 0xffff0000u)};
;                         f32x4 r1 = (f32x4){__uint_as_float(x.z << 16), __uint_as_float(x.z & 0xffff0000u), __uint_as_float(x.w << 16), __uint_as_float(x.w & 0xffff0000u)};
;                         r0 += sc[bj][0] * acc[ai][bj][m][0]; r1 += sc[bj][1] * acc[ai][bj][m][1];
;                         u32x4 w; w.x = cvt_pk_bf16(r0[0], r0[1]); w.y = cvt_pk_bf16(r0[2], r0[3]); w.z = cvt_pk_bf16(r1[0], r1[1]); w.w = cvt_pk_bf16(r1[2], r1[3]);
;                         *(u32x4*)(out + off0 + (size_t)(ai * HALF + m * 16) * D + bj * HALF) = w; }
	v_lshlrev_b32_e32 v46, 16, v138
	v_and_b32_e32 v47, 0xffff0000, v138
	v_lshlrev_b32_e32 v40, 16, v136
	v_and_b32_e32 v41, 0xffff0000, v136
	v_lshlrev_b32_e32 v42, 16, v137
	v_and_b32_e32 v43, 0xffff0000, v137
	v_lshlrev_b32_e32 v48, 16, v139
	v_and_b32_e32 v49, 0xffff0000, v139
	v_pk_fma_f32 v[38:39], v[38:39], v[206:207], v[42:43]
	v_pk_fma_f32 v[36:37], v[36:37], v[204:205], v[40:41]
	v_pk_fma_f32 v[40:41], v[34:35], v[202:203], v[48:49]
	v_pk_fma_f32 v[34:35], v[32:33], v[200:201], v[46:47]
	v_cvt_pk_bf16_f32 v32, v36, v37
	v_cvt_pk_bf16_f32 v33, v38, v39
	s_waitcnt vmcnt(14)
	v_lshlrev_b32_e32 v36, 16, v134
	v_cvt_pk_bf16_f32 v34, v34, v35
	v_cvt_pk_bf16_f32 v35, v40, v41
	global_store_dwordx4 v[44:45], v[32:35], off offset:256
	v_and_b32_e32 v37, 0xffff0000, v134
	v_lshlrev_b32_e32 v38, 16, v135
	v_lshlrev_b32_e32 v32, 16, v132
	v_and_b32_e32 v33, 0xffff0000, v132
	v_and_b32_e32 v39, 0xffff0000, v135
	v_pk_fma_f32 v[28:29], v[28:29], v[212:213], v[32:33]
	v_lshlrev_b32_e32 v34, 16, v133
	v_and_b32_e32 v35, 0xffff0000, v133
	v_pk_fma_f32 v[32:33], v[26:27], v[210:211], v[38:39]
	v_pk_fma_f32 v[26:27], v[24:25], v[208:209], v[36:37]
	v_cvt_pk_bf16_f32 v24, v28, v29
	v_add_co_u32_e32 v28, vcc, s18, v144
	v_pk_fma_f32 v[30:31], v[30:31], v[214:215], v[34:35]
	s_nop 0
	v_addc_co_u32_e32 v29, vcc, 0, v145, vcc
	v_cvt_pk_bf16_f32 v25, v30, v31
	v_cvt_pk_bf16_f32 v26, v26, v27
	v_cvt_pk_bf16_f32 v27, v32, v33
	global_store_dwordx4 v[28:29], v[24:27], off
	s_waitcnt vmcnt(15)
	v_lshlrev_b32_e32 v30, 16, v130
	v_and_b32_e32 v31, 0xffff0000, v130
	v_lshlrev_b32_e32 v24, 16, v128
	v_and_b32_e32 v25, 0xffff0000, v128
	v_lshlrev_b32_e32 v26, 16, v129
	v_and_b32_e32 v27, 0xffff0000, v129
	v_lshlrev_b32_e32 v32, 16, v131
	v_and_b32_e32 v33, 0xffff0000, v131
	v_pk_fma_f32 v[22:23], v[22:23], v[206:207], v[26:27]
	v_pk_fma_f32 v[20:21], v[20:21], v[204:205], v[24:25]
	v_pk_fma_f32 v[24:25], v[18:19], v[202:203], v[32:33]
	v_pk_fma_f32 v[18:19], v[16:17], v[200:201], v[30:31]
	v_cvt_pk_bf16_f32 v16, v20, v21
	v_cvt_pk_bf16_f32 v17, v22, v23
	s_waitcnt vmcnt(14)
	v_lshlrev_b32_e32 v20, 16, v126
	v_cvt_pk_bf16_f32 v18, v18, v19
	v_cvt_pk_bf16_f32 v19, v24, v25
	global_store_dwordx4 v[28:29], v[16:19], off offset:256
	v_and_b32_e32 v21, 0xffff0000, v126
	v_lshlrev_b32_e32 v22, 16, v127
	v_lshlrev_b32_e32 v16, 16, v124
	v_and_b32_e32 v17, 0xffff0000, v124
	v_and_b32_e32 v23, 0xffff0000, v127
	v_pk_fma_f32 v[12:13], v[12:13], v[212:213], v[16:17]
	v_lshlrev_b32_e32 v18, 16, v125
	v_and_b32_e32 v19, 0xffff0000, v125
	v_pk_fma_f32 v[16:17], v[10:11], v[210:211], v[22:23]
	v_pk_fma_f32 v[10:11], v[8:9], v[208:209], v[20:21]
	v_cvt_pk_bf16_f32 v8, v12, v13
	v_add_co_u32_e32 v12, vcc, s19, v144
	v_pk_fma_f32 v[14:15], v[14:15], v[214:215], v[18:19]
	s_nop 0
	v_addc_co_u32_e32 v13, vcc, 0, v145, vcc
	v_cvt_pk_bf16_f32 v9, v14, v15
	v_cvt_pk_bf16_f32 v10, v10, v11
	v_cvt_pk_bf16_f32 v11, v16, v17
	global_store_dwordx4 v[12:13], v[8:11], off
	s_waitcnt vmcnt(15)
	v_lshlrev_b32_e32 v14, 16, v122
	v_and_b32_e32 v15, 0xffff0000, v122
	v_lshlrev_b32_e32 v8, 16, v120
	v_and_b32_e32 v9, 0xffff0000, v120
	v_lshlrev_b32_e32 v16, 16, v123
	v_and_b32_e32 v17, 0xffff0000, v123
	v_lshlrev_b32_e32 v10, 16, v121
	v_and_b32_e32 v11, 0xffff0000, v121
	v_pk_fma_f32 v[4:5], v[4:5], v[204:205], v[8:9]
	v_pk_fma_f32 v[8:9], v[2:3], v[202:203], v[16:17]
	v_pk_fma_f32 v[2:3], v[0:1], v[200:201], v[14:15]
	s_and_b64 vcc, exec, s[4:5]
	v_pk_fma_f32 v[6:7], v[6:7], v[206:207], v[10:11]
	v_cvt_pk_bf16_f32 v0, v4, v5
	s_nop 0
	v_cvt_pk_bf16_f32 v1, v6, v7
	v_cvt_pk_bf16_f32 v2, v2, v3
	v_cvt_pk_bf16_f32 v3, v8, v9
	global_store_dwordx4 v[12:13], v[0:3], off offset:256
	s_cbranch_vccz .LBB0_603
	s_waitcnt vmcnt(0)
	s_cmpk_gt_u32 s16, 0xff
	v_readlane_b32 s38, v255, 44
	s_movk_i32 s30, 0x7ff
	s_cbranch_scc1 .LBB0_614
	s_barrier

; #define PG8_STAGE(bufoff, gbase, hoff, imm) do { _Pragma("unroll") for (int _i = 0; _i < 2; ++_i) { \
;         asm volatile("s_mov_b32 m0, %0\n\ts_nop 0\n\tglobal_load_lds_dwordx4 %1, %2" \
;             :: "s"(lds0 + (unsigned)((bufoff) + _i * 8192)), "v"(voff0), "s"((const char*)(gbase) + (size_t)(hoff) + (size_t)(_i * 8192)) : "memory"); } } while (0)
; #define PG8_LDA(dst, b, h) do { _Pragma("unroll") for (int m = 0; m < 4; ++m) _Pragma("unroll") for (int k = 0; k < 2; ++k) dst[m][k] = *(const LAS bf16x8*)(lds + PG8_SA(b, h) + aoff + m * 2048 + k * 1024); } while (0)
; #define PG8_LDB(dst, b, h) do { _Pragma("unroll") for (int n = 0; n < 2; ++n) _Pragma("unroll") for (int k = 0; k < 2; ++k) dst[n][k] = *(const LAS bf16x8*)(lds + PG8_SB(b, h) + boff + n * 2048 + k * 1024); } while (0)
; #define PG8_MMA(ai, bj, At, Bt) do { __builtin_amdgcn_s_setprio(1); _Pragma("unroll") for (int m = 0; m < 4; ++m) _Pragma("unroll") for (int n = 0; n < 2; ++n) _Pragma("unroll") for (int k = 0; k < 2; ++k) \
;         acc[ai][bj][m][n] = __builtin_amdgcn_mfma_f32_16x16x32_bf16(Bt[n][k], At[m][k], acc[ai][bj][m][n], 0, 0, 0); __builtin_amdgcn_s_setprio(0); } while (0)
; #define PG8_WAIT_V(n) asm volatile("s_waitcnt vmcnt(" #n ")" ::: "memory")
; #define PG8_BAR __builtin_amdgcn_s_barrier()
; template <class Epi>
; __device__ __forceinline__ void gemm_phase(LAS unsigned char* lds, const Gemm g, const StaticOrder& S, const Epi& E) {
;     ...
;         for (int t = 0; t < nt; t += 2) {
;             const bool last = (t == nt - 2);
;             if (last) E.pre(cur, wid, lane, (unsigned)(size_t)(lds + STAGE_BYTES));
;             const char* aT = cA + (size_t)t * KS;
;             const char* a2 = last ? nA : aT + 2 * KS; const char* b2 = last ? nB : cB + (size_t)(t + 2) * KS;
;             PG8_LDB(B0, 0, 0); PG8_SCHED; PG8_LDA(At, 0, 0); PG8_STAGE(PG8_SA(1, 1), aT + KS, hA, 0);
;             PG8_WAIT_L(8); PG8_BAR; PG8_WAIT_L(0); PG8_MMA(0, 0, At, B0); PG8_BAR; PG8_SCHED;
;             PG8_LDB(B1, 0, 1); PG8_STAGE(PG8_SB(0, 0), b2, 0, 0);
;             PG8_BAR; PG8_WAIT_L(0); PG8_MMA(0, 1, At, B1); PG8_BAR;
;             PG8_LDA(At, 0, 1); PG8_STAGE(PG8_SA(0, 0), a2, 0, 0);
;             PG8_BAR; PG8_WAIT_L(0); PG8_MMA(1, 0, At, B0); PG8_BAR; PG8_SCHED;
;             PG8_STAGE(PG8_SB(0, 1), b2, hB, 0);
;             PG8_WAIT_V(6); PG8_BAR; PG8_MMA(1, 1, At, B1); PG8_BAR;
.LBB0_860:
	s_add_u32 s58, s56, 0x8000
	v_add_u32_e32 v132, 0x10000, v236
	s_addc_u32 s59, s57, 0
	ds_read_b128 v[120:123], v132
	ds_read_b128 v[124:127], v132 offset:1024
	ds_read_b128 v[128:131], v132 offset:2048
	ds_read_b128 v[132:135], v132 offset:3072
	s_add_u32 s48, s56, 0x164000
	s_addc_u32 s49, s57, 0
	s_add_u32 s60, s56, 0x166000
	s_addc_u32 s61, s57, 0
	s_cmpk_eq_i32 s69, 0x54
	s_cselect_b32 s57, s7, s59
	s_cselect_b32 s56, s6, s58
	ds_read_b128 v[136:139], v237
	ds_read_b128 v[140:143], v237 offset:1024
	ds_read_b128 v[152:155], v237 offset:2048
	ds_read_b128 v[156:159], v237 offset:3072
	ds_read_b128 v[160:163], v237 offset:4096
	ds_read_b128 v[164:167], v237 offset:5120
	ds_read_b128 v[168:171], v237 offset:6144
	ds_read_b128 v[172:175], v237 offset:7168
	s_mov_b32 m0, s65
	s_nop 0
	global_load_lds_dwordx4 v188, s[48:49]
	s_mov_b32 m0, s66
	s_nop 0
	global_load_lds_dwordx4 v188, s[60:61]
	s_waitcnt lgkmcnt(8)
	s_waitcnt vmcnt(10)
	s_barrier
	s_waitcnt lgkmcnt(7)
	v_mfma_f32_16x16x32_bf16 v[148:151], v[120:123], v[136:139], v[148:151]
	v_mfma_f32_16x16x32_bf16 v[144:147], v[128:131], v[136:139], v[144:147]
	s_waitcnt lgkmcnt(5)
	v_mfma_f32_16x16x32_bf16 v[108:111], v[120:123], v[152:155], v[108:111]
	v_mfma_f32_16x16x32_bf16 v[104:107], v[128:131], v[152:155], v[104:107]
	s_waitcnt lgkmcnt(3)
	v_mfma_f32_16x16x32_bf16 v[92:95], v[120:123], v[160:163], v[92:95]
	v_mfma_f32_16x16x32_bf16 v[88:91], v[128:131], v[160:163], v[88:91]
	s_waitcnt lgkmcnt(1)
	v_mfma_f32_16x16x32_bf16 v[76:79], v[120:123], v[168:171], v[76:79]
	v_mfma_f32_16x16x32_bf16 v[72:75], v[128:131], v[168:171], v[72:75]
	v_mfma_f32_16x16x32_bf16 v[148:151], v[124:127], v[140:143], v[148:151]
	v_mfma_f32_16x16x32_bf16 v[144:147], v[132:135], v[140:143], v[144:147]
	v_mfma_f32_16x16x32_bf16 v[108:111], v[124:127], v[156:159], v[108:111]
	v_mfma_f32_16x16x32_bf16 v[104:107], v[132:135], v[156:159], v[104:107]
	v_mfma_f32_16x16x32_bf16 v[92:95], v[124:127], v[164:167], v[92:95]
	v_mfma_f32_16x16x32_bf16 v[88:91], v[132:135], v[164:167], v[88:91]
	s_waitcnt lgkmcnt(0)
	v_mfma_f32_16x16x32_bf16 v[76:79], v[124:127], v[172:175], v[76:79]
	v_mfma_f32_16x16x32_bf16 v[72:75], v[132:135], v[172:175], v[72:75]
	s_barrier
	v_add_u32_e32 v200, 0x14000, v236
	ds_read_b128 v[176:179], v200
	ds_read_b128 v[180:183], v200 offset:1024
	ds_read_b128 v[184:187], v200 offset:2048
	ds_read_b128 v[200:203], v200 offset:3072
	s_cselect_b32 s60, s8, s0
	s_cselect_b32 s61, s9, s1
	s_mov_b32 m0, s26
	s_nop 0
	global_load_lds_dwordx4 v188, s[60:61]
	s_add_u32 s48, s60, 0x2000
	s_addc_u32 s49, s61, 0
	s_mov_b32 m0, s27
	s_nop 0
	global_load_lds_dwordx4 v188, s[48:49]
	s_waitcnt vmcnt(10)
	s_barrier
	s_waitcnt lgkmcnt(3)
	v_mfma_f32_16x16x32_bf16 v[116:119], v[176:179], v[136:139], v[116:119]
	s_waitcnt lgkmcnt(1)
	v_mfma_f32_16x16x32_bf16 v[112:115], v[184:187], v[136:139], v[112:115]
	v_mfma_f32_16x16x32_bf16 v[100:103], v[176:179], v[152:155], v[100:103]
	v_mfma_f32_16x16x32_bf16 v[96:99], v[184:187], v[152:155], v[96:99]
	v_mfma_f32_16x16x32_bf16 v[84:87], v[176:179], v[160:163], v[84:87]
	v_mfma_f32_16x16x32_bf16 v[80:83], v[184:187], v[160:163], v[80:83]
	v_mfma_f32_16x16x32_bf16 v[68:71], v[176:179], v[168:171], v[68:71]
	v_mfma_f32_16x16x32_bf16 v[64:67], v[184:187], v[168:171], v[64:67]
	v_mfma_f32_16x16x32_bf16 v[116:119], v[180:183], v[140:143], v[116:119]
	s_waitcnt lgkmcnt(0)
	v_mfma_f32_16x16x32_bf16 v[112:115], v[200:203], v[140:143], v[112:115]
	v_mfma_f32_16x16x32_bf16 v[100:103], v[180:183], v[156:159], v[100:103]
	v_mfma_f32_16x16x32_bf16 v[96:99], v[200:203], v[156:159], v[96:99]
	v_mfma_f32_16x16x32_bf16 v[84:87], v[180:183], v[164:167], v[84:87]
	v_mfma_f32_16x16x32_bf16 v[80:83], v[200:203], v[164:167], v[80:83]
	v_mfma_f32_16x16x32_bf16 v[68:71], v[180:183], v[172:175], v[68:71]
	v_mfma_f32_16x16x32_bf16 v[64:67], v[200:203], v[172:175], v[64:67]
	s_barrier
	ds_read_b128 v[136:139], v237 offset:16384
	ds_read_b128 v[140:143], v237 offset:17408
	ds_read_b128 v[152:155], v237 offset:18432
	ds_read_b128 v[156:159], v237 offset:19456
	ds_read_b128 v[160:163], v237 offset:20480
	ds_read_b128 v[164:167], v237 offset:21504
	ds_read_b128 v[168:171], v237 offset:22528
	ds_read_b128 v[172:175], v237 offset:23552
	s_mov_b32 m0, s25
	s_nop 0
	global_load_lds_dwordx4 v188, s[56:57]
	s_add_u32 s48, s56, 0x2000
	s_addc_u32 s49, s57, 0
	s_mov_b32 m0, s28
	s_nop 0
	global_load_lds_dwordx4 v188, s[48:49]
	s_add_u32 s48, s60, 0x160000
	s_addc_u32 s49, s61, 0
	s_mov_b32 m0, s29
	s_nop 0
	global_load_lds_dwordx4 v188, s[48:49]
	s_add_u32 s48, s60, 0x162000
	s_addc_u32 s49, s61, 0
	s_mov_b32 m0, s30
	s_nop 0
	global_load_lds_dwordx4 v188, s[48:49]
	s_waitcnt vmcnt(10)
	s_barrier
; #define PG8_STAGE(bufoff, gbase, hoff, imm) do { _Pragma("unroll") for (int _i = 0; _i < 2; ++_i) { \
;         asm volatile("s_mov_b32 m0, %0\n\ts_nop 0\n\tglobal_load_lds_dwordx4 %1, %2" \
;             :: "s"(lds0 + (unsigned)((bufoff) + _i * 8192)), "v"(voff0), "s"((const char*)(gbase) + (size_t)(hoff) + (size_t)(_i * 8192)) : "memory"); } } while (0)
; #define PG8_LDA(dst, b, h) do { _Pragma("unroll") for (int m = 0; m < 4; ++m) _Pragma("unroll") for (int k = 0; k < 2; ++k) dst[m][k] = *(const LAS bf16x8*)(lds + PG8_SA(b, h) + aoff + m * 2048 + k * 1024); } while (0)
; #define PG8_LDB(dst, b, h) do { _Pragma("unroll") for (int n = 0; n < 2; ++n) _Pragma("unroll") for (int k = 0; k < 2; ++k) dst[n][k] = *(const LAS bf16x8*)(lds + PG8_SB(b, h) + boff + n * 2048 + k * 1024); } while (0)
; #define PG8_MMA(ai, bj, At, Bt) do { __builtin_amdgcn_s_setprio(1); _Pragma("unroll") for (int m = 0; m < 4; ++m) _Pragma("unroll") for (int n = 0; n < 2; ++n) _Pragma("unroll") for (int k = 0; k < 2; ++k) \
;         acc[ai][bj][m][n] = __builtin_amdgcn_mfma_f32_16x16x32_bf16(Bt[n][k], At[m][k], acc[ai][bj][m][n], 0, 0, 0); __builtin_amdgcn_s_setprio(0); } while (0)
; #define PG8_WAIT_V(n) asm volatile("s_waitcnt vmcnt(" #n ")" ::: "memory")
; #define PG8_WAIT_L(n) asm volatile("s_waitcnt lgkmcnt(" #n ")" ::: "memory")
; #define PG8_BAR __builtin_amdgcn_s_barrier()
; #define PG8_SCHED __builtin_amdgcn_sched_barrier(0)
; template <class Epi>
; __device__ __forceinline__ void gemm_phase(LAS unsigned char* lds, const Gemm g, const StaticOrder& S, const Epi& E) {
;     ...
;             PG8_WAIT_V(6); PG8_BAR; PG8_MMA(1, 1, At, B1); PG8_BAR;
;             PG8_LDB(B0, 1, 0); PG8_SCHED; PG8_LDA(At, 1, 0); PG8_STAGE(PG8_SA(0, 1), a2, hA, 0);
;             PG8_WAIT_L(8); PG8_BAR; PG8_WAIT_L(0); PG8_MMA(0, 0, At, B0); PG8_BAR; PG8_SCHED;
;             PG8_LDB(B1, 1, 1); PG8_STAGE(PG8_SB(1, 0), b2 + KS, 0, 0);
;             PG8_BAR; PG8_WAIT_L(0); PG8_MMA(0, 1, At, B1); PG8_BAR;
;             PG8_LDA(At, 1, 1); PG8_STAGE(PG8_SA(1, 0), a2 + KS, 0, 0);
;             PG8_BAR; PG8_WAIT_L(0); PG8_MMA(1, 0, At, B0); PG8_BAR; PG8_SCHED;
	s_waitcnt lgkmcnt(7)
	v_mfma_f32_16x16x32_bf16 v[60:63], v[120:123], v[136:139], v[60:63]
	v_mfma_f32_16x16x32_bf16 v[56:59], v[128:131], v[136:139], v[56:59]
	s_waitcnt lgkmcnt(5)
	v_mfma_f32_16x16x32_bf16 v[44:47], v[120:123], v[152:155], v[44:47]
	v_mfma_f32_16x16x32_bf16 v[40:43], v[128:131], v[152:155], v[40:43]
	s_waitcnt lgkmcnt(3)
	v_mfma_f32_16x16x32_bf16 v[28:31], v[120:123], v[160:163], v[28:31]
	v_mfma_f32_16x16x32_bf16 v[24:27], v[128:131], v[160:163], v[24:27]
	s_waitcnt lgkmcnt(1)
	v_mfma_f32_16x16x32_bf16 v[12:15], v[120:123], v[168:171], v[12:15]
	v_mfma_f32_16x16x32_bf16 v[8:11], v[128:131], v[168:171], v[8:11]
	v_mfma_f32_16x16x32_bf16 v[60:63], v[124:127], v[140:143], v[60:63]
	v_mfma_f32_16x16x32_bf16 v[56:59], v[132:135], v[140:143], v[56:59]
	v_mfma_f32_16x16x32_bf16 v[44:47], v[124:127], v[156:159], v[44:47]
	v_mfma_f32_16x16x32_bf16 v[40:43], v[132:135], v[156:159], v[40:43]
	v_mfma_f32_16x16x32_bf16 v[28:31], v[124:127], v[164:167], v[28:31]
	v_mfma_f32_16x16x32_bf16 v[24:27], v[132:135], v[164:167], v[24:27]
	s_waitcnt lgkmcnt(0)
	v_mfma_f32_16x16x32_bf16 v[12:15], v[124:127], v[172:175], v[12:15]
	v_mfma_f32_16x16x32_bf16 v[8:11], v[132:135], v[172:175], v[8:11]
	v_mfma_f32_16x16x32_bf16 v[52:55], v[176:179], v[136:139], v[52:55]
	v_mfma_f32_16x16x32_bf16 v[48:51], v[184:187], v[136:139], v[48:51]
	v_mfma_f32_16x16x32_bf16 v[36:39], v[176:179], v[152:155], v[36:39]
	v_mfma_f32_16x16x32_bf16 v[32:35], v[184:187], v[152:155], v[32:35]
	v_mfma_f32_16x16x32_bf16 v[20:23], v[176:179], v[160:163], v[20:23]
	v_mfma_f32_16x16x32_bf16 v[16:19], v[184:187], v[160:163], v[16:19]
	v_mfma_f32_16x16x32_bf16 v[4:7], v[176:179], v[168:171], v[4:7]
	v_mfma_f32_16x16x32_bf16 v[0:3], v[184:187], v[168:171], v[0:3]
	v_mfma_f32_16x16x32_bf16 v[52:55], v[180:183], v[140:143], v[52:55]
	v_mfma_f32_16x16x32_bf16 v[48:51], v[200:203], v[140:143], v[48:51]
	v_mfma_f32_16x16x32_bf16 v[36:39], v[180:183], v[156:159], v[36:39]
	v_mfma_f32_16x16x32_bf16 v[32:35], v[200:203], v[156:159], v[32:35]
	v_mfma_f32_16x16x32_bf16 v[20:23], v[180:183], v[164:167], v[20:23]
	v_mfma_f32_16x16x32_bf16 v[16:19], v[200:203], v[164:167], v[16:19]
	v_mfma_f32_16x16x32_bf16 v[4:7], v[180:183], v[172:175], v[4:7]
	v_mfma_f32_16x16x32_bf16 v[0:3], v[200:203], v[172:175], v[0:3]
	v_add_u32_e32 v132, 0x18000, v236
	s_barrier
	ds_read_b128 v[120:123], v132
	ds_read_b128 v[124:127], v132 offset:1024
	ds_read_b128 v[128:131], v132 offset:2048
	ds_read_b128 v[132:135], v132 offset:3072
	ds_read_b128 v[136:139], v237 offset:32768
	ds_read_b128 v[140:143], v237 offset:33792
	ds_read_b128 v[152:155], v237 offset:34816
	ds_read_b128 v[156:159], v237 offset:35840
	ds_read_b128 v[160:163], v237 offset:36864
	ds_read_b128 v[164:167], v237 offset:37888
	ds_read_b128 v[168:171], v237 offset:38912
	ds_read_b128 v[172:175], v237 offset:39936
	s_add_u32 s48, s56, 0x160000
	s_addc_u32 s49, s57, 0
	s_mov_b32 m0, s34
	s_nop 0
	global_load_lds_dwordx4 v188, s[48:49]
	s_add_u32 s48, s56, 0x162000
	s_addc_u32 s49, s57, 0
	s_mov_b32 m0, s37
	s_nop 0
	global_load_lds_dwordx4 v188, s[48:49]
	s_waitcnt lgkmcnt(8)
	s_waitcnt vmcnt(10)
	s_barrier
	s_waitcnt lgkmcnt(7)
	v_mfma_f32_16x16x32_bf16 v[148:151], v[120:123], v[136:139], v[148:151]
	v_mfma_f32_16x16x32_bf16 v[144:147], v[128:131], v[136:139], v[144:147]
	s_waitcnt lgkmcnt(5)
	v_mfma_f32_16x16x32_bf16 v[108:111], v[120:123], v[152:155], v[108:111]
	v_mfma_f32_16x16x32_bf16 v[104:107], v[128:131], v[152:155], v[104:107]
	s_waitcnt lgkmcnt(3)
	v_mfma_f32_16x16x32_bf16 v[92:95], v[120:123], v[160:163], v[92:95]
	v_mfma_f32_16x16x32_bf16 v[88:91], v[128:131], v[160:163], v[88:91]
	s_waitcnt lgkmcnt(1)
	v_mfma_f32_16x16x32_bf16 v[76:79], v[120:123], v[168:171], v[76:79]
	v_mfma_f32_16x16x32_bf16 v[72:75], v[128:131], v[168:171], v[72:75]
	v_mfma_f32_16x16x32_bf16 v[148:151], v[124:127], v[140:143], v[148:151]
	v_mfma_f32_16x16x32_bf16 v[144:147], v[132:135], v[140:143], v[144:147]
	v_mfma_f32_16x16x32_bf16 v[108:111], v[124:127], v[156:159], v[108:111]
	v_mfma_f32_16x16x32_bf16 v[104:107], v[132:135], v[156:159], v[104:107]
	v_mfma_f32_16x16x32_bf16 v[92:95], v[124:127], v[164:167], v[92:95]
	v_mfma_f32_16x16x32_bf16 v[88:91], v[132:135], v[164:167], v[88:91]
	s_waitcnt lgkmcnt(0)
	v_mfma_f32_16x16x32_bf16 v[76:79], v[124:127], v[172:175], v[76:79]
	v_mfma_f32_16x16x32_bf16 v[72:75], v[132:135], v[172:175], v[72:75]
	s_barrier
	v_add_u32_e32 v200, 0x1c000, v236
	ds_read_b128 v[176:179], v200
	ds_read_b128 v[180:183], v200 offset:1024
	ds_read_b128 v[184:187], v200 offset:2048
	ds_read_b128 v[200:203], v200 offset:3072
	s_add_u32 s48, s60, 0x4000
	s_addc_u32 s49, s61, 0
	s_mov_b32 m0, s41
	s_nop 0
	global_load_lds_dwordx4 v188, s[48:49]
	s_add_u32 s48, s60, 0x6000
	s_addc_u32 s49, s61, 0
	s_mov_b32 m0, s42
	s_nop 0
	global_load_lds_dwordx4 v188, s[48:49]
	s_waitcnt vmcnt(10)
	s_barrier
	s_waitcnt lgkmcnt(3)
	v_mfma_f32_16x16x32_bf16 v[116:119], v[176:179], v[136:139], v[116:119]
	s_waitcnt lgkmcnt(1)
	v_mfma_f32_16x16x32_bf16 v[112:115], v[184:187], v[136:139], v[112:115]
	v_mfma_f32_16x16x32_bf16 v[100:103], v[176:179], v[152:155], v[100:103]
	v_mfma_f32_16x16x32_bf16 v[96:99], v[184:187], v[152:155], v[96:99]
	v_mfma_f32_16x16x32_bf16 v[84:87], v[176:179], v[160:163], v[84:87]
	v_mfma_f32_16x16x32_bf16 v[80:83], v[184:187], v[160:163], v[80:83]
	v_mfma_f32_16x16x32_bf16 v[68:71], v[176:179], v[168:171], v[68:71]
	v_mfma_f32_16x16x32_bf16 v[64:67], v[184:187], v[168:171], v[64:67]
	v_mfma_f32_16x16x32_bf16 v[116:119], v[180:183], v[140:143], v[116:119]
	s_waitcnt lgkmcnt(0)
	v_mfma_f32_16x16x32_bf16 v[112:115], v[200:203], v[140:143], v[112:115]
	v_mfma_f32_16x16x32_bf16 v[100:103], v[180:183], v[156:159], v[100:103]
	v_mfma_f32_16x16x32_bf16 v[96:99], v[200:203], v[156:159], v[96:99]
	v_mfma_f32_16x16x32_bf16 v[84:87], v[180:183], v[164:167], v[84:87]
	v_mfma_f32_16x16x32_bf16 v[80:83], v[200:203], v[164:167], v[80:83]
	v_mfma_f32_16x16x32_bf16 v[68:71], v[180:183], v[172:175], v[68:71]
	v_mfma_f32_16x16x32_bf16 v[64:67], v[200:203], v[172:175], v[64:67]
	s_barrier
; #define PG8_STAGE(bufoff, gbase, hoff, imm) do { _Pragma("unroll") for (int _i = 0; _i < 2; ++_i) { \
;         asm volatile("s_mov_b32 m0, %0\n\ts_nop 0\n\tglobal_load_lds_dwordx4 %1, %2" \
;             :: "s"(lds0 + (unsigned)((bufoff) + _i * 8192)), "v"(voff0), "s"((const char*)(gbase) + (size_t)(hoff) + (size_t)(_i * 8192)) : "memory"); } } while (0)
; #define PG8_LDA(dst, b, h) do { _Pragma("unroll") for (int m = 0; m < 4; ++m) _Pragma("unroll") for (int k = 0; k < 2; ++k) dst[m][k] = *(const LAS bf16x8*)(lds + PG8_SA(b, h) + aoff + m * 2048 + k * 1024); } while (0)
; #define PG8_LDB(dst, b, h) do { _Pragma("unroll") for (int n = 0; n < 2; ++n) _Pragma("unroll") for (int k = 0; k < 2; ++k) dst[n][k] = *(const LAS bf16x8*)(lds + PG8_SB(b, h) + boff + n * 2048 + k * 1024); } while (0)
; #define PG8_WAIT_V(n) asm volatile("s_waitcnt vmcnt(" #n ")" ::: "memory")
; #define PG8_WAIT_L(n) asm volatile("s_waitcnt lgkmcnt(" #n ")" ::: "memory")
; #define PG8_BAR __builtin_amdgcn_s_barrier()
; #define PG8_SCHED __builtin_amdgcn_sched_barrier(0)
; template <class Epi>
; __device__ __forceinline__ void gemm_phase(LAS unsigned char* lds, const Gemm g, const StaticOrder& S, const Epi& E) {
;     ...
;             PG8_LDB(B1, 1, 1); PG8_STAGE(PG8_SB(1, 0), b2 + KS, 0, 0);
;             PG8_BAR; PG8_WAIT_L(0); PG8_MMA(0, 1, At, B1); PG8_BAR;
;             PG8_LDA(At, 1, 1); PG8_STAGE(PG8_SA(1, 0), a2 + KS, 0, 0);
;             PG8_BAR; PG8_WAIT_L(0); PG8_MMA(1, 0, At, B0); PG8_BAR; PG8_SCHED;
;             PG8_STAGE(PG8_SB(1, 1), b2 + KS, hB, 0);
;             PG8_WAIT_V(6); PG8_BAR; PG8_MMA(1, 1, At, B1); PG8_BAR;
;         }
;         E(acc, cur, wr, wc, fr, fq, lds + STAGE_BYTES);
;     __device__ __forceinline__ void operator()(f32x4 (&acc)[2][2][4][2], const Unit& u, int wr, int wc, int fr, int fq, LAS unsigned char*) const {
;         const int b = u.pm >> 6;
;         const int col0 = u.pn * BM + wc * 32 + 8 * fq;
;         const size_t off0 = (size_t)(u.pm * BM + wr * 64 + fr) * D + col0;
;         f32x4 sc[2][2];
; #pragma unroll
;         for (int bj = 0; bj < 2; ++bj)
; #pragma unroll
;             for (int n = 0; n < 2; ++n) { f32x4 gt = *(const f32x4*)(gate + (size_t)b * MODW + col0 + bj * HALF + n * 4); sc[bj][n] = gt + 1.0f;
;                 if (cs) sc[bj][n] *= *(const f32x4*)(cs + col0 + bj * HALF + n * 4); }
	ds_read_b128 v[136:139], v237 offset:49152
	ds_read_b128 v[140:143], v237 offset:50176
	ds_read_b128 v[152:155], v237 offset:51200
	ds_read_b128 v[156:159], v237 offset:52224
	ds_read_b128 v[160:163], v237 offset:53248
	ds_read_b128 v[164:167], v237 offset:54272
	ds_read_b128 v[168:171], v237 offset:55296
	ds_read_b128 v[172:175], v237 offset:56320
	s_add_u32 s48, s56, 0x4000
	s_addc_u32 s49, s57, 0
	s_mov_b32 m0, s43
	s_nop 0
	global_load_lds_dwordx4 v188, s[48:49]
	s_add_u32 s48, s56, 0x6000
	s_addc_u32 s49, s57, 0
	s_mov_b32 m0, s62
	s_nop 0
	global_load_lds_dwordx4 v188, s[48:49]
	s_add_u32 s48, s60, 0x164000
	s_addc_u32 s49, s61, 0
	s_mov_b32 m0, s63
	s_nop 0
	global_load_lds_dwordx4 v188, s[48:49]
	s_add_u32 s48, s60, 0x166000
	s_addc_u32 s49, s61, 0
	s_mov_b32 m0, s64
	s_nop 0
	global_load_lds_dwordx4 v188, s[48:49]
	s_waitcnt vmcnt(10)
	s_barrier
	s_waitcnt lgkmcnt(7)
	v_mfma_f32_16x16x32_bf16 v[60:63], v[120:123], v[136:139], v[60:63]
	v_mfma_f32_16x16x32_bf16 v[56:59], v[128:131], v[136:139], v[56:59]
	s_waitcnt lgkmcnt(5)
	v_mfma_f32_16x16x32_bf16 v[44:47], v[120:123], v[152:155], v[44:47]
	v_mfma_f32_16x16x32_bf16 v[40:43], v[128:131], v[152:155], v[40:43]
	s_waitcnt lgkmcnt(3)
	v_mfma_f32_16x16x32_bf16 v[28:31], v[120:123], v[160:163], v[28:31]
	v_mfma_f32_16x16x32_bf16 v[24:27], v[128:131], v[160:163], v[24:27]
	s_waitcnt lgkmcnt(1)
	v_mfma_f32_16x16x32_bf16 v[12:15], v[120:123], v[168:171], v[12:15]
	v_mfma_f32_16x16x32_bf16 v[8:11], v[128:131], v[168:171], v[8:11]
	v_mfma_f32_16x16x32_bf16 v[60:63], v[124:127], v[140:143], v[60:63]
	v_mfma_f32_16x16x32_bf16 v[56:59], v[132:135], v[140:143], v[56:59]
	v_mfma_f32_16x16x32_bf16 v[44:47], v[124:127], v[156:159], v[44:47]
	v_mfma_f32_16x16x32_bf16 v[40:43], v[132:135], v[156:159], v[40:43]
	v_mfma_f32_16x16x32_bf16 v[28:31], v[124:127], v[164:167], v[28:31]
	v_mfma_f32_16x16x32_bf16 v[24:27], v[132:135], v[164:167], v[24:27]
	s_waitcnt lgkmcnt(0)
	v_mfma_f32_16x16x32_bf16 v[12:15], v[124:127], v[172:175], v[12:15]
	v_mfma_f32_16x16x32_bf16 v[8:11], v[132:135], v[172:175], v[8:11]
	v_mfma_f32_16x16x32_bf16 v[52:55], v[176:179], v[136:139], v[52:55]
	v_mfma_f32_16x16x32_bf16 v[48:51], v[184:187], v[136:139], v[48:51]
	v_mfma_f32_16x16x32_bf16 v[36:39], v[176:179], v[152:155], v[36:39]
	v_mfma_f32_16x16x32_bf16 v[32:35], v[184:187], v[152:155], v[32:35]
	v_mfma_f32_16x16x32_bf16 v[20:23], v[176:179], v[160:163], v[20:23]
	v_mfma_f32_16x16x32_bf16 v[16:19], v[184:187], v[160:163], v[16:19]
	v_mfma_f32_16x16x32_bf16 v[4:7], v[176:179], v[168:171], v[4:7]
	v_mfma_f32_16x16x32_bf16 v[0:3], v[184:187], v[168:171], v[0:3]
	v_mfma_f32_16x16x32_bf16 v[52:55], v[180:183], v[140:143], v[52:55]
	v_mfma_f32_16x16x32_bf16 v[48:51], v[200:203], v[140:143], v[48:51]
	v_mfma_f32_16x16x32_bf16 v[36:39], v[180:183], v[156:159], v[36:39]
	v_mfma_f32_16x16x32_bf16 v[32:35], v[200:203], v[156:159], v[32:35]
	v_mfma_f32_16x16x32_bf16 v[20:23], v[180:183], v[164:167], v[20:23]
	v_mfma_f32_16x16x32_bf16 v[16:19], v[200:203], v[164:167], v[16:19]
	v_mfma_f32_16x16x32_bf16 v[4:7], v[180:183], v[172:175], v[4:7]
	v_mfma_f32_16x16x32_bf16 v[0:3], v[200:203], v[172:175], v[0:3]
	s_add_i32 s69, s69, 2
	s_add_u32 s0, s0, 0x8000
	s_addc_u32 s1, s1, 0
	s_cmpk_gt_u32 s69, 0x55
	s_mov_b64 s[56:57], s[58:59]
	s_barrier
	s_cbranch_scc0 .LBB0_860
	s_ashr_i32 s0, s50, 6
	s_mul_hi_i32 s1, s0, 0xc000
	s_mul_i32 s0, s0, 0xc000
	v_lshl_or_b32 v128, s51, 8, v234
	s_add_u32 s0, s39, s0
	v_ashrrev_i32_e32 v129, 31, v128
	s_addc_u32 s1, s40, s1
	v_lshl_add_u64 v[130:131], v[128:129], 2, s[0:1]
	global_load_dwordx4 v[120:123], v[130:131], off offset:16
	global_load_dwordx4 v[124:127], v[130:131], off
	s_mov_b32 s51, s67
	s_mov_b64 s[58:59], s[8:9]
	s_mov_b64 s[56:57], s[6:7]
	s_waitcnt vmcnt(1)
	v_pk_add_f32 v[210:211], v[122:123], 1.0 op_sel_hi:[1,0]
	s_waitcnt vmcnt(0)
	v_pk_add_f32 v[214:215], v[126:127], 1.0 op_sel_hi:[1,0]
	v_pk_add_f32 v[212:213], v[124:125], 1.0 op_sel_hi:[1,0]
	v_pk_add_f32 v[208:209], v[120:121], 1.0 op_sel_hi:[1,0]
	global_load_dwordx4 v[120:123], v[130:131], off offset:528
	global_load_dwordx4 v[124:127], v[130:131], off offset:512
	s_waitcnt vmcnt(1)
	v_pk_add_f32 v[200:201], v[120:121], 1.0 op_sel_hi:[1,0]
	v_lshl_add_u32 v120, s50, 8, v233
	v_ashrrev_i32_e32 v121, 31, v120
	v_lshlrev_b64 v[120:121], 11, v[120:121]
	v_lshl_add_u64 v[120:121], v[120:121], 0, v[128:129]
	v_lshlrev_b64 v[216:217], 1, v[120:121]
	v_lshl_add_u64 v[120:121], s[52:53], 0, v[216:217]
	global_load_dwordx4 v[238:241], v[120:121], off
	global_load_dwordx4 v[184:187], v[120:121], off offset:256
	v_pk_add_f32 v[202:203], v[122:123], 1.0 op_sel_hi:[1,0]
	v_add_co_u32_e32 v122, vcc, s45, v120
	s_waitcnt vmcnt(2)
	v_pk_add_f32 v[206:207], v[126:127], 1.0 op_sel_hi:[1,0]
	v_addc_co_u32_e32 v123, vcc, 0, v121, vcc
	global_load_dwordx4 v[180:183], v[122:123], off
	global_load_dwordx4 v[176:179], v[122:123], off offset:256
	v_add_co_u32_e32 v122, vcc, s36, v120
	v_pk_add_f32 v[204:205], v[124:125], 1.0 op_sel_hi:[1,0]
	s_nop 0
	v_addc_co_u32_e32 v123, vcc, 0, v121, vcc
	global_load_dwordx4 v[172:175], v[122:123], off
	global_load_dwordx4 v[168:171], v[122:123], off offset:256
	v_add_co_u32_e32 v122, vcc, s23, v120
	s_mov_b32 s50, s68
	s_nop 0
	v_addc_co_u32_e32 v123, vcc, 0, v121, vcc
	global_load_dwordx4 v[164:167], v[122:123], off
	global_load_dwordx4 v[160:163], v[122:123], off offset:256
	v_add_co_u32_e32 v122, vcc, s93, v120
	s_waitcnt vmcnt(7)
; __device__ __forceinline__ unsigned cvt_pk_bf16(float lo, float hi) { unsigned r; asm volatile("v_cvt_pk_bf16_f32 %0, %1, %2" : "=v"(r) : "v"(lo), "v"(hi)); return r; }
;     __device__ __forceinline__ void operator()(f32x4 (&acc)[2][2][4][2], const Unit& u, int wr, int wc, int fr, int fq, LAS unsigned char*) const {
;     ...
;             u32x4 xb[2][4][2];
; #pragma unroll
;             for (int ai = 0; ai < 2; ++ai)
; #pragma unroll
;                 for (int m = 0; m < 4; ++m)
; #pragma unroll
;                     for (int bj = 0; bj < 2; ++bj) xb[ai][m][bj] = *(const u32x4*)((const bf16_t*)in + off0 + (size_t)(ai * HALF + m * 16) * D + bj * HALF);
; #pragma unroll
;             for (int ai = 0; ai < 2; ++ai)
; #pragma unroll
;                 for (int m = 0; m < 4; ++m)
; #pragma unroll
;                     for (int bj = 0; bj < 2; ++bj) { const u32x4 x = xb[ai][m][bj];
;                         f32x4 r0 = (f32x4){__uint_as_float(x.x << 16), __uint_as_float(x.x & 0xffff0000u), __uint_as_float(x.y << 16), __uint_as_float(x.y & 0xffff0000u)};
;                         f32x4 r1 = (f32x4){__uint_as_float(x.z << 16), __uint_as_float(x.z & 0xffff0000u), __uint_as_float(x.w << 16), __uint_as_float(x.w & 0xffff0000u)};
;                         r0 += sc[bj][0] * acc[ai][bj][m][0]; r1 += sc[bj][1] * acc[ai][bj][m][1];
;                         u32x4 w; w.x = cvt_pk_bf16(r0[0], r0[1]); w.y = cvt_pk_bf16(r0[2], r0[3]); w.z = cvt_pk_bf16(r1[0], r1[1]); w.w = cvt_pk_bf16(r1[2], r1[3]);
;                         *(u32x4*)(out + off0 + (size_t)(ai * HALF + m * 16) * D + bj * HALF) = w; }
	v_lshlrev_b32_e32 v230, 16, v238
	v_addc_co_u32_e32 v123, vcc, 0, v121, vcc
	global_load_dwordx4 v[156:159], v[122:123], off
	global_load_dwordx4 v[152:155], v[122:123], off offset:256
	v_add_co_u32_e32 v122, vcc, s33, v120
	v_and_b32_e32 v231, 0xffff0000, v238
	s_nop 0
	v_addc_co_u32_e32 v123, vcc, 0, v121, vcc
	global_load_dwordx4 v[140:143], v[122:123], off
	global_load_dwordx4 v[136:139], v[122:123], off offset:256
	v_add_co_u32_e32 v122, vcc, s18, v120
	v_lshlrev_b32_e32 v242, 16, v240
	s_nop 0
	v_addc_co_u32_e32 v123, vcc, 0, v121, vcc
	global_load_dwordx4 v[132:135], v[122:123], off
	global_load_dwordx4 v[128:131], v[122:123], off offset:256
	v_add_co_u32_e32 v120, vcc, s19, v120
	v_and_b32_e32 v243, 0xffff0000, v240
	s_nop 0
	v_addc_co_u32_e32 v121, vcc, 0, v121, vcc
	global_load_dwordx4 v[124:127], v[120:121], off
	s_nop 0
	global_load_dwordx4 v[120:123], v[120:121], off offset:256
	v_lshlrev_b32_e32 v238, 16, v239
	v_and_b32_e32 v239, 0xffff0000, v239
	v_lshlrev_b32_e32 v240, 16, v241
	v_and_b32_e32 v241, 0xffff0000, v241
	v_pk_fma_f32 v[148:149], v[148:149], v[212:213], v[230:231]
	v_pk_fma_f32 v[144:145], v[144:145], v[208:209], v[242:243]
	v_pk_fma_f32 v[150:151], v[150:151], v[214:215], v[238:239]
	v_pk_fma_f32 v[230:231], v[146:147], v[210:211], v[240:241]
	v_cvt_pk_bf16_f32 v146, v148, v149
	v_cvt_pk_bf16_f32 v147, v150, v151
	v_cvt_pk_bf16_f32 v148, v144, v145
	v_lshl_add_u64 v[144:145], s[54:55], 0, v[216:217]
	v_cvt_pk_bf16_f32 v149, v230, v231
	global_store_dwordx4 v[144:145], v[146:149], off
	s_waitcnt vmcnt(15)
	v_lshlrev_b32_e32 v150, 16, v186
	v_and_b32_e32 v151, 0xffff0000, v186
	v_lshlrev_b32_e32 v146, 16, v184
	v_and_b32_e32 v147, 0xffff0000, v184
	v_lshlrev_b32_e32 v148, 16, v185
	v_and_b32_e32 v149, 0xffff0000, v185
	v_lshlrev_b32_e32 v184, 16, v187
	v_and_b32_e32 v185, 0xffff0000, v187
	v_pk_fma_f32 v[118:119], v[118:119], v[206:207], v[148:149]
	v_pk_fma_f32 v[116:117], v[116:117], v[204:205], v[146:147]
	v_pk_fma_f32 v[146:147], v[114:115], v[202:203], v[184:185]
	v_pk_fma_f32 v[114:115], v[112:113], v[200:201], v[150:151]
	v_cvt_pk_bf16_f32 v112, v116, v117
	v_cvt_pk_bf16_f32 v113, v118, v119
	s_waitcnt vmcnt(14)
	v_lshlrev_b32_e32 v116, 16, v182
	v_cvt_pk_bf16_f32 v114, v114, v115
	v_cvt_pk_bf16_f32 v115, v146, v147
	global_store_dwordx4 v[144:145], v[112:115], off offset:256
	v_and_b32_e32 v117, 0xffff0000, v182
	v_lshlrev_b32_e32 v118, 16, v183
	v_lshlrev_b32_e32 v112, 16, v180
	v_and_b32_e32 v113, 0xffff0000, v180
	v_and_b32_e32 v119, 0xffff0000, v183
	v_pk_fma_f32 v[108:109], v[108:109], v[212:213], v[112:113]
	v_lshlrev_b32_e32 v114, 16, v181
	v_and_b32_e32 v115, 0xffff0000, v181
	v_pk_fma_f32 v[112:113], v[106:107], v[210:211], v[118:119]
	v_pk_fma_f32 v[106:107], v[104:105], v[208:209], v[116:117]
	v_cvt_pk_bf16_f32 v104, v108, v109
	v_add_co_u32_e32 v108, vcc, s45, v144
	v_pk_fma_f32 v[110:111], v[110:111], v[214:215], v[114:115]
	s_nop 0
	v_addc_co_u32_e32 v109, vcc, 0, v145, vcc
	v_cvt_pk_bf16_f32 v105, v110, v111
	v_cvt_pk_bf16_f32 v106, v106, v107
	v_cvt_pk_bf16_f32 v107, v112, v113
	global_store_dwordx4 v[108:109], v[104:107], off
	s_waitcnt vmcnt(15)
	v_lshlrev_b32_e32 v110, 16, v178
	v_and_b32_e32 v111, 0xffff0000, v178
	v_lshlrev_b32_e32 v104, 16, v176
	v_and_b32_e32 v105, 0xffff0000, v176
	v_lshlrev_b32_e32 v106, 16, v177
	v_and_b32_e32 v107, 0xffff0000, v177
	v_lshlrev_b32_e32 v112, 16, v179
	v_and_b32_e32 v113, 0xffff0000, v179
	v_pk_fma_f32 v[102:103], v[102:103], v[206:207], v[106:107]
	v_pk_fma_f32 v[100:101], v[100:101], v[204:205], v[104:105]
	v_pk_fma_f32 v[104:105], v[98:99], v[202:203], v[112:113]
	v_pk_fma_f32 v[98:99], v[96:97], v[200:201], v[110:111]
	v_cvt_pk_bf16_f32 v96, v100, v101
	v_cvt_pk_bf16_f32 v97, v102, v103
	s_waitcnt vmcnt(14)
	v_lshlrev_b32_e32 v100, 16, v174
	v_cvt_pk_bf16_f32 v98, v98, v99
	v_cvt_pk_bf16_f32 v99, v104, v105
	global_store_dwordx4 v[108:109], v[96:99], off offset:256
	v_and_b32_e32 v101, 0xffff0000, v174
	v_lshlrev_b32_e32 v102, 16, v175
	v_lshlrev_b32_e32 v96, 16, v172
	v_and_b32_e32 v97, 0xffff0000, v172
	v_and_b32_e32 v103, 0xffff0000, v175
	v_pk_fma_f32 v[92:93], v[92:93], v[212:213], v[96:97]
	v_lshlrev_b32_e32 v98, 16, v173
	v_and_b32_e32 v99, 0xffff0000, v173
	v_pk_fma_f32 v[96:97], v[90:91], v[210:211], v[102:103]
	v_pk_fma_f32 v[90:91], v[88:89], v[208:209], v[100:101]
	v_cvt_pk_bf16_f32 v88, v92, v93
	v_add_co_u32_e32 v92, vcc, s36, v144
	v_pk_fma_f32 v[94:95], v[94:95], v[214:215], v[98:99]
	s_nop 0
	v_addc_co_u32_e32 v93, vcc, 0, v145, vcc
	v_cvt_pk_bf16_f32 v89, v94, v95
	v_cvt_pk_bf16_f32 v90, v90, v91
	v_cvt_pk_bf16_f32 v91, v96, v97
	global_store_dwordx4 v[92:93], v[88:91], off
	s_waitcnt vmcnt(15)
	v_lshlrev_b32_e32 v94, 16, v170
	v_and_b32_e32 v95, 0xffff0000, v170
	v_lshlrev_b32_e32 v88, 16, v168
	v_and_b32_e32 v89, 0xffff0000, v168
	v_lshlrev_b32_e32 v90, 16, v169
	v_and_b32_e32 v91, 0xffff0000, v169
	v_lshlrev_b32_e32 v96, 16, v171
	v_and_b32_e32 v97, 0xffff0000, v171
	v_pk_fma_f32 v[86:87], v[86:87], v[206:207], v[90:91]
	v_pk_fma_f32 v[84:85], v[84:85], v[204:205], v[88:89]
	v_pk_fma_f32 v[88:89], v[82:83], v[202:203], v[96:97]
	v_pk_fma_f32 v[82:83], v[80:81], v[200:201], v[94:95]
	v_cvt_pk_bf16_f32 v80, v84, v85
	v_cvt_pk_bf16_f32 v81, v86, v87
	s_waitcnt vmcnt(14)
; __device__ __forceinline__ unsigned cvt_pk_bf16(float lo, float hi) { unsigned r; asm volatile("v_cvt_pk_bf16_f32 %0, %1, %2" : "=v"(r) : "v"(lo), "v"(hi)); return r; }
;     __device__ __forceinline__ void operator()(f32x4 (&acc)[2][2][4][2], const Unit& u, int wr, int wc, int fr, int fq, LAS unsigned char*) const {
;     ...
;                     for (int bj = 0; bj < 2; ++bj) { const u32x4 x = xb[ai][m][bj];
;                         f32x4 r0 = (f32x4){__uint_as_float(x.x << 16), __uint_as_float(x.x & 0xffff0000u), __uint_as_float(x.y << 16), __uint_as_float(x.y & 0xffff0000u)};
;                         f32x4 r1 = (f32x4){__uint_as_float(x.z << 16), __uint_as_float(x.z & 0xffff0000u), __uint_as_float(x.w << 16), __uint_as_float(x.w & 0xffff0000u)};
;                         r0 += sc[bj][0] * acc[ai][bj][m][0]; r1 += sc[bj][1] * acc[ai][bj][m][1];
;                         u32x4 w; w.x = cvt_pk_bf16(r0[0], r0[1]); w.y = cvt_pk_bf16(r0[2], r0[3]); w.z = cvt_pk_bf16(r1[0], r1[1]); w.w = cvt_pk_bf16(r1[2], r1[3]);
;                         *(u32x4*)(out + off0 + (size_t)(ai * HALF + m * 16) * D + bj * HALF) = w; }
	v_lshlrev_b32_e32 v84, 16, v166
	v_cvt_pk_bf16_f32 v82, v82, v83
	v_cvt_pk_bf16_f32 v83, v88, v89
	global_store_dwordx4 v[92:93], v[80:83], off offset:256
	v_and_b32_e32 v85, 0xffff0000, v166
	v_lshlrev_b32_e32 v86, 16, v167
	v_lshlrev_b32_e32 v80, 16, v164
	v_and_b32_e32 v81, 0xffff0000, v164
	v_and_b32_e32 v87, 0xffff0000, v167
	v_pk_fma_f32 v[76:77], v[76:77], v[212:213], v[80:81]
	v_lshlrev_b32_e32 v82, 16, v165
	v_and_b32_e32 v83, 0xffff0000, v165
	v_pk_fma_f32 v[80:81], v[74:75], v[210:211], v[86:87]
	v_pk_fma_f32 v[74:75], v[72:73], v[208:209], v[84:85]
	v_cvt_pk_bf16_f32 v72, v76, v77
	v_add_co_u32_e32 v76, vcc, s23, v144
	v_pk_fma_f32 v[78:79], v[78:79], v[214:215], v[82:83]
	s_nop 0
	v_addc_co_u32_e32 v77, vcc, 0, v145, vcc
	v_cvt_pk_bf16_f32 v73, v78, v79
	v_cvt_pk_bf16_f32 v74, v74, v75
	v_cvt_pk_bf16_f32 v75, v80, v81
	global_store_dwordx4 v[76:77], v[72:75], off
	s_waitcnt vmcnt(15)
	v_lshlrev_b32_e32 v78, 16, v162
	v_and_b32_e32 v79, 0xffff0000, v162
	v_lshlrev_b32_e32 v72, 16, v160
	v_and_b32_e32 v73, 0xffff0000, v160
	v_lshlrev_b32_e32 v74, 16, v161
	v_and_b32_e32 v75, 0xffff0000, v161
	v_lshlrev_b32_e32 v80, 16, v163
	v_and_b32_e32 v81, 0xffff0000, v163
	v_pk_fma_f32 v[70:71], v[70:71], v[206:207], v[74:75]
	v_pk_fma_f32 v[68:69], v[68:69], v[204:205], v[72:73]
	v_pk_fma_f32 v[72:73], v[66:67], v[202:203], v[80:81]
	v_pk_fma_f32 v[66:67], v[64:65], v[200:201], v[78:79]
	v_cvt_pk_bf16_f32 v64, v68, v69
	v_cvt_pk_bf16_f32 v65, v70, v71
	s_waitcnt vmcnt(14)
	v_lshlrev_b32_e32 v68, 16, v158
	v_cvt_pk_bf16_f32 v66, v66, v67
	v_cvt_pk_bf16_f32 v67, v72, v73
	global_store_dwordx4 v[76:77], v[64:67], off offset:256
	v_and_b32_e32 v69, 0xffff0000, v158
	v_lshlrev_b32_e32 v70, 16, v159
	v_lshlrev_b32_e32 v64, 16, v156
	v_and_b32_e32 v65, 0xffff0000, v156
	v_and_b32_e32 v71, 0xffff0000, v159
	v_pk_fma_f32 v[60:61], v[60:61], v[212:213], v[64:65]
	v_lshlrev_b32_e32 v66, 16, v157
	v_and_b32_e32 v67, 0xffff0000, v157
	v_pk_fma_f32 v[64:65], v[58:59], v[210:211], v[70:71]
	v_pk_fma_f32 v[58:59], v[56:57], v[208:209], v[68:69]
	v_cvt_pk_bf16_f32 v56, v60, v61
	v_add_co_u32_e32 v60, vcc, s93, v144
	v_pk_fma_f32 v[62:63], v[62:63], v[214:215], v[66:67]
	s_nop 0
	v_addc_co_u32_e32 v61, vcc, 0, v145, vcc
	v_cvt_pk_bf16_f32 v57, v62, v63
	v_cvt_pk_bf16_f32 v58, v58, v59
	v_cvt_pk_bf16_f32 v59, v64, v65
	global_store_dwordx4 v[60:61], v[56:59], off
	s_waitcnt vmcnt(15)
	v_lshlrev_b32_e32 v62, 16, v154
	v_and_b32_e32 v63, 0xffff0000, v154
	v_lshlrev_b32_e32 v56, 16, v152
	v_and_b32_e32 v57, 0xffff0000, v152
	v_lshlrev_b32_e32 v58, 16, v153
	v_and_b32_e32 v59, 0xffff0000, v153
	v_lshlrev_b32_e32 v64, 16, v155
	v_and_b32_e32 v65, 0xffff0000, v155
	v_pk_fma_f32 v[54:55], v[54:55], v[206:207], v[58:59]
	v_pk_fma_f32 v[52:53], v[52:53], v[204:205], v[56:57]
	v_pk_fma_f32 v[56:57], v[50:51], v[202:203], v[64:65]
	v_pk_fma_f32 v[50:51], v[48:49], v[200:201], v[62:63]
	v_cvt_pk_bf16_f32 v48, v52, v53
	v_cvt_pk_bf16_f32 v49, v54, v55
	s_waitcnt vmcnt(14)
	v_lshlrev_b32_e32 v52, 16, v142
	v_cvt_pk_bf16_f32 v50, v50, v51
	v_cvt_pk_bf16_f32 v51, v56, v57
	global_store_dwordx4 v[60:61], v[48:51], off offset:256
	v_and_b32_e32 v53, 0xffff0000, v142
	v_lshlrev_b32_e32 v54, 16, v143
	v_lshlrev_b32_e32 v48, 16, v140
	v_and_b32_e32 v49, 0xffff0000, v140
	v_and_b32_e32 v55, 0xffff0000, v143
	v_pk_fma_f32 v[44:45], v[44:45], v[212:213], v[48:49]
	v_lshlrev_b32_e32 v50, 16, v141
	v_and_b32_e32 v51, 0xffff0000, v141
	v_pk_fma_f32 v[48:49], v[42:43], v[210:211], v[54:55]
	v_pk_fma_f32 v[42:43], v[40:41], v[208:209], v[52:53]
	v_cvt_pk_bf16_f32 v40, v44, v45
	v_add_co_u32_e32 v44, vcc, s33, v144
	v_pk_fma_f32 v[46:47], v[46:47], v[214:215], v[50:51]
	s_nop 0
	v_addc_co_u32_e32 v45, vcc, 0, v145, vcc
	v_cvt_pk_bf16_f32 v41, v46, v47
	v_cvt_pk_bf16_f32 v42, v42, v43
	v_cvt_pk_bf16_f32 v43, v48, v49
	global_store_dwordx4 v[44:45], v[40:43], off
	s_waitcnt vmcnt(15)
; __device__ __forceinline__ unsigned cvt_pk_bf16(float lo, float hi) { unsigned r; asm volatile("v_cvt_pk_bf16_f32 %0, %1, %2" : "=v"(r) : "v"(lo), "v"(hi)); return r; }
; #define PG8_WAIT_V(n) asm volatile("s_waitcnt vmcnt(" #n ")" ::: "memory")
; #define PG8_BAR __builtin_amdgcn_s_barrier()
; template <class Epi>
; __device__ __forceinline__ void gemm_phase(LAS unsigned char* lds, const Gemm g, const StaticOrder& S, const Epi& E) {
;     ...
;         if (!has_next) break;
; #pragma unroll
;         for (int a = 0; a < 2; ++a)
; #pragma unroll
;             for (int b = 0; b < 2; ++b)
; #pragma unroll
;                 for (int m = 0; m < 4; ++m)
; #pragma unroll
;                     for (int n = 0; n < 2; ++n) acc[a][b][m][n] = (f32x4){0.f, 0.f, 0.f, 0.f};
;         cur = nxt; cA = nA; cB = nB; ++ui;
;     }
;     PG8_WAIT_V(0);
;     if (wr == 0) PG8_BAR;
;     PG8_BAR;
;     __device__ __forceinline__ void operator()(f32x4 (&acc)[2][2][4][2], const Unit& u, int wr, int wc, int fr, int fq, LAS unsigned char*) const {
;     ...
;             for (int ai = 0; ai < 2; ++ai)
; #pragma unroll
;                 for (int m = 0; m < 4; ++m)
; #pragma unroll
;                     for (int bj = 0; bj < 2; ++bj) { const u32x4 x = xb[ai][m][bj];
;                         f32x4 r0 = (f32x4){__uint_as_float(x.x << 16), __uint_as_float(x.x & 0xffff0000u), __uint_as_float(x.y << 16), __uint_as_float(x.y & 0xffff0000u)};
;                         f32x4 r1 = (f32x4){__uint_as_float(x.z << 16), __uint_as_float(x.z & 0xffff0000u), __uint_as_float(x.w << 16), __uint_as_float(x.w & 0xffff0000u)};
;                         r0 += sc[bj][0] * acc[ai][bj][m][0]; r1 += sc[bj][1] * acc[ai][bj][m][1];
;                         u32x4 w; w.x = cvt_pk_bf16(r0[0], r0[1]); w.y = cvt_pk_bf16(r0[2], r0[3]); w.z = cvt_pk_bf16(r1[0], r1[1]); w.w = cvt_pk_bf16(r1[2], r1[3]);
;                         *(u32x4*)(out + off0 + (size_t)(ai * HALF + m * 16) * D + bj * HALF) = w; }
	v_lshlrev_b32_e32 v46, 16, v138
	v_and_b32_e32 v47, 0xffff0000, v138
	v_lshlrev_b32_e32 v40, 16, v136
	v_and_b32_e32 v41, 0xffff0000, v136
	v_lshlrev_b32_e32 v42, 16, v137
	v_and_b32_e32 v43, 0xffff0000, v137
	v_lshlrev_b32_e32 v48, 16, v139
	v_and_b32_e32 v49, 0xffff0000, v139
	v_pk_fma_f32 v[38:39], v[38:39], v[206:207], v[42:43]
	v_pk_fma_f32 v[36:37], v[36:37], v[204:205], v[40:41]
	v_pk_fma_f32 v[40:41], v[34:35], v[202:203], v[48:49]
	v_pk_fma_f32 v[34:35], v[32:33], v[200:201], v[46:47]
	v_cvt_pk_bf16_f32 v32, v36, v37
	v_cvt_pk_bf16_f32 v33, v38, v39
	s_waitcnt vmcnt(14)
	v_lshlrev_b32_e32 v36, 16, v134
	v_cvt_pk_bf16_f32 v34, v34, v35
	v_cvt_pk_bf16_f32 v35, v40, v41
	global_store_dwordx4 v[44:45], v[32:35], off offset:256
	v_and_b32_e32 v37, 0xffff0000, v134
	v_lshlrev_b32_e32 v38, 16, v135
	v_lshlrev_b32_e32 v32, 16, v132
	v_and_b32_e32 v33, 0xffff0000, v132
	v_and_b32_e32 v39, 0xffff0000, v135
	v_pk_fma_f32 v[28:29], v[28:29], v[212:213], v[32:33]
	v_lshlrev_b32_e32 v34, 16, v133
	v_and_b32_e32 v35, 0xffff0000, v133
	v_pk_fma_f32 v[32:33], v[26:27], v[210:211], v[38:39]
	v_pk_fma_f32 v[26:27], v[24:25], v[208:209], v[36:37]
	v_cvt_pk_bf16_f32 v24, v28, v29
	v_add_co_u32_e32 v28, vcc, s18, v144
	v_pk_fma_f32 v[30:31], v[30:31], v[214:215], v[34:35]
	s_nop 0
	v_addc_co_u32_e32 v29, vcc, 0, v145, vcc
	v_cvt_pk_bf16_f32 v25, v30, v31
	v_cvt_pk_bf16_f32 v26, v26, v27
	v_cvt_pk_bf16_f32 v27, v32, v33
	global_store_dwordx4 v[28:29], v[24:27], off
	s_waitcnt vmcnt(15)
	v_lshlrev_b32_e32 v30, 16, v130
	v_and_b32_e32 v31, 0xffff0000, v130
	v_lshlrev_b32_e32 v24, 16, v128
	v_and_b32_e32 v25, 0xffff0000, v128
	v_lshlrev_b32_e32 v26, 16, v129
	v_and_b32_e32 v27, 0xffff0000, v129
	v_lshlrev_b32_e32 v32, 16, v131
	v_and_b32_e32 v33, 0xffff0000, v131
	v_pk_fma_f32 v[22:23], v[22:23], v[206:207], v[26:27]
	v_pk_fma_f32 v[20:21], v[20:21], v[204:205], v[24:25]
	v_pk_fma_f32 v[24:25], v[18:19], v[202:203], v[32:33]
	v_pk_fma_f32 v[18:19], v[16:17], v[200:201], v[30:31]
	v_cvt_pk_bf16_f32 v16, v20, v21
	v_cvt_pk_bf16_f32 v17, v22, v23
	s_waitcnt vmcnt(14)
	v_lshlrev_b32_e32 v20, 16, v126
	v_cvt_pk_bf16_f32 v18, v18, v19
	v_cvt_pk_bf16_f32 v19, v24, v25
	global_store_dwordx4 v[28:29], v[16:19], off offset:256
	v_and_b32_e32 v21, 0xffff0000, v126
	v_lshlrev_b32_e32 v22, 16, v127
	v_lshlrev_b32_e32 v16, 16, v124
	v_and_b32_e32 v17, 0xffff0000, v124
	v_and_b32_e32 v23, 0xffff0000, v127
	v_pk_fma_f32 v[12:13], v[12:13], v[212:213], v[16:17]
	v_lshlrev_b32_e32 v18, 16, v125
	v_and_b32_e32 v19, 0xffff0000, v125
	v_pk_fma_f32 v[16:17], v[10:11], v[210:211], v[22:23]
	v_pk_fma_f32 v[10:11], v[8:9], v[208:209], v[20:21]
	v_cvt_pk_bf16_f32 v8, v12, v13
	v_add_co_u32_e32 v12, vcc, s19, v144
	v_pk_fma_f32 v[14:15], v[14:15], v[214:215], v[18:19]
	s_nop 0
	v_addc_co_u32_e32 v13, vcc, 0, v145, vcc
	v_cvt_pk_bf16_f32 v9, v14, v15
	v_cvt_pk_bf16_f32 v10, v10, v11
	v_cvt_pk_bf16_f32 v11, v16, v17
	global_store_dwordx4 v[12:13], v[8:11], off
	s_waitcnt vmcnt(15)
	v_lshlrev_b32_e32 v14, 16, v122
	v_and_b32_e32 v15, 0xffff0000, v122
	v_lshlrev_b32_e32 v8, 16, v120
	v_and_b32_e32 v9, 0xffff0000, v120
	v_lshlrev_b32_e32 v16, 16, v123
	v_and_b32_e32 v17, 0xffff0000, v123
	v_lshlrev_b32_e32 v10, 16, v121
	v_and_b32_e32 v11, 0xffff0000, v121
	v_pk_fma_f32 v[4:5], v[4:5], v[204:205], v[8:9]
	v_pk_fma_f32 v[8:9], v[2:3], v[202:203], v[16:17]
	v_pk_fma_f32 v[2:3], v[0:1], v[200:201], v[14:15]
	s_and_b64 vcc, exec, s[4:5]
	v_pk_fma_f32 v[6:7], v[6:7], v[206:207], v[10:11]
	v_cvt_pk_bf16_f32 v0, v4, v5
	s_nop 0
	v_cvt_pk_bf16_f32 v1, v6, v7
	v_cvt_pk_bf16_f32 v2, v2, v3
	v_cvt_pk_bf16_f32 v3, v8, v9
	global_store_dwordx4 v[12:13], v[0:3], off offset:256
	s_cbranch_vccz .LBB0_849
	s_waitcnt vmcnt(0)
	s_cmpk_gt_u32 s21, 0xff
	v_readlane_b32 s38, v255, 44
	s_cbranch_scc1 .LBB0_864
	s_barrier
